# v1 plus every flat_load/flat_store rewritten as global_load/global_store (same addresses) so LDS waits no longer cover them
# baseline (speedup 1.0000x reference)
.LBB0_477:
	s_lshl_b32 s26, s21, 8
	s_lshl_b32 s10, s20, 8
	v_or_b32_e32 v194, s10, v212
	v_add_u32_e32 v198, s26, v210
	v_ashrrev_i32_e32 v195, 31, v194
	v_ashrrev_i32_e32 v199, 31, v198
	v_lshl_add_u64 v[192:193], v[194:195], 1, s[44:45]
	v_lshlrev_b64 v[112:113], 11, v[198:199]
	v_lshl_add_u64 v[112:113], v[192:193], 0, v[112:113]
	global_load_dwordx4 v[172:175], v[112:113], off
	global_load_dwordx4 v[168:171], v[112:113], off offset:256
	v_or_b32_e32 v112, 16, v198
	v_ashrrev_i32_e32 v113, 31, v112
	v_lshlrev_b64 v[112:113], 11, v[112:113]
	v_lshl_add_u64 v[112:113], v[192:193], 0, v[112:113]
	global_load_dwordx4 v[164:167], v[112:113], off
	global_load_dwordx4 v[160:163], v[112:113], off offset:256
	v_or_b32_e32 v112, 32, v198
	v_ashrrev_i32_e32 v113, 31, v112
	v_lshlrev_b64 v[112:113], 11, v[112:113]
	v_lshl_add_u64 v[112:113], v[192:193], 0, v[112:113]
	global_load_dwordx4 v[156:159], v[112:113], off
	global_load_dwordx4 v[152:155], v[112:113], off offset:256
	v_or_b32_e32 v112, 48, v198
	v_ashrrev_i32_e32 v113, 31, v112
	v_lshlrev_b64 v[112:113], 11, v[112:113]
	v_lshl_add_u64 v[112:113], v[192:193], 0, v[112:113]
	global_load_dwordx4 v[148:151], v[112:113], off
	global_load_dwordx4 v[144:147], v[112:113], off offset:256
	v_and_b32_e32 v113, 64, v204
	v_xor_b32_e32 v112, 16, v204
	v_add_u32_e32 v113, 64, v113
	v_cmp_lt_i32_e32 vcc, v112, v113
	v_mul_f32_e32 v114, v143, v143
	v_fmac_f32_e32 v114, v142, v142
	v_cndmask_b32_e32 v112, v204, v112, vcc
	v_lshlrev_b32_e32 v236, 2, v112
	v_mul_f32_e32 v112, v141, v141
	v_fmac_f32_e32 v112, v140, v140
	v_add_f32_e32 v112, v112, v114
	v_mul_f32_e32 v114, v137, v137
	v_mul_f32_e32 v115, v139, v139
	v_fmac_f32_e32 v114, v136, v136
	v_fmac_f32_e32 v115, v138, v138
	v_add_f32_e32 v114, v114, v115
	v_add_f32_e32 v112, v112, v114
	v_mul_f32_e32 v114, v133, v133
	v_mul_f32_e32 v115, v135, v135
	v_fmac_f32_e32 v114, v132, v132
	v_fmac_f32_e32 v115, v134, v134
	v_add_f32_e32 v114, v114, v115
	v_add_f32_e32 v112, v112, v114
	v_mul_f32_e32 v114, v121, v121
	v_mul_f32_e32 v115, v123, v123
	v_fmac_f32_e32 v114, v120, v120
	v_fmac_f32_e32 v115, v122, v122
	v_add_f32_e32 v114, v114, v115
	v_add_f32_e32 v112, v112, v114
	ds_bpermute_b32 v114, v236, v112
	v_xor_b32_e32 v115, 32, v204
	v_cmp_lt_i32_e32 vcc, v115, v113
	s_waitcnt lgkmcnt(0)
	v_add_f32_e32 v112, v112, v114
	v_cndmask_b32_e32 v113, v204, v115, vcc
	v_lshlrev_b32_e32 v237, 2, v113
	ds_bpermute_b32 v113, v237, v112
	s_and_saveexec_b64 s[0:1], s[2:3]
	s_cbranch_execz .LBB0_479
	s_waitcnt lgkmcnt(0)
	v_add_f32_e32 v112, v112, v113
	ds_write_b32 v234, v112

.LBB0_493:
	s_or_b64 exec, exec, s[0:1]
	v_add_u32_e32 v114, s26, v213
	s_waitcnt lgkmcnt(0)
	s_barrier
	v_ashrrev_i32_e32 v115, 31, v114
	s_waitcnt lgkmcnt(0)
	v_lshlrev_b64 v[112:113], 5, v[114:115]
	v_lshl_add_u64 v[112:113], s[76:77], 0, v[112:113]
	v_add_u32_e32 v238, 0x20400, v235
	s_and_saveexec_b64 s[0:1], s[4:5]
	s_cbranch_execz .LBB0_495
	ds_read_b128 v[116:119], v238
	s_ashr_i32 s21, s20, 31
	s_waitcnt lgkmcnt(0)
	v_mov_b32_e32 v124, v117
	v_mov_b32_e32 v125, v118
	v_mov_b32_e32 v117, v119
	v_pk_add_f32 v[116:117], v[124:125], v[116:117]
	v_lshl_add_u64 v[118:119], s[20:21], 3, v[112:113]
	v_pk_add_f32 v[116:117], v[116:117], v[116:117] op_sel:[0,1] op_sel_hi:[1,0]
	s_nop 0
	v_mov_b32_e32 v117, s84
	s_waitcnt vmcnt(0)
	global_store_dwordx2 v[118:119], v[116:117], off sc1

.LBB0_497:
	s_waitcnt vmcnt(0)
	global_load_dwordx2 v[114:115], v[112:113], off sc1
	global_load_dwordx2 v[116:117], v[112:113], off offset:8 sc1
	global_load_dwordx2 v[124:125], v[112:113], off offset:16 sc1
	global_load_dwordx2 v[118:119], v[112:113], off offset:24 sc1
	s_waitcnt vmcnt(0) lgkmcnt(0)
	v_cmp_eq_u32_e32 vcc, s84, v115
	v_cmp_eq_u32_e64 s[0:1], s84, v117
	s_and_b64 s[0:1], vcc, s[0:1]
	v_cmp_eq_u32_e32 vcc, s84, v125
	s_and_b64 s[0:1], s[0:1], vcc
	v_cmp_eq_u32_e32 vcc, s84, v119
	s_and_b64 s[0:1], s[0:1], vcc
	v_cndmask_b32_e64 v115, 0, 1, s[0:1]
	v_cmp_ne_u32_e32 vcc, 0, v115
	s_cmp_eq_u64 vcc, exec
	s_cselect_b64 s[0:1], -1, 0
	v_subrev_co_u32_e32 v126, vcc, 1, v126
	s_or_b64 s[0:1], s[0:1], vcc
	s_and_b64 vcc, exec, s[0:1]
	s_cbranch_vccz .LBB0_496

.LBB0_501:
	s_or_b64 exec, exec, s[0:1]
	s_waitcnt vmcnt(0) lgkmcnt(0)
	s_barrier
	s_cmp_eq_u32 s20, s56
	s_cbranch_scc1 .LBB0_505
	s_barrier
	s_and_saveexec_b64 s[0:1], s[6:7]
	s_cbranch_execz .LBB0_504
	v_add_u32_e32 v112, s10, v214
	v_ashrrev_i32_e32 v113, 31, v112
	v_lshl_add_u64 v[112:113], v[112:113], 2, s[68:69]
	global_load_dword v112, v[112:113], off
	v_readlane_b32 s10, v255, 37
	s_nop 1
	v_lshl_add_u32 v113, v214, 2, s10
	s_waitcnt vmcnt(0) lgkmcnt(0)
	ds_write_b32 v113, v112

.LBB0_507:
	v_lshl_add_u64 v[172:173], v[198:199], 1, v[192:193]
	v_cvt_pk_f16_f32 v168, v140, v141
	v_cvt_pk_f16_f32 v169, v142, v143
	v_cvt_pk_f16_f32 v170, v136, v137
	v_cvt_pk_f16_f32 v171, v138, v139
	global_store_dwordx4 v[172:173], v[168:171], off
	s_nop 1
	v_cvt_pk_f16_f32 v168, v132, v133
	v_cvt_pk_f16_f32 v169, v134, v135
	v_cvt_pk_f16_f32 v170, v120, v121
	v_cvt_pk_f16_f32 v171, v122, v123
	global_store_dwordx4 v[172:173], v[168:171], off offset:256

.LBB0_512:
	v_lshl_add_u64 v[132:133], v[120:121], 1, v[192:193]
	v_cvt_pk_f16_f32 v120, v108, v109
	v_cvt_pk_f16_f32 v121, v110, v111
	v_cvt_pk_f16_f32 v122, v104, v105
	v_cvt_pk_f16_f32 v123, v106, v107
	global_store_dwordx4 v[132:133], v[120:123], off
	s_nop 1
	v_cvt_pk_f16_f32 v120, v100, v101
	v_cvt_pk_f16_f32 v121, v102, v103
	v_cvt_pk_f16_f32 v122, v96, v97
	v_cvt_pk_f16_f32 v123, v98, v99
	global_store_dwordx4 v[132:133], v[120:123], off offset:256

.LBB0_517:
	v_lshl_add_u64 v[100:101], v[96:97], 1, v[192:193]
	v_cvt_pk_f16_f32 v96, v92, v93
	v_cvt_pk_f16_f32 v97, v94, v95
	v_cvt_pk_f16_f32 v98, v88, v89
	v_cvt_pk_f16_f32 v99, v90, v91
	global_store_dwordx4 v[100:101], v[96:99], off
	s_nop 1
	v_cvt_pk_f16_f32 v96, v84, v85
	v_cvt_pk_f16_f32 v97, v86, v87
	v_cvt_pk_f16_f32 v98, v80, v81
	v_cvt_pk_f16_f32 v99, v82, v83
	global_store_dwordx4 v[100:101], v[96:99], off offset:256

.LBB0_522:
	v_lshl_add_u64 v[84:85], v[80:81], 1, v[192:193]
	v_cvt_pk_f16_f32 v80, v76, v77
	v_cvt_pk_f16_f32 v81, v78, v79
	v_cvt_pk_f16_f32 v82, v72, v73
	v_cvt_pk_f16_f32 v83, v74, v75
	global_store_dwordx4 v[84:85], v[80:83], off
	s_nop 1
	v_cvt_pk_f16_f32 v80, v68, v69
	v_cvt_pk_f16_f32 v81, v70, v71
	v_cvt_pk_f16_f32 v82, v64, v65
	v_cvt_pk_f16_f32 v83, v66, v67
	global_store_dwordx4 v[84:85], v[80:83], off offset:256

.LBB0_525:
	s_or_b64 exec, exec, s[0:1]
	v_add_u32_e32 v88, s26, v215
	v_ashrrev_i32_e32 v89, 31, v88
	s_waitcnt lgkmcnt(0)
	v_lshlrev_b64 v[64:65], 11, v[88:89]
	v_lshl_add_u64 v[64:65], v[192:193], 0, v[64:65]
	global_load_dwordx4 v[90:93], v[64:65], off
	global_load_dwordx4 v[94:97], v[64:65], off offset:256
	v_or_b32_e32 v66, 16, v88
	v_or_b32_e32 v68, 32, v88
	v_or_b32_e32 v64, 48, v88
	v_ashrrev_i32_e32 v67, 31, v66
	v_ashrrev_i32_e32 v69, 31, v68
	v_ashrrev_i32_e32 v65, 31, v64
	v_lshlrev_b64 v[66:67], 11, v[66:67]
	v_lshlrev_b64 v[68:69], 11, v[68:69]
	v_lshlrev_b64 v[64:65], 11, v[64:65]
	v_lshl_add_u64 v[66:67], v[192:193], 0, v[66:67]
	v_lshl_add_u64 v[68:69], v[192:193], 0, v[68:69]
	v_lshl_add_u64 v[64:65], v[192:193], 0, v[64:65]
	global_load_dwordx4 v[84:87], v[66:67], off
	global_load_dwordx4 v[80:83], v[66:67], off offset:256
	global_load_dwordx4 v[76:79], v[68:69], off
	global_load_dwordx4 v[72:75], v[68:69], off offset:256
	s_nop 0
	global_load_dwordx4 v[68:71], v[64:65], off
	s_nop 0
	global_load_dwordx4 v[64:67], v[64:65], off offset:256
	v_lshl_add_u32 v98, v215, 2, s63
	ds_read_b32 v98, v98
	s_and_b64 vcc, exec, s[10:11]
	v_lshlrev_b64 v[88:89], 10, v[88:89]
	s_waitcnt lgkmcnt(0)
	v_pk_mul_f32 v[62:63], v[62:63], v[98:99] op_sel_hi:[1,0]
	v_pk_mul_f32 v[60:61], v[60:61], v[98:99] op_sel_hi:[1,0]
	v_pk_mul_f32 v[58:59], v[58:59], v[98:99] op_sel_hi:[1,0]
	v_pk_mul_f32 v[56:57], v[56:57], v[98:99] op_sel_hi:[1,0]
	v_pk_mul_f32 v[54:55], v[54:55], v[98:99] op_sel_hi:[1,0]
	v_pk_mul_f32 v[52:53], v[52:53], v[98:99] op_sel_hi:[1,0]
	v_pk_mul_f32 v[50:51], v[50:51], v[98:99] op_sel_hi:[1,0]
	v_pk_mul_f32 v[48:49], v[48:49], v[98:99] op_sel_hi:[1,0]
	s_waitcnt vmcnt(0)
	v_cvt_f32_f16_e32 v98, v90
	v_cvt_f32_f16_sdwa v99, v90 dst_sel:DWORD dst_unused:UNUSED_PAD src0_sel:WORD_1
	v_cvt_f32_f16_e32 v90, v91
	v_cvt_f32_f16_sdwa v91, v91 dst_sel:DWORD dst_unused:UNUSED_PAD src0_sel:WORD_1
	v_cvt_f32_f16_e32 v100, v92
	v_cvt_f32_f16_sdwa v101, v92 dst_sel:DWORD dst_unused:UNUSED_PAD src0_sel:WORD_1
	v_cvt_f32_f16_e32 v92, v93
	v_cvt_f32_f16_sdwa v93, v93 dst_sel:DWORD dst_unused:UNUSED_PAD src0_sel:WORD_1
	v_cvt_f32_f16_e32 v102, v94
	v_cvt_f32_f16_sdwa v103, v94 dst_sel:DWORD dst_unused:UNUSED_PAD src0_sel:WORD_1
	v_cvt_f32_f16_e32 v94, v95
	v_cvt_f32_f16_sdwa v95, v95 dst_sel:DWORD dst_unused:UNUSED_PAD src0_sel:WORD_1
	v_cvt_f32_f16_e32 v104, v96
	v_cvt_f32_f16_sdwa v105, v96 dst_sel:DWORD dst_unused:UNUSED_PAD src0_sel:WORD_1
	v_cvt_f32_f16_e32 v96, v97
	v_cvt_f32_f16_sdwa v97, v97 dst_sel:DWORD dst_unused:UNUSED_PAD src0_sel:WORD_1
	v_pk_fma_f32 v[62:63], v[130:131], v[62:63], v[90:91]
	v_pk_fma_f32 v[60:61], v[128:129], v[60:61], v[98:99]
	v_pk_fma_f32 v[58:59], v[126:127], v[58:59], v[92:93]
	v_pk_fma_f32 v[56:57], v[124:125], v[56:57], v[100:101]
	v_pk_fma_f32 v[54:55], v[118:119], v[54:55], v[94:95]
	v_pk_fma_f32 v[52:53], v[116:117], v[52:53], v[102:103]
	v_pk_fma_f32 v[50:51], v[114:115], v[50:51], v[96:97]
	v_pk_fma_f32 v[48:49], v[112:113], v[48:49], v[104:105]
	s_cbranch_vccnz .LBB0_554
	v_lshl_add_u64 v[90:91], v[88:89], 0, v[194:195]
	v_lshl_add_u64 v[90:91], v[90:91], 2, s[38:39]
	global_store_dwordx4 v[90:91], v[60:63], off
	global_store_dwordx4 v[90:91], v[56:59], off offset:16
	global_store_dwordx4 v[90:91], v[52:55], off offset:512
	global_store_dwordx4 v[90:91], v[48:51], off offset:528
	s_cbranch_execnz .LBB0_528
.LBB0_527:
	v_lshl_add_u64 v[92:93], v[88:89], 1, v[192:193]
	v_cvt_pk_f16_f32 v88, v60, v61
	v_cvt_pk_f16_f32 v89, v62, v63
	v_cvt_pk_f16_f32 v90, v56, v57
	v_cvt_pk_f16_f32 v91, v58, v59
	global_store_dwordx4 v[92:93], v[88:91], off
	s_nop 1
	v_cvt_pk_f16_f32 v88, v52, v53
	v_cvt_pk_f16_f32 v89, v54, v55
	v_cvt_pk_f16_f32 v90, v48, v49
	v_cvt_pk_f16_f32 v91, v50, v51
	global_store_dwordx4 v[92:93], v[88:91], off offset:256

.LBB0_532:
	v_lshl_add_u64 v[52:53], v[48:49], 1, v[192:193]
	v_cvt_pk_f16_f32 v48, v44, v45
	v_cvt_pk_f16_f32 v49, v46, v47
	v_cvt_pk_f16_f32 v50, v40, v41
	v_cvt_pk_f16_f32 v51, v42, v43
	global_store_dwordx4 v[52:53], v[48:51], off
	s_nop 1
	v_cvt_pk_f16_f32 v48, v36, v37
	v_cvt_pk_f16_f32 v49, v38, v39
	v_cvt_pk_f16_f32 v50, v32, v33
	v_cvt_pk_f16_f32 v51, v34, v35
	global_store_dwordx4 v[52:53], v[48:51], off offset:256

.LBB0_537:
	v_lshl_add_u64 v[36:37], v[32:33], 1, v[192:193]
	v_cvt_pk_f16_f32 v32, v28, v29
	v_cvt_pk_f16_f32 v33, v30, v31
	v_cvt_pk_f16_f32 v34, v24, v25
	v_cvt_pk_f16_f32 v35, v26, v27
	global_store_dwordx4 v[36:37], v[32:35], off
	s_nop 1
	v_cvt_pk_f16_f32 v32, v20, v21
	v_cvt_pk_f16_f32 v33, v22, v23
	v_cvt_pk_f16_f32 v34, v16, v17
	v_cvt_pk_f16_f32 v35, v18, v19
	global_store_dwordx4 v[36:37], v[32:35], off offset:256

.LBB0_542:
	v_lshl_add_u64 v[20:21], v[16:17], 1, v[192:193]
	v_cvt_pk_f16_f32 v16, v12, v13
	v_cvt_pk_f16_f32 v17, v14, v15
	v_cvt_pk_f16_f32 v18, v8, v9
	v_cvt_pk_f16_f32 v19, v10, v11
	global_store_dwordx4 v[20:21], v[16:19], off
	s_nop 1
	v_cvt_pk_f16_f32 v16, v4, v5
	v_cvt_pk_f16_f32 v17, v6, v7
	v_cvt_pk_f16_f32 v18, v0, v1
	v_cvt_pk_f16_f32 v19, v2, v3
	global_store_dwordx4 v[20:21], v[16:19], off offset:256

.LBB0_545:
	s_or_b64 exec, exec, s[0:1]
	s_waitcnt lgkmcnt(0)
	s_barrier
	s_and_saveexec_b64 s[0:1], s[4:5]
	s_cbranch_execz .LBB0_547
	s_waitcnt lgkmcnt(0)
	ds_read_b128 v[0:3], v238
	s_ashr_i32 s21, s20, 31
	v_lshl_add_u64 v[4:5], v[196:197], 2, s[46:47]
	s_waitcnt lgkmcnt(0)
	v_mov_b32_e32 v6, v1
	v_mov_b32_e32 v7, v2
	v_mov_b32_e32 v1, v3
	v_pk_add_f32 v[0:1], v[6:7], v[0:1]
	s_nop 0
	v_add_f32_e32 v2, v0, v1
	v_lshl_add_u64 v[0:1], s[20:21], 2, v[4:5]
	global_store_dword v[0:1], v2, off

.LBB0_573:
	s_cmp_eq_u32 s42, s36
	s_cbranch_scc1 .LBB0_577
	s_barrier
	s_and_saveexec_b64 s[18:19], s[2:3]
	s_cbranch_execz .LBB0_576
	v_lshl_add_u32 v140, s42, 8, v144
	v_ashrrev_i32_e32 v141, 31, v140
	v_lshl_add_u64 v[140:141], v[140:141], 4, s[46:47]
	global_load_dwordx4 v[148:151], v[140:141], off
	s_waitcnt vmcnt(0) lgkmcnt(0)
	v_mov_b32_e32 v140, v149
	v_mov_b32_e32 v141, v150
	v_mov_b32_e32 v149, v151
	v_pk_add_f32 v[140:141], v[140:141], v[148:149]
	s_nop 0
	v_add_f32_e32 v140, v140, v141
	v_fmamk_f32 v140, v140, 0x3a800000, v205
	v_mul_f32_e32 v141, 0x4b800000, v140
	v_cmp_gt_f32_e32 vcc, s67, v140
	s_nop 1
	v_cndmask_b32_e32 v140, v140, v141, vcc
	v_rsq_f32_e32 v140, v140
	s_nop 0
	v_mul_f32_e32 v141, 0x45800000, v140
	v_cndmask_b32_e32 v140, v140, v141, vcc
	ds_write_b32 v145, v140

.LBB0_577:
	ds_read2_b32 v[150:151], v146 offset1:16
	v_pk_mul_f32 v[120:121], v[124:125], v[120:121]
	v_pk_mul_f32 v[112:113], v[116:117], v[112:113]
	v_pk_mul_f32 v[114:115], v[118:119], v[114:115]
	v_pk_mul_f32 v[122:123], v[126:127], v[122:123]
	s_waitcnt lgkmcnt(0)
	v_mul_f32_e32 v149, 0xbfb8aa3b, v150
	v_mul_f32_e32 v152, v150, v150
	v_mul_f32_e32 v150, v124, v149
	v_mul_f32_e32 v153, v116, v149
	v_exp_f32_e32 v150, v150
	v_mul_f32_e32 v154, v125, v149
	v_exp_f32_e32 v153, v153
	v_exp_f32_e32 v155, v154
	v_add_f32_e32 v150, 1.0, v150
	v_rcp_f32_e32 v154, v150
	v_add_f32_e32 v150, 1.0, v153
	v_add_f32_e32 v153, 1.0, v155
	v_rcp_f32_e32 v156, v150
	v_mul_f32_e32 v150, v117, v149
	v_rcp_f32_e32 v155, v153
	v_exp_f32_e32 v150, v150
	v_mul_f32_e32 v116, v126, v149
	v_mul_f32_e32 v119, v119, v149
	v_pk_mul_f32 v[124:125], v[152:153], v[154:155] op_sel_hi:[0,1]
	v_pk_mul_f32 v[120:121], v[120:121], v[124:125]
	v_add_f32_e32 v124, 1.0, v150
	v_rcp_f32_e32 v157, v124
	v_exp_f32_e32 v124, v116
	v_mul_f32_e32 v116, v118, v149
	v_exp_f32_e32 v125, v116
	v_exp_f32_e32 v126, v119
	v_add_f32_e32 v118, 1.0, v124
	v_rcp_f32_e32 v118, v118
	v_add_f32_e32 v124, 1.0, v125
	v_mul_f32_e32 v125, v127, v149
	v_exp_f32_e32 v125, v125
	v_rcp_f32_e32 v124, v124
	v_pk_mul_f32 v[116:117], v[152:153], v[156:157] op_sel_hi:[0,1]
	v_pk_mul_f32 v[116:117], v[112:113], v[116:117]
	v_add_f32_e32 v119, 1.0, v125
	v_rcp_f32_e32 v119, v119
	v_add_f32_e32 v125, 1.0, v126
	v_rcp_f32_e32 v125, v125
	v_lshl_add_u32 v148, s42, 8, v142
	v_pk_mul_f32 v[112:113], v[152:153], v[118:119] op_sel_hi:[0,1]
	v_pk_mul_f32 v[118:119], v[122:123], v[112:113]
	v_pk_mul_f32 v[112:113], v[152:153], v[124:125] op_sel_hi:[0,1]
	v_pk_mul_f32 v[122:123], v[114:115], v[112:113]
	v_mov_b64_e32 v[112:113], s[48:49]
	v_mad_i64_i32 v[114:115], s[18:19], v148, s75, v[112:113]
	s_lshl_b32 s18, s37, 7
	s_ashr_i32 s19, s18, 31
	s_lshl_b64 s[18:19], s[18:19], 1
	v_lshl_add_u64 v[114:115], v[114:115], 0, s[18:19]
	v_lshl_add_u64 v[124:125], v[114:115], 0, v[176:177]
	v_cvt_pk_f16_f32 v114, v120, v121
	v_cvt_pk_f16_f32 v115, v118, v119
	v_cvt_pk_f16_f32 v116, v116, v117
	v_cvt_pk_f16_f32 v117, v122, v123
	v_mul_f32_e32 v120, 0xbfb8aa3b, v151
	ds_read2_b32 v[140:141], v146 offset0:32 offset1:48
	global_store_dwordx4 v[124:125], v[114:117], off
	v_mul_f32_e32 v118, v109, v120
	v_exp_f32_e32 v119, v118
	v_mul_f32_e32 v117, v100, v120
	v_mul_f32_e32 v114, v108, v120
	v_exp_f32_e32 v117, v117
	v_exp_f32_e32 v116, v114
	v_mul_f32_e32 v121, v101, v120
	v_or_b32_e32 v115, 16, v148
	v_add_f32_e32 v117, 1.0, v117
	v_add_f32_e32 v116, 1.0, v116
	v_rcp_f32_e32 v118, v117
	v_add_f32_e32 v117, 1.0, v119
	v_rcp_f32_e32 v116, v116
	v_rcp_f32_e32 v117, v117
	v_exp_f32_e32 v119, v121
	v_mul_f32_e32 v114, v151, v151
	v_pk_mul_f32 v[104:105], v[108:109], v[104:105]
	v_pk_mul_f32 v[108:109], v[114:115], v[116:117] op_sel_hi:[0,1]
	v_pk_mul_f32 v[104:105], v[104:105], v[108:109]
	v_add_f32_e32 v108, 1.0, v119
	v_pk_mul_f32 v[96:97], v[100:101], v[96:97]
	v_mul_f32_e32 v100, v110, v120
	v_rcp_f32_e32 v119, v108
	v_exp_f32_e32 v108, v100
	v_mul_f32_e32 v100, v102, v120
	v_exp_f32_e32 v109, v100
	v_pk_mul_f32 v[98:99], v[102:103], v[98:99]
	v_add_f32_e32 v102, 1.0, v108
	v_mul_f32_e32 v103, v103, v120
	v_add_f32_e32 v108, 1.0, v109
	v_mul_f32_e32 v109, v111, v120
	v_exp_f32_e32 v109, v109
	v_pk_mul_f32 v[106:107], v[110:111], v[106:107]
	v_exp_f32_e32 v110, v103
	v_rcp_f32_e32 v102, v102
	v_add_f32_e32 v103, 1.0, v109
	v_rcp_f32_e32 v103, v103
	v_add_f32_e32 v109, 1.0, v110
	v_rcp_f32_e32 v108, v108
	v_rcp_f32_e32 v109, v109
	v_pk_mul_f32 v[100:101], v[114:115], v[118:119] op_sel_hi:[0,1]
	v_pk_mul_f32 v[100:101], v[96:97], v[100:101]
	v_pk_mul_f32 v[96:97], v[114:115], v[102:103] op_sel_hi:[0,1]
	v_pk_mul_f32 v[102:103], v[106:107], v[96:97]
	v_pk_mul_f32 v[96:97], v[114:115], v[108:109] op_sel_hi:[0,1]
	v_pk_mul_f32 v[106:107], v[98:99], v[96:97]
	v_mad_i64_i32 v[96:97], s[20:21], v115, s75, v[112:113]
	v_lshl_add_u64 v[96:97], v[96:97], 0, s[18:19]
	v_lshl_add_u64 v[108:109], v[96:97], 0, v[176:177]
	v_cvt_pk_f16_f32 v96, v104, v105
	v_cvt_pk_f16_f32 v97, v102, v103
	v_cvt_pk_f16_f32 v98, v100, v101
	v_cvt_pk_f16_f32 v99, v106, v107
	s_waitcnt lgkmcnt(0)
	v_mul_f32_e32 v102, 0xbfb8aa3b, v140
	global_store_dwordx4 v[108:109], v[96:99], off
	v_mul_f32_e32 v100, v93, v102
	v_exp_f32_e32 v101, v100
	v_mul_f32_e32 v99, v84, v102
	v_mul_f32_e32 v96, v92, v102
	v_exp_f32_e32 v99, v99
	v_exp_f32_e32 v98, v96
	v_mul_f32_e32 v103, v85, v102
	v_or_b32_e32 v97, 32, v148
	v_add_f32_e32 v99, 1.0, v99
	v_add_f32_e32 v98, 1.0, v98
	v_rcp_f32_e32 v100, v99
	v_add_f32_e32 v99, 1.0, v101
	v_rcp_f32_e32 v98, v98
	v_rcp_f32_e32 v99, v99
	v_exp_f32_e32 v101, v103
	v_mul_f32_e32 v96, v140, v140
	v_pk_mul_f32 v[88:89], v[92:93], v[88:89]
	v_pk_mul_f32 v[92:93], v[96:97], v[98:99] op_sel_hi:[0,1]
	v_pk_mul_f32 v[88:89], v[88:89], v[92:93]
	v_add_f32_e32 v92, 1.0, v101
	v_pk_mul_f32 v[80:81], v[84:85], v[80:81]
	v_mul_f32_e32 v84, v94, v102
	v_rcp_f32_e32 v101, v92
	v_exp_f32_e32 v92, v84
	v_mul_f32_e32 v84, v86, v102
	v_exp_f32_e32 v93, v84
	v_pk_mul_f32 v[82:83], v[86:87], v[82:83]
	v_add_f32_e32 v86, 1.0, v92
	v_mul_f32_e32 v87, v87, v102
	v_add_f32_e32 v92, 1.0, v93
	v_mul_f32_e32 v93, v95, v102
	v_exp_f32_e32 v93, v93
	v_pk_mul_f32 v[90:91], v[94:95], v[90:91]
	v_exp_f32_e32 v94, v87
	v_rcp_f32_e32 v86, v86
	v_add_f32_e32 v87, 1.0, v93
	v_rcp_f32_e32 v87, v87
	v_add_f32_e32 v93, 1.0, v94
	v_rcp_f32_e32 v92, v92
	v_rcp_f32_e32 v93, v93
	v_pk_mul_f32 v[84:85], v[96:97], v[100:101] op_sel_hi:[0,1]
	v_pk_mul_f32 v[84:85], v[80:81], v[84:85]
	v_pk_mul_f32 v[80:81], v[96:97], v[86:87] op_sel_hi:[0,1]
	v_pk_mul_f32 v[86:87], v[90:91], v[80:81]
	v_pk_mul_f32 v[80:81], v[96:97], v[92:93] op_sel_hi:[0,1]
	v_pk_mul_f32 v[90:91], v[82:83], v[80:81]
	v_mad_i64_i32 v[80:81], s[20:21], v97, s75, v[112:113]
	v_lshl_add_u64 v[80:81], v[80:81], 0, s[18:19]
	v_lshl_add_u64 v[92:93], v[80:81], 0, v[176:177]
	v_cvt_pk_f16_f32 v80, v88, v89
	v_cvt_pk_f16_f32 v81, v86, v87
	v_cvt_pk_f16_f32 v82, v84, v85
	v_cvt_pk_f16_f32 v83, v90, v91
	v_mul_f32_e32 v86, 0xbfb8aa3b, v141
	global_store_dwordx4 v[92:93], v[80:83], off
	v_mul_f32_e32 v84, v77, v86
	v_exp_f32_e32 v85, v84
	v_mul_f32_e32 v83, v68, v86
	v_mul_f32_e32 v80, v76, v86
	v_exp_f32_e32 v83, v83
	v_exp_f32_e32 v82, v80
	v_mul_f32_e32 v87, v69, v86
	v_or_b32_e32 v81, 48, v148
	v_add_f32_e32 v83, 1.0, v83
	v_add_f32_e32 v82, 1.0, v82
	v_rcp_f32_e32 v84, v83
	v_add_f32_e32 v83, 1.0, v85
	v_rcp_f32_e32 v82, v82
	v_rcp_f32_e32 v83, v83
	v_exp_f32_e32 v85, v87
	v_mul_f32_e32 v80, v141, v141
	v_pk_mul_f32 v[72:73], v[76:77], v[72:73]
	v_pk_mul_f32 v[76:77], v[80:81], v[82:83] op_sel_hi:[0,1]
	v_pk_mul_f32 v[72:73], v[72:73], v[76:77]
	v_add_f32_e32 v76, 1.0, v85
	v_pk_mul_f32 v[64:65], v[68:69], v[64:65]
	v_mul_f32_e32 v68, v78, v86
	v_rcp_f32_e32 v85, v76
	v_exp_f32_e32 v76, v68
	v_mul_f32_e32 v68, v70, v86
	v_exp_f32_e32 v77, v68
	v_pk_mul_f32 v[66:67], v[70:71], v[66:67]
	v_add_f32_e32 v70, 1.0, v76
	v_mul_f32_e32 v71, v71, v86
	v_add_f32_e32 v76, 1.0, v77
	v_mul_f32_e32 v77, v79, v86
	v_exp_f32_e32 v77, v77
	v_pk_mul_f32 v[74:75], v[78:79], v[74:75]
	v_exp_f32_e32 v78, v71
	v_rcp_f32_e32 v70, v70
	v_add_f32_e32 v71, 1.0, v77
	v_rcp_f32_e32 v71, v71
	v_add_f32_e32 v77, 1.0, v78
	v_rcp_f32_e32 v76, v76
	v_rcp_f32_e32 v77, v77
	v_pk_mul_f32 v[68:69], v[80:81], v[84:85] op_sel_hi:[0,1]
	v_pk_mul_f32 v[68:69], v[64:65], v[68:69]
	v_pk_mul_f32 v[64:65], v[80:81], v[70:71] op_sel_hi:[0,1]
	v_pk_mul_f32 v[70:71], v[74:75], v[64:65]
	v_pk_mul_f32 v[64:65], v[80:81], v[76:77] op_sel_hi:[0,1]
	v_pk_mul_f32 v[74:75], v[66:67], v[64:65]
	v_mad_i64_i32 v[64:65], s[20:21], v81, s75, v[112:113]
	v_lshl_add_u64 v[64:65], v[64:65], 0, s[18:19]
	v_lshl_add_u64 v[76:77], v[64:65], 0, v[176:177]
	v_cvt_pk_f16_f32 v64, v72, v73
	v_cvt_pk_f16_f32 v65, v70, v71
	v_cvt_pk_f16_f32 v66, v68, v69
	v_cvt_pk_f16_f32 v67, v74, v75
	global_store_dwordx4 v[76:77], v[64:67], off
	ds_read2_b32 v[66:67], v146 offset0:128 offset1:144
	ds_read2_b32 v[64:65], v146 offset0:160 offset1:176
	v_pk_mul_f32 v[56:57], v[60:61], v[56:57]
	v_pk_mul_f32 v[48:49], v[52:53], v[48:49]
	v_pk_mul_f32 v[50:51], v[54:55], v[50:51]
	s_waitcnt lgkmcnt(0)
	v_mul_f32_e32 v73, 0xbfb8aa3b, v66
	v_mul_f32_e32 v69, v52, v73
	v_mul_f32_e32 v68, v60, v73
	v_exp_f32_e32 v69, v69
	v_mul_f32_e32 v70, v61, v73
	v_exp_f32_e32 v68, v68
	v_exp_f32_e32 v71, v70
	v_add_f32_e32 v69, 1.0, v69
	v_rcp_f32_e32 v70, v69
	v_add_f32_e32 v68, 1.0, v68
	v_add_f32_e32 v69, 1.0, v71
	v_rcp_f32_e32 v68, v68
	v_mul_f32_e32 v74, v53, v73
	v_rcp_f32_e32 v69, v69
	v_exp_f32_e32 v71, v74
	v_mul_f32_e32 v66, v66, v66
	v_mul_f32_e32 v52, v62, v73
	v_pk_mul_f32 v[60:61], v[66:67], v[68:69] op_sel_hi:[0,1]
	v_pk_mul_f32 v[56:57], v[56:57], v[60:61]
	v_add_f32_e32 v60, 1.0, v71
	v_rcp_f32_e32 v71, v60
	v_exp_f32_e32 v60, v52
	v_mul_f32_e32 v52, v54, v73
	v_exp_f32_e32 v61, v52
	v_mul_f32_e32 v55, v55, v73
	v_add_f32_e32 v54, 1.0, v60
	v_pk_mul_f32 v[58:59], v[62:63], v[58:59]
	v_add_f32_e32 v60, 1.0, v61
	v_mul_f32_e32 v61, v63, v73
	v_exp_f32_e32 v61, v61
	v_exp_f32_e32 v62, v55
	v_rcp_f32_e32 v54, v54
	v_rcp_f32_e32 v60, v60
	v_add_f32_e32 v55, 1.0, v61
	v_rcp_f32_e32 v55, v55
	v_add_f32_e32 v61, 1.0, v62
	v_rcp_f32_e32 v61, v61
	v_pk_mul_f32 v[52:53], v[66:67], v[70:71] op_sel_hi:[0,1]
	v_pk_mul_f32 v[52:53], v[48:49], v[52:53]
	v_pk_mul_f32 v[48:49], v[66:67], v[54:55] op_sel_hi:[0,1]
	v_add_u32_e32 v72, 0x80, v148
	v_pk_mul_f32 v[54:55], v[58:59], v[48:49]
	v_pk_mul_f32 v[48:49], v[66:67], v[60:61] op_sel_hi:[0,1]
	v_pk_mul_f32 v[58:59], v[50:51], v[48:49]
	v_mad_i64_i32 v[48:49], s[20:21], v72, s75, v[112:113]
	v_lshl_add_u64 v[48:49], v[48:49], 0, s[18:19]
	v_lshl_add_u64 v[60:61], v[48:49], 0, v[176:177]
	v_cvt_pk_f16_f32 v48, v56, v57
	v_cvt_pk_f16_f32 v49, v54, v55
	v_cvt_pk_f16_f32 v50, v52, v53
	v_cvt_pk_f16_f32 v51, v58, v59
	v_mul_f32_e32 v54, 0xbfb8aa3b, v67
	global_store_dwordx4 v[60:61], v[48:51], off
	v_mul_f32_e32 v52, v45, v54
	v_exp_f32_e32 v53, v52
	v_mul_f32_e32 v51, v36, v54
	v_mul_f32_e32 v48, v44, v54
	v_exp_f32_e32 v51, v51
	v_exp_f32_e32 v50, v48
	v_mul_f32_e32 v55, v37, v54
	v_add_u32_e32 v49, 0x90, v148
	v_add_f32_e32 v51, 1.0, v51
	v_add_f32_e32 v50, 1.0, v50
	v_rcp_f32_e32 v52, v51
	v_add_f32_e32 v51, 1.0, v53
	v_rcp_f32_e32 v50, v50
	v_rcp_f32_e32 v51, v51
	v_exp_f32_e32 v53, v55
	v_mul_f32_e32 v48, v67, v67
	v_pk_mul_f32 v[40:41], v[44:45], v[40:41]
	v_pk_mul_f32 v[44:45], v[48:49], v[50:51] op_sel_hi:[0,1]
	v_pk_mul_f32 v[40:41], v[40:41], v[44:45]
	v_add_f32_e32 v44, 1.0, v53
	v_pk_mul_f32 v[32:33], v[36:37], v[32:33]
	v_mul_f32_e32 v36, v46, v54
	v_rcp_f32_e32 v53, v44
	v_exp_f32_e32 v44, v36
	v_mul_f32_e32 v36, v38, v54
	v_exp_f32_e32 v45, v36
	v_pk_mul_f32 v[34:35], v[38:39], v[34:35]
	v_add_f32_e32 v38, 1.0, v44
	v_mul_f32_e32 v39, v39, v54
	v_add_f32_e32 v44, 1.0, v45
	v_mul_f32_e32 v45, v47, v54
	v_exp_f32_e32 v45, v45
	v_pk_mul_f32 v[42:43], v[46:47], v[42:43]
	v_exp_f32_e32 v46, v39
	v_rcp_f32_e32 v38, v38
	v_add_f32_e32 v39, 1.0, v45
	v_rcp_f32_e32 v39, v39
	v_add_f32_e32 v45, 1.0, v46
	v_rcp_f32_e32 v44, v44
	v_rcp_f32_e32 v45, v45
	v_pk_mul_f32 v[36:37], v[48:49], v[52:53] op_sel_hi:[0,1]
	v_pk_mul_f32 v[36:37], v[32:33], v[36:37]
	v_pk_mul_f32 v[32:33], v[48:49], v[38:39] op_sel_hi:[0,1]
	v_pk_mul_f32 v[38:39], v[42:43], v[32:33]
	v_pk_mul_f32 v[32:33], v[48:49], v[44:45] op_sel_hi:[0,1]
	v_pk_mul_f32 v[42:43], v[34:35], v[32:33]
	v_mad_i64_i32 v[32:33], s[20:21], v49, s75, v[112:113]
	v_lshl_add_u64 v[32:33], v[32:33], 0, s[18:19]
	v_lshl_add_u64 v[44:45], v[32:33], 0, v[176:177]
	v_cvt_pk_f16_f32 v32, v40, v41
	v_cvt_pk_f16_f32 v33, v38, v39
	v_cvt_pk_f16_f32 v34, v36, v37
	v_cvt_pk_f16_f32 v35, v42, v43
	v_mul_f32_e32 v38, 0xbfb8aa3b, v64
	global_store_dwordx4 v[44:45], v[32:35], off
	v_mul_f32_e32 v36, v29, v38
	v_exp_f32_e32 v37, v36
	v_mul_f32_e32 v35, v20, v38
	v_mul_f32_e32 v32, v28, v38
	v_exp_f32_e32 v35, v35
	v_exp_f32_e32 v34, v32
	v_mul_f32_e32 v39, v21, v38
	v_add_u32_e32 v33, 0xa0, v148
	v_add_f32_e32 v35, 1.0, v35
	v_add_f32_e32 v34, 1.0, v34
	v_rcp_f32_e32 v36, v35
	v_add_f32_e32 v35, 1.0, v37
	v_rcp_f32_e32 v34, v34
	v_rcp_f32_e32 v35, v35
	v_exp_f32_e32 v37, v39
	v_mul_f32_e32 v32, v64, v64
	v_pk_mul_f32 v[24:25], v[28:29], v[24:25]
	v_pk_mul_f32 v[28:29], v[32:33], v[34:35] op_sel_hi:[0,1]
	v_pk_mul_f32 v[24:25], v[24:25], v[28:29]
	v_add_f32_e32 v28, 1.0, v37
	v_pk_mul_f32 v[16:17], v[20:21], v[16:17]
	v_mul_f32_e32 v20, v30, v38
	v_rcp_f32_e32 v37, v28
	v_exp_f32_e32 v28, v20
	v_mul_f32_e32 v20, v22, v38
	v_exp_f32_e32 v29, v20
	v_pk_mul_f32 v[18:19], v[22:23], v[18:19]
	v_add_f32_e32 v22, 1.0, v28
	v_mul_f32_e32 v23, v23, v38
	v_add_f32_e32 v28, 1.0, v29
	v_mul_f32_e32 v29, v31, v38
	v_exp_f32_e32 v29, v29
	v_pk_mul_f32 v[26:27], v[30:31], v[26:27]
	v_exp_f32_e32 v30, v23
	v_rcp_f32_e32 v22, v22
	v_add_f32_e32 v23, 1.0, v29
	v_rcp_f32_e32 v23, v23
	v_add_f32_e32 v29, 1.0, v30
	v_rcp_f32_e32 v28, v28
	v_rcp_f32_e32 v29, v29
	v_pk_mul_f32 v[20:21], v[32:33], v[36:37] op_sel_hi:[0,1]
	v_pk_mul_f32 v[20:21], v[16:17], v[20:21]
	v_pk_mul_f32 v[16:17], v[32:33], v[22:23] op_sel_hi:[0,1]
	v_pk_mul_f32 v[22:23], v[26:27], v[16:17]
	v_pk_mul_f32 v[16:17], v[32:33], v[28:29] op_sel_hi:[0,1]
	v_pk_mul_f32 v[26:27], v[18:19], v[16:17]
	v_mad_i64_i32 v[16:17], s[20:21], v33, s75, v[112:113]
	v_lshl_add_u64 v[16:17], v[16:17], 0, s[18:19]
	v_lshl_add_u64 v[28:29], v[16:17], 0, v[176:177]
	v_cvt_pk_f16_f32 v16, v24, v25
	v_cvt_pk_f16_f32 v17, v22, v23
	v_cvt_pk_f16_f32 v18, v20, v21
	v_cvt_pk_f16_f32 v19, v26, v27
	v_mul_f32_e32 v22, 0xbfb8aa3b, v65
	global_store_dwordx4 v[28:29], v[16:19], off
	v_mul_f32_e32 v20, v13, v22
	v_exp_f32_e32 v21, v20
	v_mul_f32_e32 v19, v4, v22
	v_mul_f32_e32 v16, v12, v22
	v_exp_f32_e32 v19, v19
	v_exp_f32_e32 v18, v16
	v_mul_f32_e32 v23, v5, v22
	v_add_u32_e32 v17, 0xb0, v148
	v_add_f32_e32 v19, 1.0, v19
	v_add_f32_e32 v18, 1.0, v18
	v_rcp_f32_e32 v20, v19
	v_add_f32_e32 v19, 1.0, v21
	v_rcp_f32_e32 v18, v18
	v_rcp_f32_e32 v19, v19
	v_exp_f32_e32 v21, v23
	v_mul_f32_e32 v16, v65, v65
	v_pk_mul_f32 v[8:9], v[12:13], v[8:9]
	v_pk_mul_f32 v[12:13], v[16:17], v[18:19] op_sel_hi:[0,1]
	v_pk_mul_f32 v[8:9], v[8:9], v[12:13]
	v_add_f32_e32 v12, 1.0, v21
	v_pk_mul_f32 v[0:1], v[4:5], v[0:1]
	v_mul_f32_e32 v4, v14, v22
	v_rcp_f32_e32 v21, v12
	v_exp_f32_e32 v12, v4
	v_mul_f32_e32 v4, v6, v22
	v_exp_f32_e32 v13, v4
	v_pk_mul_f32 v[2:3], v[6:7], v[2:3]
	v_add_f32_e32 v6, 1.0, v12
	v_mul_f32_e32 v7, v7, v22
	v_add_f32_e32 v12, 1.0, v13
	v_mul_f32_e32 v13, v15, v22
	v_exp_f32_e32 v13, v13
	v_pk_mul_f32 v[10:11], v[14:15], v[10:11]
	v_exp_f32_e32 v14, v7
	v_rcp_f32_e32 v6, v6
	v_add_f32_e32 v7, 1.0, v13
	v_rcp_f32_e32 v7, v7
	v_add_f32_e32 v13, 1.0, v14
	v_rcp_f32_e32 v12, v12
	v_rcp_f32_e32 v13, v13
	v_pk_mul_f32 v[4:5], v[16:17], v[20:21] op_sel_hi:[0,1]
	v_pk_mul_f32 v[4:5], v[0:1], v[4:5]
	v_pk_mul_f32 v[0:1], v[16:17], v[6:7] op_sel_hi:[0,1]
	v_pk_mul_f32 v[6:7], v[10:11], v[0:1]
	v_pk_mul_f32 v[0:1], v[16:17], v[12:13] op_sel_hi:[0,1]
	v_pk_mul_f32 v[10:11], v[2:3], v[0:1]
	v_mad_i64_i32 v[0:1], s[20:21], v17, s75, v[112:113]
	v_lshl_add_u64 v[0:1], v[0:1], 0, s[18:19]
	v_lshl_add_u64 v[12:13], v[0:1], 0, v[176:177]
	v_cvt_pk_f16_f32 v0, v8, v9
	v_cvt_pk_f16_f32 v1, v6, v7
	v_cvt_pk_f16_f32 v2, v4, v5
	v_cvt_pk_f16_f32 v3, v10, v11
	global_store_dwordx4 v[12:13], v[0:3], off
	s_andn2_b64 vcc, exec, s[4:5]
	s_mov_b64 s[4:5], -1
	s_cbranch_vccnz .LBB0_566
	s_andn2_b64 vcc, exec, s[0:1]
	s_cbranch_vccnz .LBB0_565
	s_barrier
	s_branch .LBB0_565

.LBB0_602:
	s_lshl_b32 s21, s19, 8
	s_lshl_b32 s10, s18, 8
	v_or_b32_e32 v194, s10, v212
	v_add_u32_e32 v198, s21, v210
	v_ashrrev_i32_e32 v195, 31, v194
	v_ashrrev_i32_e32 v199, 31, v198
	v_lshl_add_u64 v[192:193], v[194:195], 1, s[44:45]
	v_lshlrev_b64 v[112:113], 11, v[198:199]
	v_lshl_add_u64 v[112:113], v[192:193], 0, v[112:113]
	global_load_dwordx4 v[172:175], v[112:113], off
	global_load_dwordx4 v[168:171], v[112:113], off offset:256
	v_or_b32_e32 v112, 16, v198
	v_ashrrev_i32_e32 v113, 31, v112
	v_lshlrev_b64 v[112:113], 11, v[112:113]
	v_lshl_add_u64 v[112:113], v[192:193], 0, v[112:113]
	global_load_dwordx4 v[164:167], v[112:113], off
	global_load_dwordx4 v[160:163], v[112:113], off offset:256
	v_or_b32_e32 v112, 32, v198
	v_ashrrev_i32_e32 v113, 31, v112
	v_lshlrev_b64 v[112:113], 11, v[112:113]
	v_lshl_add_u64 v[112:113], v[192:193], 0, v[112:113]
	global_load_dwordx4 v[156:159], v[112:113], off
	global_load_dwordx4 v[152:155], v[112:113], off offset:256
	v_or_b32_e32 v112, 48, v198
	v_ashrrev_i32_e32 v113, 31, v112
	v_lshlrev_b64 v[112:113], 11, v[112:113]
	v_lshl_add_u64 v[112:113], v[192:193], 0, v[112:113]
	global_load_dwordx4 v[148:151], v[112:113], off
	global_load_dwordx4 v[144:147], v[112:113], off offset:256
	v_and_b32_e32 v113, 64, v204
	v_xor_b32_e32 v112, 16, v204
	v_add_u32_e32 v113, 64, v113
	v_cmp_lt_i32_e32 vcc, v112, v113
	v_mul_f32_e32 v114, v143, v143
	v_fmac_f32_e32 v114, v142, v142
	v_cndmask_b32_e32 v112, v204, v112, vcc
	v_lshlrev_b32_e32 v236, 2, v112
	v_mul_f32_e32 v112, v141, v141
	v_fmac_f32_e32 v112, v140, v140
	v_add_f32_e32 v112, v112, v114
	v_mul_f32_e32 v114, v137, v137
	v_mul_f32_e32 v115, v139, v139
	v_fmac_f32_e32 v114, v136, v136
	v_fmac_f32_e32 v115, v138, v138
	v_add_f32_e32 v114, v114, v115
	v_add_f32_e32 v112, v112, v114
	v_mul_f32_e32 v114, v133, v133
	v_mul_f32_e32 v115, v135, v135
	v_fmac_f32_e32 v114, v132, v132
	v_fmac_f32_e32 v115, v134, v134
	v_add_f32_e32 v114, v114, v115
	v_add_f32_e32 v112, v112, v114
	v_mul_f32_e32 v114, v121, v121
	v_mul_f32_e32 v115, v123, v123
	v_fmac_f32_e32 v114, v120, v120
	v_fmac_f32_e32 v115, v122, v122
	v_add_f32_e32 v114, v114, v115
	v_add_f32_e32 v112, v112, v114
	ds_bpermute_b32 v114, v236, v112
	v_xor_b32_e32 v115, 32, v204
	v_cmp_lt_i32_e32 vcc, v115, v113
	s_waitcnt lgkmcnt(0)
	v_add_f32_e32 v112, v112, v114
	v_cndmask_b32_e32 v113, v204, v115, vcc
	v_lshlrev_b32_e32 v237, 2, v113
	ds_bpermute_b32 v113, v237, v112
	s_and_saveexec_b64 s[0:1], s[2:3]
	s_cbranch_execz .LBB0_604
	s_waitcnt lgkmcnt(0)
	v_add_f32_e32 v112, v112, v113
	ds_write_b32 v234, v112

.LBB0_618:
	s_or_b64 exec, exec, s[0:1]
	v_add_u32_e32 v114, s21, v213
	s_waitcnt lgkmcnt(0)
	s_barrier
	v_ashrrev_i32_e32 v115, 31, v114
	s_waitcnt lgkmcnt(0)
	v_lshlrev_b64 v[112:113], 5, v[114:115]
	v_lshl_add_u64 v[112:113], s[76:77], 0, v[112:113]
	v_add_u32_e32 v238, 0x20400, v235
	s_and_saveexec_b64 s[0:1], s[4:5]
	s_cbranch_execz .LBB0_620
	ds_read_b128 v[116:119], v238
	s_ashr_i32 s19, s18, 31
	s_waitcnt lgkmcnt(0)
	v_mov_b32_e32 v124, v117
	v_mov_b32_e32 v125, v118
	v_mov_b32_e32 v117, v119
	v_pk_add_f32 v[116:117], v[124:125], v[116:117]
	v_lshl_add_u64 v[118:119], s[18:19], 3, v[112:113]
	v_pk_add_f32 v[116:117], v[116:117], v[116:117] op_sel:[0,1] op_sel_hi:[1,0]
	s_nop 0
	v_mov_b32_e32 v117, s84
	s_waitcnt vmcnt(0)
	global_store_dwordx2 v[118:119], v[116:117], off sc1

.LBB0_626:
	s_or_b64 exec, exec, s[0:1]
	s_waitcnt vmcnt(0) lgkmcnt(0)
	s_barrier
	s_cmp_eq_u32 s18, s71
	s_cbranch_scc1 .LBB0_630
	s_barrier
	s_and_saveexec_b64 s[0:1], s[6:7]
	s_cbranch_execz .LBB0_629
	v_add_u32_e32 v112, s10, v214
	v_ashrrev_i32_e32 v113, 31, v112
	v_lshl_add_u64 v[112:113], v[112:113], 2, s[68:69]
	global_load_dword v112, v[112:113], off
	v_readlane_b32 s10, v255, 37
	s_nop 1
	v_lshl_add_u32 v113, v214, 2, s10
	s_waitcnt vmcnt(0) lgkmcnt(0)
	ds_write_b32 v113, v112

.LBB0_650:
	s_or_b64 exec, exec, s[0:1]
	v_add_u32_e32 v88, s21, v215
	v_ashrrev_i32_e32 v89, 31, v88
	s_waitcnt lgkmcnt(0)
	v_lshlrev_b64 v[64:65], 11, v[88:89]
	v_lshl_add_u64 v[64:65], v[192:193], 0, v[64:65]
	global_load_dwordx4 v[90:93], v[64:65], off
	global_load_dwordx4 v[94:97], v[64:65], off offset:256
	v_or_b32_e32 v66, 16, v88
	v_or_b32_e32 v68, 32, v88
	v_or_b32_e32 v64, 48, v88
	v_ashrrev_i32_e32 v67, 31, v66
	v_ashrrev_i32_e32 v69, 31, v68
	v_ashrrev_i32_e32 v65, 31, v64
	v_lshlrev_b64 v[66:67], 11, v[66:67]
	v_lshlrev_b64 v[68:69], 11, v[68:69]
	v_lshlrev_b64 v[64:65], 11, v[64:65]
	v_lshl_add_u64 v[66:67], v[192:193], 0, v[66:67]
	v_lshl_add_u64 v[68:69], v[192:193], 0, v[68:69]
	v_lshl_add_u64 v[64:65], v[192:193], 0, v[64:65]
	global_load_dwordx4 v[84:87], v[66:67], off
	global_load_dwordx4 v[80:83], v[66:67], off offset:256
	global_load_dwordx4 v[76:79], v[68:69], off
	global_load_dwordx4 v[72:75], v[68:69], off offset:256
	s_nop 0
	global_load_dwordx4 v[68:71], v[64:65], off
	s_nop 0
	global_load_dwordx4 v[64:67], v[64:65], off offset:256
	v_lshl_add_u32 v98, v215, 2, s63
	ds_read_b32 v98, v98
	s_and_b64 vcc, exec, s[10:11]
	v_lshlrev_b64 v[88:89], 10, v[88:89]
	s_waitcnt lgkmcnt(0)
	v_pk_mul_f32 v[62:63], v[62:63], v[98:99] op_sel_hi:[1,0]
	v_pk_mul_f32 v[60:61], v[60:61], v[98:99] op_sel_hi:[1,0]
	v_pk_mul_f32 v[58:59], v[58:59], v[98:99] op_sel_hi:[1,0]
	v_pk_mul_f32 v[56:57], v[56:57], v[98:99] op_sel_hi:[1,0]
	v_pk_mul_f32 v[54:55], v[54:55], v[98:99] op_sel_hi:[1,0]
	v_pk_mul_f32 v[52:53], v[52:53], v[98:99] op_sel_hi:[1,0]
	v_pk_mul_f32 v[50:51], v[50:51], v[98:99] op_sel_hi:[1,0]
	v_pk_mul_f32 v[48:49], v[48:49], v[98:99] op_sel_hi:[1,0]
	s_waitcnt vmcnt(0)
	v_cvt_f32_f16_e32 v98, v90
	v_cvt_f32_f16_sdwa v99, v90 dst_sel:DWORD dst_unused:UNUSED_PAD src0_sel:WORD_1
	v_cvt_f32_f16_e32 v90, v91
	v_cvt_f32_f16_sdwa v91, v91 dst_sel:DWORD dst_unused:UNUSED_PAD src0_sel:WORD_1
	v_cvt_f32_f16_e32 v100, v92
	v_cvt_f32_f16_sdwa v101, v92 dst_sel:DWORD dst_unused:UNUSED_PAD src0_sel:WORD_1
	v_cvt_f32_f16_e32 v92, v93
	v_cvt_f32_f16_sdwa v93, v93 dst_sel:DWORD dst_unused:UNUSED_PAD src0_sel:WORD_1
	v_cvt_f32_f16_e32 v102, v94
	v_cvt_f32_f16_sdwa v103, v94 dst_sel:DWORD dst_unused:UNUSED_PAD src0_sel:WORD_1
	v_cvt_f32_f16_e32 v94, v95
	v_cvt_f32_f16_sdwa v95, v95 dst_sel:DWORD dst_unused:UNUSED_PAD src0_sel:WORD_1
	v_cvt_f32_f16_e32 v104, v96
	v_cvt_f32_f16_sdwa v105, v96 dst_sel:DWORD dst_unused:UNUSED_PAD src0_sel:WORD_1
	v_cvt_f32_f16_e32 v96, v97
	v_cvt_f32_f16_sdwa v97, v97 dst_sel:DWORD dst_unused:UNUSED_PAD src0_sel:WORD_1
	v_pk_fma_f32 v[62:63], v[130:131], v[62:63], v[90:91]
	v_pk_fma_f32 v[60:61], v[128:129], v[60:61], v[98:99]
	v_pk_fma_f32 v[58:59], v[126:127], v[58:59], v[92:93]
	v_pk_fma_f32 v[56:57], v[124:125], v[56:57], v[100:101]
	v_pk_fma_f32 v[54:55], v[118:119], v[54:55], v[94:95]
	v_pk_fma_f32 v[52:53], v[116:117], v[52:53], v[102:103]
	v_pk_fma_f32 v[50:51], v[114:115], v[50:51], v[96:97]
	v_pk_fma_f32 v[48:49], v[112:113], v[48:49], v[104:105]
	s_cbranch_vccnz .LBB0_679
	v_lshl_add_u64 v[90:91], v[88:89], 0, v[194:195]
	v_lshl_add_u64 v[90:91], v[90:91], 2, s[38:39]
	global_store_dwordx4 v[90:91], v[60:63], off
	global_store_dwordx4 v[90:91], v[56:59], off offset:16
	global_store_dwordx4 v[90:91], v[52:55], off offset:512
	global_store_dwordx4 v[90:91], v[48:51], off offset:528
	s_cbranch_execnz .LBB0_653

.LBB0_670:
	s_or_b64 exec, exec, s[0:1]
	s_waitcnt lgkmcnt(0)
	s_barrier
	s_and_saveexec_b64 s[0:1], s[4:5]
	s_cbranch_execz .LBB0_672
	s_waitcnt lgkmcnt(0)
	ds_read_b128 v[0:3], v238
	s_ashr_i32 s19, s18, 31
	v_lshl_add_u64 v[4:5], v[196:197], 2, s[46:47]
	s_waitcnt lgkmcnt(0)
	v_mov_b32_e32 v6, v1
	v_mov_b32_e32 v7, v2
	v_mov_b32_e32 v1, v3
	v_pk_add_f32 v[0:1], v[6:7], v[0:1]
	s_nop 0
	v_add_f32_e32 v2, v0, v1
	v_lshl_add_u64 v[0:1], s[18:19], 2, v[4:5]
	global_store_dword v[0:1], v2, off

.LBB0_685:
	s_andn2_b64 vcc, exec, s[0:1]
	s_cbranch_vccnz .LBB0_699
	v_readlane_b32 s0, v254, 20
	v_readlane_b32 s1, v254, 21
	v_mov_b32_e32 v0, v201
	s_andn2_b64 vcc, exec, s[0:1]
	s_cbranch_vccnz .LBB0_699
	v_and_b32_e32 v190, 31, v0
	v_readlane_b32 s4, v255, 18
	v_readlane_b32 s2, v254, 23
	v_readlane_b32 s3, v254, 24
	v_or_b32_e32 v2, s4, v190
	v_or_b32_e32 v2, s2, v2
	v_mov_b32_e32 v3, s3
	v_readlane_b32 s0, v254, 26
	v_lshlrev_b64 v[2:3], 11, v[2:3]
	v_readlane_b32 s1, v254, 27
	v_readlane_b32 s6, v254, 25
	s_waitcnt lgkmcnt(0)
	v_ashrrev_i32_e32 v1, 5, v0
	v_lshl_add_u64 v[2:3], s[0:1], 0, v[2:3]
	s_lshl_b32 s0, s6, 1
	s_add_u32 s0, s50, s0
	v_lshlrev_b32_e32 v9, 4, v0
	v_lshlrev_b32_e32 v152, 3, v1
	s_addc_u32 s1, s51, 0
	v_and_b32_e32 v176, 0x70, v9
	v_ashrrev_i32_e32 v153, 31, v152
	v_ashrrev_i32_e32 v154, 3, v0
	v_lshl_add_u64 v[4:5], s[0:1], 0, v[176:177]
	s_lshl_b64 s[0:1], s[2:3], 1
	v_lshl_add_u64 v[2:3], v[152:153], 1, v[2:3]
	v_ashrrev_i32_e32 v155, 31, v154
	s_add_u32 s0, s42, s0
	global_load_dwordx4 v[64:67], v[2:3], off
	global_load_dwordx4 v[68:71], v[2:3], off offset:32
	global_load_dwordx4 v[72:75], v[2:3], off offset:64
	global_load_dwordx4 v[76:79], v[2:3], off offset:96
	v_lshl_add_u64 v[2:3], s[2:3], 0, v[154:155]
	v_lshlrev_b32_e32 v7, 3, v0
	s_addc_u32 s1, s43, s1
	s_lshl_b32 s2, s4, 1
	v_ashrrev_i32_e32 v191, 2, v0
	s_add_u32 s0, s0, s2
	v_and_b32_e32 v8, 24, v7
	v_readlane_b32 s5, v255, 19
	v_add_u32_e32 v6, s6, v191
	s_addc_u32 s1, s1, 0
	s_waitcnt vmcnt(0)
	v_lshlrev_b32_e32 v10, 1, v8
	v_mov_b32_e32 v11, v177
	v_lshl_add_u64 v[12:13], s[0:1], 0, v[10:11]
	v_lshl_add_u64 v[14:15], v[2:3], 0, s[4:5]
	v_ashrrev_i32_e32 v7, 31, v6
	v_readlane_b32 s0, v255, 20
	v_lshlrev_b64 v[14:15], 11, v[14:15]
	v_lshlrev_b64 v[6:7], 17, v[6:7]
	v_readlane_b32 s1, v255, 21
	v_lshl_add_u64 v[14:15], v[4:5], 0, v[14:15]
	v_lshl_add_u64 v[6:7], v[12:13], 0, v[6:7]
	v_lshl_add_u64 v[12:13], v[2:3], 0, s[0:1]
	s_mov_b32 s0, 0x200000
	global_load_dwordx4 v[48:51], v[14:15], off
	global_load_dwordx4 v[52:55], v[6:7], off
	v_lshlrev_b64 v[12:13], 11, v[12:13]
	v_add_co_u32_e32 v14, vcc, s0, v6
	v_readlane_b32 s0, v255, 22
	v_lshl_add_u64 v[12:13], v[4:5], 0, v[12:13]
	v_readlane_b32 s1, v255, 23
	v_addc_co_u32_e32 v15, vcc, 0, v7, vcc
	global_load_dwordx4 v[56:59], v[12:13], off
	global_load_dwordx4 v[60:63], v[14:15], off
	v_lshl_add_u64 v[12:13], v[2:3], 0, s[0:1]
	s_mov_b32 s0, 0x400000
	v_add_co_u32_e32 v14, vcc, s0, v6
	v_readlane_b32 s0, v255, 24
	v_readlane_b32 s1, v255, 25
	v_lshlrev_b64 v[12:13], 11, v[12:13]
	v_addc_co_u32_e32 v15, vcc, 0, v7, vcc
	v_lshl_add_u64 v[2:3], v[2:3], 0, s[0:1]
	v_lshlrev_b64 v[2:3], 11, v[2:3]
	s_mov_b32 s0, 0x600000
	v_lshl_add_u64 v[12:13], v[4:5], 0, v[12:13]
	v_lshl_add_u64 v[2:3], v[4:5], 0, v[2:3]
	v_add_co_u32_e32 v4, vcc, s0, v6
	global_load_dwordx4 v[80:83], v[12:13], off
	global_load_dwordx4 v[84:87], v[14:15], off
	v_addc_co_u32_e32 v5, vcc, 0, v7, vcc
	global_load_dwordx4 v[88:91], v[2:3], off
	global_load_dwordx4 v[92:95], v[4:5], off
	v_cmp_gt_u32_e64 s[2:3], 32, v0
	v_lshlrev_b32_e32 v0, 2, v1
	v_readlane_b32 s0, v254, 22
	v_and_b32_e32 v9, 48, v9
	v_or_b32_e32 v21, 1, v0
	v_mov_b32_e32 v2, s0
	v_lshl_add_u32 v3, v190, 1, s0
	v_add_u32_e32 v4, -8, v190
	v_add_u32_e32 v5, -9, v190
	v_add_u32_e32 v6, -10, v190
	v_add_u32_e32 v7, -11, v190
	v_add_u32_e32 v12, -16, v190
	v_subrev_u32_e32 v13, 17, v190
	v_subrev_u32_e32 v14, 18, v190
	v_subrev_u32_e32 v15, 19, v190
	v_subrev_u32_e32 v16, 24, v190
	v_subrev_u32_e32 v17, 25, v190
	v_subrev_u32_e32 v18, 26, v190
	v_subrev_u32_e32 v19, 27, v190
	v_add_u32_e32 v20, s0, v176
	v_add_u32_e32 v9, s0, v9
	v_lshl_add_u64 v[158:159], s[42:43], 0, v[10:11]
	s_movk_i32 s1, 0x90
	v_add_u32_e32 v11, s0, v152
	v_cmp_lt_i32_e64 s[6:7], v21, v190
	v_or_b32_e32 v21, 2, v0
	s_movk_i32 s0, 0x50
	v_add_u32_e32 v162, 8, v154
	v_add_u32_e32 v164, 16, v154
	v_add_u32_e32 v166, 24, v154
	v_mad_u32_u24 v2, v190, s1, v2
	v_lshlrev_b32_e32 v10, 4, v1
	v_cmp_lt_i32_e64 s[4:5], v0, v190
	v_cmp_lt_i32_e64 s[8:9], v21, v190
	v_or_b32_e32 v21, 3, v0
	v_cmp_lt_i32_e64 s[12:13], v0, v4
	v_cmp_lt_i32_e64 s[14:15], v0, v5
	v_cmp_lt_i32_e64 s[16:17], v0, v6
	v_cmp_lt_i32_e64 s[18:19], v0, v7
	v_cmp_lt_i32_e64 s[20:21], v0, v12
	v_cmp_lt_i32_e64 s[22:23], v0, v13
	v_cmp_lt_i32_e64 s[24:25], v0, v14
	v_cmp_lt_i32_e64 s[26:27], v0, v15
	v_cmp_lt_i32_e64 s[28:29], v0, v16
	v_cmp_lt_i32_e64 s[30:31], v0, v17
	v_cmp_lt_i32_e64 s[34:35], v0, v18
	v_cmp_lt_i32_e64 s[36:37], v0, v19
	v_lshlrev_b32_e32 v0, 9, v1
	v_lshlrev_b32_e32 v1, 7, v154
	v_mul_lo_u32 v4, v154, s1
	v_mul_lo_u32 v5, v191, s0
	v_mul_u32_u24_e32 v6, 0x50, v190
	v_lshlrev_b32_e32 v7, 7, v162
	v_lshlrev_b32_e32 v12, 7, v164
	v_lshlrev_b32_e32 v13, 7, v166
	v_lshl_add_u64 v[156:157], s[50:51], 0, v[176:177]
	v_cmp_lt_i32_e64 s[10:11], v21, v190
	v_lshl_add_u64 v[160:161], s[78:79], 0, v[176:177]
	v_ashrrev_i32_e32 v163, 31, v162
	v_ashrrev_i32_e32 v165, 31, v164
	v_ashrrev_i32_e32 v167, 31, v166
	v_lshlrev_b32_e32 v168, 1, v8
	v_add_u32_e32 v192, v3, v0
	v_add_u32_e32 v193, v20, v1
	v_add_u32_e32 v194, v20, v7
	v_add_u32_e32 v195, v20, v12
	v_add_u32_e32 v196, v20, v13
	v_add_u32_e32 v197, v20, v4
	v_add_u32_e32 v198, v9, v5
	v_add_u32_e32 v199, v2, v10
	v_add_u32_e32 v210, v11, v6
	v_readlane_b32 s71, v254, 8
	s_branch .LBB0_689
.LBB0_688:
	s_nop 4
	v_cvt_f16_f32_e32 v0, v0
	s_nop 4
	v_cvt_f16_f32_e32 v16, v16
	v_cvt_f16_f32_e32 v1, v1
	v_cvt_f16_f32_e32 v17, v17
	ds_write_b16 v192, v0
	ds_write_b16 v192, v16 offset:64
	ds_write_b16 v192, v1 offset:128
	ds_write_b16 v192, v17 offset:192
	v_cvt_f16_f32_e32 v0, v2
	v_cvt_f16_f32_e32 v1, v18
	v_cvt_f16_f32_e32 v2, v3
	v_cvt_f16_f32_e32 v3, v19
	ds_write_b16 v192, v0 offset:256
	ds_write_b16 v192, v1 offset:320
	ds_write_b16 v192, v2 offset:384
	ds_write_b16 v192, v3 offset:448
	v_cvt_f16_f32_e32 v0, v4
	v_cvt_f16_f32_e32 v1, v20
	v_cvt_f16_f32_e32 v2, v5
	v_cvt_f16_f32_e32 v3, v21
	ds_write_b16 v192, v0 offset:1024
	ds_write_b16 v192, v1 offset:1088
	ds_write_b16 v192, v2 offset:1152
	ds_write_b16 v192, v3 offset:1216
	v_cvt_f16_f32_e32 v0, v6
	v_cvt_f16_f32_e32 v1, v22
	v_cvt_f16_f32_e32 v2, v7
	v_cvt_f16_f32_e32 v3, v23
	ds_write_b16 v192, v0 offset:1280
	ds_write_b16 v192, v1 offset:1344
	ds_write_b16 v192, v2 offset:1408
	ds_write_b16 v192, v3 offset:1472
	v_cvt_f16_f32_e32 v0, v8
	v_cvt_f16_f32_e32 v1, v24
	v_cvt_f16_f32_e32 v2, v9
	v_cvt_f16_f32_e32 v3, v25
	ds_write_b16 v192, v0 offset:2048
	ds_write_b16 v192, v1 offset:2112
	ds_write_b16 v192, v2 offset:2176
	ds_write_b16 v192, v3 offset:2240
	v_cvt_f16_f32_e32 v0, v10
	v_cvt_f16_f32_e32 v1, v26
	v_cvt_f16_f32_e32 v2, v11
	v_cvt_f16_f32_e32 v3, v27
	ds_write_b16 v192, v0 offset:2304
	ds_write_b16 v192, v1 offset:2368
	ds_write_b16 v192, v2 offset:2432
	ds_write_b16 v192, v3 offset:2496
	v_cvt_f16_f32_e32 v0, v12
	v_cvt_f16_f32_e32 v1, v28
	v_cvt_f16_f32_e32 v2, v13
	v_cvt_f16_f32_e32 v3, v29
	ds_write_b16 v192, v0 offset:3072
	ds_write_b16 v192, v1 offset:3136
	ds_write_b16 v192, v2 offset:3200
	ds_write_b16 v192, v3 offset:3264
	v_cvt_f16_f32_e32 v0, v14
	v_cvt_f16_f32_e32 v1, v30
	v_cvt_f16_f32_e32 v2, v15
	v_cvt_f16_f32_e32 v3, v31
	ds_write_b16 v192, v0 offset:3328
	ds_write_b16 v192, v1 offset:3392
	ds_write_b16 v192, v2 offset:3456
	ds_write_b16 v192, v3 offset:3520
	s_waitcnt lgkmcnt(0)
	ds_read_b128 v[0:3], v193
	s_or_b32 s0, s0, s85
	s_mov_b32 s55, s97
	v_lshl_add_u64 v[6:7], s[0:1], 0, v[154:155]
	v_lshl_add_u64 v[4:5], v[160:161], 0, s[54:55]
	v_lshlrev_b64 v[6:7], 11, v[6:7]
	v_lshl_add_u64 v[6:7], v[4:5], 0, v[6:7]
	s_waitcnt lgkmcnt(0)
	global_store_dwordx4 v[6:7], v[0:3], off
	ds_read_b128 v[0:3], v194
	v_lshl_add_u64 v[6:7], s[0:1], 0, v[162:163]
	v_lshlrev_b64 v[6:7], 11, v[6:7]
	v_lshl_add_u64 v[6:7], v[4:5], 0, v[6:7]
	s_waitcnt vmcnt(0)
	v_mov_b64_e32 v[64:65], v[104:105]
	s_waitcnt lgkmcnt(0)
	global_store_dwordx4 v[6:7], v[0:3], off
	ds_read_b128 v[0:3], v195
	v_lshl_add_u64 v[6:7], s[0:1], 0, v[164:165]
	v_lshlrev_b64 v[6:7], 11, v[6:7]
	v_lshl_add_u64 v[6:7], v[4:5], 0, v[6:7]
	v_mov_b64_e32 v[68:69], v[108:109]
	s_waitcnt lgkmcnt(0)
	global_store_dwordx4 v[6:7], v[0:3], off
	ds_read_b128 v[0:3], v196
	v_lshl_add_u64 v[6:7], s[0:1], 0, v[166:167]
	v_lshlrev_b64 v[6:7], 11, v[6:7]
	v_lshl_add_u64 v[4:5], v[4:5], 0, v[6:7]
	v_mov_b64_e32 v[72:73], v[112:113]
	s_waitcnt lgkmcnt(0)
	global_store_dwordx4 v[4:5], v[0:3], off
	s_waitcnt lgkmcnt(0)
	v_mov_b64_e32 v[76:77], v[120:121]
	s_and_b64 vcc, exec, s[56:57]
	v_mov_b64_e32 v[66:67], v[106:107]
	v_mov_b64_e32 v[70:71], v[110:111]
	v_mov_b64_e32 v[74:75], v[114:115]
	v_mov_b64_e32 v[78:79], v[122:123]
	s_cbranch_vccnz .LBB0_699
.LBB0_689:
	s_ashr_i32 s56, s71, 11
	s_lshr_b32 s53, s71, 1
	s_waitcnt vmcnt(0) lgkmcnt(0)
	ds_write_b128 v197, v[48:51] offset:4096
	ds_write_b128 v198, v[52:55] offset:8704
	ds_write_b128 v197, v[56:59] offset:5248
	ds_write_b128 v198, v[60:63] offset:9984
	ds_write_b128 v197, v[80:83] offset:6400
	ds_write_b128 v198, v[84:87] offset:11264
	ds_write_b128 v197, v[88:91] offset:7552
	ds_write_b128 v198, v[92:95] offset:12544
	s_lshl_b32 s0, s71, 5
	s_ashr_i32 s57, s56, 31
	s_and_b32 s53, s53, 0x3c0
	s_waitcnt lgkmcnt(0)
	s_and_b32 s85, s0, 0xfe0
	s_lshl_b64 s[0:1], s[56:57], 12
	s_lshl_b32 s54, s53, 1
	s_mov_b32 s55, s97
	v_add_u32_e32 v32, s53, v191
	s_lshl_b64 s[56:57], s[56:57], 13
	v_lshl_add_u64 v[170:171], s[0:1], 0, v[154:155]
	v_lshl_add_u64 v[172:173], v[156:157], 0, s[54:55]
	v_lshl_add_u64 v[174:175], v[158:159], 0, s[56:57]
	s_cmp_eq_u32 s85, 0
	v_ashrrev_i32_e32 v33, 31, v32
	s_cbranch_scc1 .LBB0_691
	s_sub_i32 s96, s85, 32
	v_lshl_add_u64 v[0:1], v[170:171], 0, s[96:97]
	v_lshlrev_b64 v[0:1], 11, v[0:1]
	v_lshl_add_u64 v[2:3], s[96:97], 1, v[174:175]
	v_lshl_add_u64 v[0:1], v[172:173], 0, v[0:1]
	v_lshlrev_b64 v[4:5], 17, v[32:33]
	v_lshl_add_u64 v[2:3], v[2:3], 0, v[4:5]
	v_add_co_u32_e32 v4, vcc, 0x4000, v0
	global_load_dwordx4 v[96:99], v[0:1], off
	global_load_dwordx4 v[100:103], v[2:3], off
	v_addc_co_u32_e32 v5, vcc, 0, v1, vcc
	v_add_co_u32_e32 v6, vcc, 0x200000, v2
	s_mov_b32 s53, 0xc000
	s_nop 0
	v_addc_co_u32_e32 v7, vcc, 0, v3, vcc
	global_load_dwordx4 v[124:127], v[4:5], off
	global_load_dwordx4 v[116:119], v[6:7], off
	v_add_co_u32_e32 v4, vcc, s62, v0
	s_nop 1
	v_addc_co_u32_e32 v5, vcc, 0, v1, vcc
	v_add_co_u32_e32 v6, vcc, 0x400000, v2
	s_nop 1
	v_addc_co_u32_e32 v7, vcc, 0, v3, vcc
	v_add_co_u32_e32 v0, vcc, s53, v0
	global_load_dwordx4 v[132:135], v[4:5], off
	global_load_dwordx4 v[128:131], v[6:7], off
	v_addc_co_u32_e32 v1, vcc, 0, v1, vcc
	v_add_co_u32_e32 v2, vcc, 0x600000, v2
	s_nop 1
	v_addc_co_u32_e32 v3, vcc, 0, v3, vcc
	global_load_dwordx4 v[140:143], v[0:1], off
	global_load_dwordx4 v[136:139], v[2:3], off
	s_branch .LBB0_692

.LBB0_692:
	s_add_i32 s71, s71, s59
	s_cmpk_gt_i32 s71, 0x7fff
	s_cselect_b64 s[56:57], -1, 0
	v_mov_b64_e32 v[106:107], v[66:67]
	v_mov_b64_e32 v[110:111], v[70:71]
	v_mov_b64_e32 v[114:115], v[74:75]
	v_mov_b64_e32 v[122:123], v[78:79]
	s_and_b64 vcc, exec, s[56:57]
	v_mov_b64_e32 v[104:105], v[64:65]
	v_mov_b64_e32 v[108:109], v[68:69]
	v_mov_b64_e32 v[112:113], v[72:73]
	v_mov_b64_e32 v[120:121], v[76:77]
	s_cbranch_vccnz .LBB0_694
	s_lshl_b32 s53, s71, 5
	s_ashr_i32 vcc_lo, s71, 11
	s_and_b32 s86, s53, 0xfe0
	s_ashr_i32 vcc_hi, vcc_lo, 31
	s_lshl_b64 s[92:93], vcc, 12
	v_or_b32_e32 v0, s86, v190
	v_or_b32_e32 v0, s92, v0
	v_mov_b32_e32 v1, s93
	s_lshr_b32 s53, s71, 1
	v_lshlrev_b64 v[0:1], 11, v[0:1]
	s_and_b32 s53, s53, 0x3c0
	v_lshl_add_u64 v[0:1], s[40:41], 0, v[0:1]
	s_lshl_b32 s96, s53, 1
	v_lshl_add_u64 v[2:3], s[92:93], 0, v[154:155]
	s_lshl_b64 s[92:93], vcc, 13
	v_lshl_add_u64 v[0:1], v[0:1], 0, s[96:97]
	v_add_u32_e32 v6, s53, v191
	s_add_u32 s53, s42, s92
	v_lshl_add_u64 v[0:1], v[152:153], 1, v[0:1]
	s_mov_b32 s87, s97
	s_addc_u32 s55, s43, s93
	s_lshl_b32 s92, s86, 1
	s_add_u32 s92, s53, s92
	global_load_dwordx4 v[104:107], v[0:1], off
	global_load_dwordx4 v[108:111], v[0:1], off offset:32
	global_load_dwordx4 v[112:115], v[0:1], off offset:64
	global_load_dwordx4 v[120:123], v[0:1], off offset:96
	v_lshl_add_u64 v[0:1], v[2:3], 0, s[86:87]
	v_lshl_add_u64 v[4:5], v[156:157], 0, s[96:97]
	s_addc_u32 s93, s55, 0
	v_mov_b32_e32 v169, v177
	v_lshlrev_b64 v[0:1], 11, v[0:1]
	v_ashrrev_i32_e32 v7, 31, v6
	v_lshl_add_u64 v[8:9], s[92:93], 0, v[168:169]
	v_lshl_add_u64 v[0:1], v[4:5], 0, v[0:1]
	v_lshlrev_b64 v[6:7], 17, v[6:7]
	s_or_b32 s96, s86, 8
	v_lshl_add_u64 v[6:7], v[8:9], 0, v[6:7]
	global_load_dwordx4 v[48:51], v[0:1], off
	global_load_dwordx4 v[52:55], v[6:7], off
	v_lshl_add_u64 v[0:1], v[2:3], 0, s[96:97]
	v_lshlrev_b64 v[0:1], 11, v[0:1]
	s_mov_b32 s53, 0x200000
	v_lshl_add_u64 v[0:1], v[4:5], 0, v[0:1]
	v_add_co_u32_e32 v8, vcc, s53, v6
	s_or_b32 s96, s86, 16
	s_nop 0
	v_addc_co_u32_e32 v9, vcc, 0, v7, vcc
	global_load_dwordx4 v[56:59], v[0:1], off
	global_load_dwordx4 v[60:63], v[8:9], off
	v_lshl_add_u64 v[0:1], v[2:3], 0, s[96:97]
	v_lshlrev_b64 v[0:1], 11, v[0:1]
	v_lshl_add_u64 v[0:1], v[4:5], 0, v[0:1]
	v_add_co_u32_e32 v8, vcc, 0x400000, v6
	s_or_b32 s96, s86, 24
	s_nop 0
	v_addc_co_u32_e32 v9, vcc, 0, v7, vcc
	global_load_dwordx4 v[80:83], v[0:1], off
	global_load_dwordx4 v[84:87], v[8:9], off
	v_lshl_add_u64 v[0:1], v[2:3], 0, s[96:97]
	v_lshlrev_b64 v[0:1], 11, v[0:1]
	v_lshl_add_u64 v[0:1], v[4:5], 0, v[0:1]
	v_add_co_u32_e32 v2, vcc, 0x600000, v6
	s_nop 1
	v_addc_co_u32_e32 v3, vcc, 0, v7, vcc
	global_load_dwordx4 v[88:91], v[0:1], off
	global_load_dwordx4 v[92:95], v[2:3], off

.LBB0_697:
	s_waitcnt vmcnt(0)
	ds_write_b128 v197, v[96:99] offset:4096
	ds_write_b128 v198, v[100:103] offset:8704
	ds_write_b128 v197, v[124:127] offset:5248
	ds_write_b128 v198, v[116:119] offset:9984
	ds_write_b128 v197, v[132:135] offset:6400
	ds_write_b128 v198, v[128:131] offset:11264
	ds_write_b128 v197, v[140:143] offset:7552
	ds_write_b128 v198, v[136:139] offset:12544
	s_waitcnt lgkmcnt(0)
	s_cmp_eq_u32 s53, 32
	s_cbranch_scc1 .LBB0_696
	s_sub_i32 s96, s53, 64
	v_lshl_add_u64 v[32:33], v[170:171], 0, s[96:97]
	v_lshl_add_u64 v[34:35], s[96:97], 1, v[174:175]
	v_lshlrev_b64 v[32:33], 11, v[32:33]
	v_lshl_add_u64 v[32:33], v[172:173], 0, v[32:33]
	v_lshl_add_u64 v[36:37], v[34:35], 0, v[182:183]
	global_load_dwordx4 v[96:99], v[32:33], off
	global_load_dwordx4 v[100:103], v[36:37], off
	v_add_co_u32_e32 v36, vcc, 0x4000, v32
	v_lshl_add_u64 v[38:39], v[34:35], 0, v[184:185]
	s_nop 0
	v_addc_co_u32_e32 v37, vcc, 0, v33, vcc
	global_load_dwordx4 v[124:127], v[36:37], off
	global_load_dwordx4 v[116:119], v[38:39], off
	v_add_co_u32_e32 v36, vcc, s62, v32
	v_lshl_add_u64 v[38:39], v[34:35], 0, v[186:187]
	s_nop 0
	v_addc_co_u32_e32 v37, vcc, 0, v33, vcc
	v_add_co_u32_e32 v32, vcc, 0xc000, v32
	global_load_dwordx4 v[132:135], v[36:37], off
	global_load_dwordx4 v[128:131], v[38:39], off
	v_addc_co_u32_e32 v33, vcc, 0, v33, vcc
	v_lshl_add_u64 v[34:35], v[34:35], 0, v[188:189]
	global_load_dwordx4 v[140:143], v[32:33], off
	global_load_dwordx4 v[136:139], v[34:35], off
	s_branch .LBB0_696

.LBB0_714:
	s_lshl_b32 s9, s36, 8
	s_cmp_eq_u32 s36, s34
	s_cbranch_scc1 .LBB0_718
	s_barrier
	s_and_saveexec_b64 s[16:17], s[2:3]
	s_cbranch_execz .LBB0_717
	v_add_u32_e32 v140, s9, v144
	v_ashrrev_i32_e32 v141, 31, v140
	v_lshl_add_u64 v[140:141], v[140:141], 4, s[46:47]
	global_load_dwordx4 v[148:151], v[140:141], off
	s_waitcnt vmcnt(0) lgkmcnt(0)
	v_mov_b32_e32 v140, v149
	v_mov_b32_e32 v141, v150
	v_mov_b32_e32 v149, v151
	v_pk_add_f32 v[140:141], v[140:141], v[148:149]
	s_nop 0
	v_add_f32_e32 v140, v140, v141
	v_fmamk_f32 v140, v140, 0x3a800000, v205
	v_mul_f32_e32 v141, 0x4b800000, v140
	v_cmp_gt_f32_e32 vcc, s67, v140
	s_nop 1
	v_cndmask_b32_e32 v140, v140, v141, vcc
	v_rsq_f32_e32 v140, v140
	s_nop 0
	v_mul_f32_e32 v141, 0x45800000, v140
	v_cndmask_b32_e32 v140, v140, v141, vcc
	ds_write_b32 v145, v140

.LBB0_718:
	ds_read2_b32 v[140:141], v146 offset1:16
	s_cmp_lt_u32 s35, 4
	v_add_u32_e32 v148, s9, v142
	s_cselect_b64 vcc, -1, 0
	v_cndmask_b32_e32 v153, 1.0, v208, vcc
	s_and_b64 s[16:17], vcc, exec
	v_ashrrev_i32_e32 v149, 31, v148
	s_waitcnt lgkmcnt(0)
	v_mul_f32_e32 v152, v153, v140
	v_mul_f32_e32 v154, v153, v141
	s_cselect_b32 s17, s41, s51
	s_cselect_b32 s16, s40, s50
	v_lshlrev_b64 v[140:141], 11, v[148:149]
	s_lshl_b32 s9, s35, 9
	v_lshl_add_u64 v[140:141], s[16:17], 0, v[140:141]
	s_and_b32 s96, s9, 0x600
	v_lshl_add_u64 v[140:141], v[140:141], 0, s[96:97]
	v_pk_mul_f32 v[126:127], v[126:127], v[152:153] op_sel_hi:[1,0]
	v_pk_mul_f32 v[124:125], v[124:125], v[152:153] op_sel_hi:[1,0]
	v_pk_mul_f32 v[158:159], v[122:123], v[152:153] op_sel_hi:[1,0]
	v_pk_mul_f32 v[122:123], v[120:121], v[152:153] op_sel_hi:[1,0]
	v_lshl_add_u64 v[140:141], v[140:141], 0, v[176:177]
	v_cvt_pk_f16_f32 v120, v124, v125
	v_cvt_pk_f16_f32 v121, v126, v127
	v_cvt_pk_f16_f32 v122, v122, v123
	v_cvt_pk_f16_f32 v123, v158, v159
	ds_read2_b32 v[150:151], v146 offset0:32 offset1:48
	global_store_dwordx4 v[140:141], v[120:123], off
	v_pk_mul_f32 v[118:119], v[118:119], v[152:153] op_sel_hi:[1,0]
	v_pk_mul_f32 v[116:117], v[116:117], v[152:153] op_sel_hi:[1,0]
	v_pk_mul_f32 v[120:121], v[110:111], v[152:153] op_sel_hi:[1,0]
	v_pk_mul_f32 v[110:111], v[108:109], v[152:153] op_sel_hi:[1,0]
	v_cvt_pk_f16_f32 v108, v116, v117
	v_cvt_pk_f16_f32 v109, v118, v119
	v_cvt_pk_f16_f32 v110, v110, v111
	v_cvt_pk_f16_f32 v111, v120, v121
	global_store_dwordx4 v[140:141], v[108:111], off offset:256
	v_pk_mul_f32 v[112:113], v[112:113], v[154:155] op_sel_hi:[1,0]
	v_pk_mul_f32 v[102:103], v[102:103], v[154:155] op_sel_hi:[1,0]
	v_or_b32_e32 v108, 16, v148
	v_ashrrev_i32_e32 v109, 31, v108
	v_lshlrev_b64 v[108:109], 11, v[108:109]
	v_lshl_add_u64 v[108:109], s[16:17], 0, v[108:109]
	v_lshl_add_u64 v[108:109], v[108:109], 0, s[96:97]
	v_pk_mul_f32 v[110:111], v[114:115], v[154:155] op_sel_hi:[1,0]
	v_pk_mul_f32 v[114:115], v[106:107], v[154:155] op_sel_hi:[1,0]
	v_pk_mul_f32 v[106:107], v[104:105], v[154:155] op_sel_hi:[1,0]
	v_lshl_add_u64 v[108:109], v[108:109], 0, v[176:177]
	v_cvt_pk_f16_f32 v104, v112, v113
	v_cvt_pk_f16_f32 v105, v110, v111
	v_cvt_pk_f16_f32 v106, v106, v107
	v_cvt_pk_f16_f32 v107, v114, v115
	global_store_dwordx4 v[108:109], v[104:107], off
	v_pk_mul_f32 v[100:101], v[100:101], v[154:155] op_sel_hi:[1,0]
	s_waitcnt lgkmcnt(0)
	v_mul_f32_e32 v150, v153, v150
	v_pk_mul_f32 v[104:105], v[94:95], v[154:155] op_sel_hi:[1,0]
	v_pk_mul_f32 v[94:95], v[92:93], v[154:155] op_sel_hi:[1,0]
	v_cvt_pk_f16_f32 v92, v100, v101
	v_cvt_pk_f16_f32 v93, v102, v103
	v_cvt_pk_f16_f32 v94, v94, v95
	v_cvt_pk_f16_f32 v95, v104, v105
	global_store_dwordx4 v[108:109], v[92:95], off offset:256
	v_pk_mul_f32 v[96:97], v[96:97], v[150:151] op_sel_hi:[1,0]
	v_pk_mul_f32 v[86:87], v[86:87], v[150:151] op_sel_hi:[1,0]
	v_or_b32_e32 v92, 32, v148
	v_ashrrev_i32_e32 v93, 31, v92
	v_lshlrev_b64 v[92:93], 11, v[92:93]
	v_lshl_add_u64 v[92:93], s[16:17], 0, v[92:93]
	v_lshl_add_u64 v[92:93], v[92:93], 0, s[96:97]
	v_pk_mul_f32 v[94:95], v[98:99], v[150:151] op_sel_hi:[1,0]
	v_pk_mul_f32 v[98:99], v[90:91], v[150:151] op_sel_hi:[1,0]
	v_pk_mul_f32 v[90:91], v[88:89], v[150:151] op_sel_hi:[1,0]
	v_lshl_add_u64 v[92:93], v[92:93], 0, v[176:177]
	v_cvt_pk_f16_f32 v88, v96, v97
	v_cvt_pk_f16_f32 v89, v94, v95
	v_cvt_pk_f16_f32 v90, v90, v91
	v_cvt_pk_f16_f32 v91, v98, v99
	global_store_dwordx4 v[92:93], v[88:91], off
	v_pk_mul_f32 v[84:85], v[84:85], v[150:151] op_sel_hi:[1,0]
	v_mul_f32_e32 v156, v153, v151
	v_pk_mul_f32 v[88:89], v[78:79], v[150:151] op_sel_hi:[1,0]
	v_pk_mul_f32 v[78:79], v[76:77], v[150:151] op_sel_hi:[1,0]
	v_cvt_pk_f16_f32 v76, v84, v85
	v_cvt_pk_f16_f32 v77, v86, v87
	v_cvt_pk_f16_f32 v78, v78, v79
	v_cvt_pk_f16_f32 v79, v88, v89
	global_store_dwordx4 v[92:93], v[76:79], off offset:256
	v_pk_mul_f32 v[80:81], v[80:81], v[156:157] op_sel_hi:[1,0]
	v_pk_mul_f32 v[70:71], v[70:71], v[156:157] op_sel_hi:[1,0]
	v_or_b32_e32 v76, 48, v148
	v_ashrrev_i32_e32 v77, 31, v76
	v_lshlrev_b64 v[76:77], 11, v[76:77]
	v_lshl_add_u64 v[76:77], s[16:17], 0, v[76:77]
	v_lshl_add_u64 v[76:77], v[76:77], 0, s[96:97]
	v_pk_mul_f32 v[78:79], v[82:83], v[156:157] op_sel_hi:[1,0]
	v_pk_mul_f32 v[82:83], v[74:75], v[156:157] op_sel_hi:[1,0]
	v_pk_mul_f32 v[74:75], v[72:73], v[156:157] op_sel_hi:[1,0]
	v_lshl_add_u64 v[76:77], v[76:77], 0, v[176:177]
	v_cvt_pk_f16_f32 v72, v80, v81
	v_cvt_pk_f16_f32 v73, v78, v79
	v_cvt_pk_f16_f32 v74, v74, v75
	v_cvt_pk_f16_f32 v75, v82, v83
	global_store_dwordx4 v[76:77], v[72:75], off
	v_pk_mul_f32 v[68:69], v[68:69], v[156:157] op_sel_hi:[1,0]
	s_mov_b32 s9, 0x40000
	v_pk_mul_f32 v[72:73], v[66:67], v[156:157] op_sel_hi:[1,0]
	v_pk_mul_f32 v[66:67], v[64:65], v[156:157] op_sel_hi:[1,0]
	v_cvt_pk_f16_f32 v64, v68, v69
	v_cvt_pk_f16_f32 v65, v70, v71
	v_cvt_pk_f16_f32 v66, v66, v67
	v_cvt_pk_f16_f32 v67, v72, v73
	global_store_dwordx4 v[76:77], v[64:67], off offset:256
	ds_read2_b32 v[64:65], v146 offset0:128 offset1:144
	ds_read2_b32 v[66:67], v146 offset0:160 offset1:176
	s_mov_b64 s[16:17], 0x40000
	v_lshl_add_u64 v[72:73], v[140:141], 0, s[16:17]
	s_mov_b64 s[16:17], 0x48000
	s_waitcnt lgkmcnt(0)
	v_mul_f32_e32 v64, v153, v64
	v_pk_mul_f32 v[60:61], v[60:61], v[64:65] op_sel_hi:[1,0]
	v_pk_mul_f32 v[62:63], v[62:63], v[64:65] op_sel_hi:[1,0]
	v_pk_mul_f32 v[74:75], v[58:59], v[64:65] op_sel_hi:[1,0]
	v_pk_mul_f32 v[58:59], v[56:57], v[64:65] op_sel_hi:[1,0]
	v_cvt_pk_f16_f32 v56, v60, v61
	v_add_co_u32_e32 v60, vcc, s9, v140
	v_cvt_pk_f16_f32 v57, v62, v63
	v_cvt_pk_f16_f32 v58, v58, v59
	v_cvt_pk_f16_f32 v59, v74, v75
	v_addc_co_u32_e32 v61, vcc, 0, v141, vcc
	global_store_dwordx4 v[60:61], v[56:59], off
	v_pk_mul_f32 v[50:51], v[50:51], v[64:65] op_sel_hi:[1,0]
	v_pk_mul_f32 v[48:49], v[48:49], v[64:65] op_sel_hi:[1,0]
	v_pk_mul_f32 v[56:57], v[42:43], v[64:65] op_sel_hi:[1,0]
	v_pk_mul_f32 v[42:43], v[40:41], v[64:65] op_sel_hi:[1,0]
	v_mul_f32_e32 v68, v153, v65
	v_cvt_pk_f16_f32 v40, v48, v49
	v_cvt_pk_f16_f32 v41, v50, v51
	v_cvt_pk_f16_f32 v42, v42, v43
	v_cvt_pk_f16_f32 v43, v56, v57
	global_store_dwordx4 v[72:73], v[40:43], off offset:256
	v_pk_mul_f32 v[44:45], v[44:45], v[68:69] op_sel_hi:[1,0]
	s_mov_b32 s9, 0x48000
	v_pk_mul_f32 v[42:43], v[54:55], v[68:69] op_sel_hi:[1,0]
	v_pk_mul_f32 v[40:41], v[52:53], v[68:69] op_sel_hi:[1,0]
	v_pk_mul_f32 v[46:47], v[46:47], v[68:69] op_sel_hi:[1,0]
	v_cvt_pk_f16_f32 v40, v40, v41
	v_cvt_pk_f16_f32 v41, v42, v43
	v_cvt_pk_f16_f32 v42, v44, v45
	v_add_co_u32_e32 v44, vcc, s9, v140
	v_cvt_pk_f16_f32 v43, v46, v47
	s_nop 0
	v_addc_co_u32_e32 v45, vcc, 0, v141, vcc
	global_store_dwordx4 v[44:45], v[40:43], off
	v_pk_mul_f32 v[34:35], v[34:35], v[68:69] op_sel_hi:[1,0]
	v_pk_mul_f32 v[32:33], v[32:33], v[68:69] op_sel_hi:[1,0]
	v_pk_mul_f32 v[40:41], v[26:27], v[68:69] op_sel_hi:[1,0]
	v_pk_mul_f32 v[26:27], v[24:25], v[68:69] op_sel_hi:[1,0]
	v_mul_f32_e32 v66, v153, v66
	v_lshl_add_u64 v[48:49], v[140:141], 0, s[16:17]
	v_cvt_pk_f16_f32 v24, v32, v33
	v_cvt_pk_f16_f32 v25, v34, v35
	v_cvt_pk_f16_f32 v26, v26, v27
	v_cvt_pk_f16_f32 v27, v40, v41
	global_store_dwordx4 v[48:49], v[24:27], off offset:256
	v_pk_mul_f32 v[28:29], v[28:29], v[66:67] op_sel_hi:[1,0]
	s_mov_b32 s9, 0x50000
	v_pk_mul_f32 v[26:27], v[38:39], v[66:67] op_sel_hi:[1,0]
	v_pk_mul_f32 v[24:25], v[36:37], v[66:67] op_sel_hi:[1,0]
	v_pk_mul_f32 v[30:31], v[30:31], v[66:67] op_sel_hi:[1,0]
	v_cvt_pk_f16_f32 v24, v24, v25
	v_cvt_pk_f16_f32 v25, v26, v27
	v_cvt_pk_f16_f32 v26, v28, v29
	v_add_co_u32_e32 v28, vcc, s9, v140
	v_cvt_pk_f16_f32 v27, v30, v31
	s_nop 0
	v_addc_co_u32_e32 v29, vcc, 0, v141, vcc
	s_mov_b64 s[16:17], 0x50000
	global_store_dwordx4 v[28:29], v[24:27], off
	v_pk_mul_f32 v[18:19], v[18:19], v[66:67] op_sel_hi:[1,0]
	v_pk_mul_f32 v[16:17], v[16:17], v[66:67] op_sel_hi:[1,0]
	v_pk_mul_f32 v[24:25], v[10:11], v[66:67] op_sel_hi:[1,0]
	v_pk_mul_f32 v[10:11], v[8:9], v[66:67] op_sel_hi:[1,0]
	v_mul_f32_e32 v70, v153, v67
	v_lshl_add_u64 v[32:33], v[140:141], 0, s[16:17]
	v_cvt_pk_f16_f32 v8, v16, v17
	v_cvt_pk_f16_f32 v9, v18, v19
	v_cvt_pk_f16_f32 v10, v10, v11
	v_cvt_pk_f16_f32 v11, v24, v25
	global_store_dwordx4 v[32:33], v[8:11], off offset:256
	v_pk_mul_f32 v[12:13], v[12:13], v[70:71] op_sel_hi:[1,0]
	s_mov_b32 s9, 0x58000
	v_pk_mul_f32 v[10:11], v[22:23], v[70:71] op_sel_hi:[1,0]
	v_pk_mul_f32 v[8:9], v[20:21], v[70:71] op_sel_hi:[1,0]
	v_pk_mul_f32 v[14:15], v[14:15], v[70:71] op_sel_hi:[1,0]
	v_cvt_pk_f16_f32 v8, v8, v9
	v_cvt_pk_f16_f32 v9, v10, v11
	v_cvt_pk_f16_f32 v10, v12, v13
	v_add_co_u32_e32 v12, vcc, s9, v140
	v_cvt_pk_f16_f32 v11, v14, v15
	s_nop 0
	v_addc_co_u32_e32 v13, vcc, 0, v141, vcc
	s_mov_b64 s[16:17], 0x58000
	global_store_dwordx4 v[12:13], v[8:11], off
	v_pk_mul_f32 v[6:7], v[6:7], v[70:71] op_sel_hi:[1,0]
	v_pk_mul_f32 v[4:5], v[4:5], v[70:71] op_sel_hi:[1,0]
	v_pk_mul_f32 v[8:9], v[2:3], v[70:71] op_sel_hi:[1,0]
	v_pk_mul_f32 v[2:3], v[0:1], v[70:71] op_sel_hi:[1,0]
	v_lshl_add_u64 v[16:17], v[140:141], 0, s[16:17]
	v_cvt_pk_f16_f32 v0, v4, v5
	v_cvt_pk_f16_f32 v1, v6, v7
	v_cvt_pk_f16_f32 v2, v2, v3
	v_cvt_pk_f16_f32 v3, v8, v9
	global_store_dwordx4 v[16:17], v[0:3], off offset:256
	s_andn2_b64 vcc, exec, s[4:5]
	s_mov_b64 s[4:5], -1
	s_cbranch_vccnz .LBB0_707
	s_andn2_b64 vcc, exec, s[0:1]
	s_cbranch_vccnz .LBB0_706
	s_barrier
	s_branch .LBB0_706

.LBB0_760:
	v_lshl_or_b32 v156, s30, 8, v168
	v_or_b32_e32 v128, 4, v156
	v_or_b32_e32 v130, 0x80, v156
	v_ashrrev_i32_e32 v157, 31, v156
	v_ashrrev_i32_e32 v129, 31, v128
	v_or_b32_e32 v150, 0x84, v156
	v_lshl_add_u64 v[132:133], v[156:157], 4, s[46:47]
	v_lshl_add_u64 v[128:129], v[128:129], 4, s[46:47]
	v_ashrrev_i32_e32 v131, 31, v130
	global_load_dwordx4 v[136:139], v[132:133], off
	global_load_dwordx4 v[162:165], v[128:129], off
	v_lshl_add_u64 v[128:129], v[130:131], 4, s[46:47]
	v_ashrrev_i32_e32 v151, 31, v150
	global_load_dwordx4 v[132:135], v[128:129], off
	v_lshl_add_u64 v[128:129], v[150:151], 4, s[46:47]
	v_or_b32_e32 v150, 1, v156
	v_ashrrev_i32_e32 v151, 31, v150
	v_lshl_add_u64 v[150:151], v[150:151], 4, s[46:47]
	global_load_dwordx4 v[158:161], v[150:151], off
	s_mov_b32 s0, 0x358637bd
	global_load_dwordx4 v[128:131], v[128:129], off
	v_lshl_add_u32 v152, s31, 8, v166
	s_waitcnt vmcnt(0) lgkmcnt(0)
	v_mov_b32_e32 v150, v136
	v_mov_b32_e32 v154, v162
	v_mov_b32_e32 v151, v158
	v_mov_b32_e32 v158, v137
	v_pk_add_f32 v[136:137], v[150:151], v[158:159]
	v_mov_b32_e32 v150, v138
	v_mov_b32_e32 v151, v160
	v_mov_b32_e32 v160, v139
	v_pk_add_f32 v[138:139], v[150:151], v[160:161]
	v_mov_b64_e32 v[160:161], s[0:1]
	v_pk_add_f32 v[136:137], v[136:137], v[138:139]
	v_mov_b32_e32 v158, v132
	v_pk_fma_f32 v[136:137], v[136:137], s[82:83], v[160:161] op_sel_hi:[1,0,0]
	s_nop 0
	v_mul_f32_e32 v138, 0x4b800000, v136
	v_cmp_gt_f32_e64 s[0:1], s67, v136
	v_cmp_gt_f32_e32 vcc, s67, v137
	s_nop 0
	v_cndmask_b32_e64 v136, v136, v138, s[0:1]
	v_mul_f32_e32 v138, 0x4b800000, v137
	v_cndmask_b32_e32 v137, v137, v138, vcc
	v_rsq_f32_e32 v136, v136
	v_rsq_f32_e32 v137, v137
	s_nop 0
	v_pk_mul_f32 v[138:139], v[136:137], s[88:89] op_sel_hi:[1,0]
	s_nop 0
	v_cndmask_b32_e64 v150, v136, v138, s[0:1]
	v_or_b32_e32 v136, 5, v156
	v_cndmask_b32_e32 v151, v137, v139, vcc
	v_ashrrev_i32_e32 v137, 31, v136
	v_lshl_add_u64 v[136:137], v[136:137], 4, s[46:47]
	global_load_dwordx4 v[136:139], v[136:137], off
	v_pk_mul_f32 v[124:125], v[124:125], v[150:151]
	v_pk_mul_f32 v[112:113], v[112:113], v[150:151]
	v_pk_mul_f32 v[96:97], v[96:97], v[150:151]
	v_pk_mul_f32 v[80:81], v[80:81], v[150:151]
	v_pk_mul_f32 v[60:61], v[60:61], v[150:151]
	s_waitcnt vmcnt(0) lgkmcnt(0)
	v_mov_b32_e32 v155, v136
	v_mov_b32_e32 v136, v163
	v_pk_add_f32 v[136:137], v[154:155], v[136:137]
	v_mov_b32_e32 v154, v164
	v_mov_b32_e32 v155, v138
	v_mov_b32_e32 v138, v165
	v_pk_add_f32 v[138:139], v[154:155], v[138:139]
	v_or_b32_e32 v164, 3, v156
	v_pk_add_f32 v[136:137], v[136:137], v[138:139]
	v_ashrrev_i32_e32 v165, 31, v164
	v_pk_fma_f32 v[136:137], v[136:137], s[82:83], v[160:161] op_sel_hi:[1,0,0]
	v_lshl_add_u64 v[164:165], v[164:165], 4, s[46:47]
	v_mul_f32_e32 v138, 0x4b800000, v136
	v_cmp_gt_f32_e64 s[0:1], s67, v136
	v_cmp_gt_f32_e32 vcc, s67, v137
	global_load_dwordx4 v[182:185], v[164:165], off
	v_cndmask_b32_e64 v136, v136, v138, s[0:1]
	v_mul_f32_e32 v138, 0x4b800000, v137
	v_cndmask_b32_e32 v137, v137, v138, vcc
	v_rsq_f32_e32 v136, v136
	v_rsq_f32_e32 v137, v137
	s_waitcnt vmcnt(0) lgkmcnt(0)
	v_mov_b32_e32 v165, v182
	v_pk_mul_f32 v[138:139], v[136:137], s[88:89] op_sel_hi:[1,0]
	s_nop 0
	v_cndmask_b32_e64 v154, v136, v138, s[0:1]
	v_or_b32_e32 v136, 0x81, v156
	v_cndmask_b32_e32 v155, v137, v139, vcc
	v_ashrrev_i32_e32 v137, 31, v136
	v_lshl_add_u64 v[136:137], v[136:137], 4, s[46:47]
	global_load_dwordx4 v[136:139], v[136:137], off
	v_pk_mul_f32 v[44:45], v[44:45], v[154:155]
	v_pk_mul_f32 v[28:29], v[28:29], v[154:155]
	v_pk_mul_f32 v[12:13], v[12:13], v[154:155]
	s_waitcnt vmcnt(0) lgkmcnt(0)
	v_mov_b32_e32 v159, v136
	v_mov_b32_e32 v136, v133
	v_pk_add_f32 v[132:133], v[158:159], v[136:137]
	v_mov_b32_e32 v136, v134
	v_mov_b32_e32 v137, v138
	v_mov_b32_e32 v138, v135
	v_pk_add_f32 v[134:135], v[136:137], v[138:139]
	s_nop 0
	v_pk_add_f32 v[132:133], v[132:133], v[134:135]
	s_nop 0
	v_pk_fma_f32 v[132:133], v[132:133], s[82:83], v[160:161] op_sel_hi:[1,0,0]
	s_nop 0
	v_mul_f32_e32 v134, 0x4b800000, v132
	v_cmp_gt_f32_e64 s[0:1], s67, v132
	v_cmp_gt_f32_e32 vcc, s67, v133
	s_nop 0
	v_cndmask_b32_e64 v132, v132, v134, s[0:1]
	v_mul_f32_e32 v134, 0x4b800000, v133
	v_cndmask_b32_e32 v133, v133, v134, vcc
	v_rsq_f32_e32 v132, v132
	v_rsq_f32_e32 v133, v133
	s_nop 0
	v_pk_mul_f32 v[134:135], v[132:133], s[88:89] op_sel_hi:[1,0]
	s_nop 0
	v_cndmask_b32_e64 v158, v132, v134, s[0:1]
	v_or_b32_e32 v132, 0x85, v156
	v_cndmask_b32_e32 v159, v133, v135, vcc
	v_ashrrev_i32_e32 v133, 31, v132
	v_lshl_add_u64 v[132:133], v[132:133], 4, s[46:47]
	global_load_dwordx4 v[132:135], v[132:133], off
	v_mov_b32_e32 v136, v128
	v_pk_mul_f32 v[116:117], v[116:117], v[158:159]
	v_pk_mul_f32 v[100:101], v[100:101], v[158:159]
	v_pk_mul_f32 v[84:85], v[84:85], v[158:159]
	v_pk_mul_f32 v[68:69], v[68:69], v[158:159]
	v_pk_mul_f32 v[48:49], v[48:49], v[158:159]
	v_pk_mul_f32 v[32:33], v[32:33], v[158:159]
	v_pk_mul_f32 v[16:17], v[16:17], v[158:159]
	v_pk_mul_f32 v[4:5], v[4:5], v[158:159]
	s_waitcnt vmcnt(0) lgkmcnt(0)
	v_mov_b32_e32 v137, v132
	v_mov_b32_e32 v132, v129
	v_pk_add_f32 v[128:129], v[136:137], v[132:133]
	v_mov_b32_e32 v132, v130
	v_mov_b32_e32 v133, v134
	v_mov_b32_e32 v134, v131
	v_pk_add_f32 v[130:131], v[132:133], v[134:135]
	s_nop 0
	v_pk_add_f32 v[128:129], v[128:129], v[130:131]
	s_nop 0
	v_pk_fma_f32 v[128:129], v[128:129], s[82:83], v[160:161] op_sel_hi:[1,0,0]
	s_nop 0
	v_mul_f32_e32 v130, 0x4b800000, v128
	v_cmp_gt_f32_e64 s[0:1], s67, v128
	v_cmp_gt_f32_e32 vcc, s67, v129
	s_nop 0
	v_cndmask_b32_e64 v128, v128, v130, s[0:1]
	v_mul_f32_e32 v130, 0x4b800000, v129
	v_cndmask_b32_e32 v129, v129, v130, vcc
	v_rsq_f32_e32 v128, v128
	v_rsq_f32_e32 v129, v129
	s_nop 0
	v_pk_mul_f32 v[130:131], v[128:129], s[88:89] op_sel_hi:[1,0]
	s_nop 0
	v_cndmask_b32_e64 v162, v128, v130, s[0:1]
	v_or_b32_e32 v128, 2, v156
	v_cndmask_b32_e32 v163, v129, v131, vcc
	v_ashrrev_i32_e32 v129, 31, v128
	v_lshl_add_u64 v[128:129], v[128:129], 4, s[46:47]
	global_load_dwordx4 v[170:173], v[128:129], off
	v_or_b32_e32 v128, 6, v156
	v_ashrrev_i32_e32 v129, 31, v128
	v_lshl_add_u64 v[128:129], v[128:129], 4, s[46:47]
	global_load_dwordx4 v[136:139], v[128:129], off
	s_waitcnt vmcnt(0) lgkmcnt(0)
	v_mov_b32_e32 v164, v170
	v_mov_b32_e32 v182, v171
	v_mov_b32_e32 v170, v172
	v_mov_b32_e32 v171, v184
	v_mov_b32_e32 v184, v173
	v_pk_add_f32 v[164:165], v[164:165], v[182:183]
	v_pk_add_f32 v[170:171], v[170:171], v[184:185]
	s_nop 0
	v_pk_add_f32 v[164:165], v[164:165], v[170:171]
	s_nop 0
	v_pk_fma_f32 v[164:165], v[164:165], s[82:83], v[160:161] op_sel_hi:[1,0,0]
	s_nop 0
	v_mul_f32_e32 v153, 0x4b800000, v164
	v_cmp_gt_f32_e64 s[0:1], s67, v164
	v_cmp_gt_f32_e32 vcc, s67, v165
	s_nop 0
	v_cndmask_b32_e64 v153, v164, v153, s[0:1]
	v_rsq_f32_e32 v164, v153
	v_mul_f32_e32 v153, 0x4b800000, v165
	v_cndmask_b32_e32 v153, v165, v153, vcc
	v_rsq_f32_e32 v165, v153
	v_ashrrev_i32_e32 v153, 31, v152
	v_pk_mul_f32 v[170:171], v[164:165], s[88:89] op_sel_hi:[1,0]
	s_nop 0
	v_cndmask_b32_e64 v164, v164, v170, s[0:1]
	v_or_b32_e32 v170, 7, v156
	v_cndmask_b32_e32 v165, v165, v171, vcc
	v_ashrrev_i32_e32 v171, 31, v170
	v_lshl_add_u64 v[170:171], v[170:171], 4, s[46:47]
	global_load_dwordx4 v[170:173], v[170:171], off
	v_mov_b32_e32 v174, v136
	v_or_b32_e32 v128, 0x82, v156
	v_ashrrev_i32_e32 v129, 31, v128
	v_lshl_add_u64 v[128:129], v[128:129], 4, s[46:47]
	global_load_dwordx4 v[132:135], v[128:129], off
	v_pk_mul_f32 v[126:127], v[126:127], v[164:165]
	v_pk_mul_f32 v[62:63], v[62:63], v[164:165]
	s_waitcnt vmcnt(0) lgkmcnt(0)
	v_mov_b32_e32 v175, v170
	v_mov_b32_e32 v170, v137
	v_pk_add_f32 v[136:137], v[174:175], v[170:171]
	v_mov_b32_e32 v170, v138
	v_mov_b32_e32 v171, v172
	v_mov_b32_e32 v172, v139
	v_pk_add_f32 v[138:139], v[170:171], v[172:173]
	s_nop 0
	v_pk_add_f32 v[136:137], v[136:137], v[138:139]
	s_nop 0
	v_pk_fma_f32 v[136:137], v[136:137], s[82:83], v[160:161] op_sel_hi:[1,0,0]
	s_nop 0
	v_mul_f32_e32 v138, 0x4b800000, v136
	v_cmp_gt_f32_e64 s[0:1], s67, v136
	v_cmp_gt_f32_e32 vcc, s67, v137
	s_nop 0
	v_cndmask_b32_e64 v136, v136, v138, s[0:1]
	v_mul_f32_e32 v138, 0x4b800000, v137
	v_cndmask_b32_e32 v137, v137, v138, vcc
	v_rsq_f32_e32 v136, v136
	v_rsq_f32_e32 v137, v137
	s_nop 0
	v_pk_mul_f32 v[138:139], v[136:137], s[88:89] op_sel_hi:[1,0]
	s_nop 0
	v_cndmask_b32_e64 v136, v136, v138, s[0:1]
	v_or_b32_e32 v138, 0x83, v156
	v_cndmask_b32_e32 v137, v137, v139, vcc
	v_ashrrev_i32_e32 v139, 31, v138
	v_lshl_add_u64 v[138:139], v[138:139], 4, s[46:47]
	global_load_dwordx4 v[170:173], v[138:139], off
	v_mov_b32_e32 v138, v132
	v_or_b32_e32 v128, 0x86, v156
	v_ashrrev_i32_e32 v129, 31, v128
	v_lshl_add_u64 v[128:129], v[128:129], 4, s[46:47]
	global_load_dwordx4 v[128:131], v[128:129], off
	v_pk_mul_f32 v[46:47], v[46:47], v[136:137]
	v_pk_mul_f32 v[30:31], v[30:31], v[136:137]
	v_pk_mul_f32 v[14:15], v[14:15], v[136:137]
	s_waitcnt vmcnt(0) lgkmcnt(0)
	v_mov_b32_e32 v139, v170
	v_mov_b32_e32 v170, v133
	v_pk_add_f32 v[132:133], v[138:139], v[170:171]
	v_mov_b32_e32 v138, v134
	v_mov_b32_e32 v139, v172
	v_mov_b32_e32 v172, v135
	v_pk_add_f32 v[134:135], v[138:139], v[172:173]
	s_nop 0
	v_pk_add_f32 v[132:133], v[132:133], v[134:135]
	s_nop 0
	v_pk_fma_f32 v[132:133], v[132:133], s[82:83], v[160:161] op_sel_hi:[1,0,0]
	s_nop 0
	v_mul_f32_e32 v134, 0x4b800000, v132
	v_cmp_gt_f32_e64 s[0:1], s67, v132
	v_cmp_gt_f32_e32 vcc, s67, v133
	s_nop 0
	v_cndmask_b32_e64 v132, v132, v134, s[0:1]
	v_mul_f32_e32 v134, 0x4b800000, v133
	v_cndmask_b32_e32 v133, v133, v134, vcc
	v_rsq_f32_e32 v132, v132
	v_rsq_f32_e32 v133, v133
	s_nop 0
	v_pk_mul_f32 v[134:135], v[132:133], s[88:89] op_sel_hi:[1,0]
	s_nop 0
	v_cndmask_b32_e64 v138, v132, v134, s[0:1]
	v_or_b32_e32 v132, 0x87, v156
	v_cndmask_b32_e32 v139, v133, v135, vcc
	v_ashrrev_i32_e32 v133, 31, v132
	v_lshl_add_u64 v[132:133], v[132:133], 4, s[46:47]
	global_load_dwordx4 v[132:135], v[132:133], off
	v_mov_b32_e32 v170, v128
	v_pk_mul_f32 v[118:119], v[118:119], v[138:139]
	v_pk_mul_f32 v[102:103], v[102:103], v[138:139]
	v_pk_mul_f32 v[86:87], v[86:87], v[138:139]
	v_pk_mul_f32 v[70:71], v[70:71], v[138:139]
	v_pk_mul_f32 v[50:51], v[50:51], v[138:139]
	v_pk_mul_f32 v[34:35], v[34:35], v[138:139]
	v_pk_mul_f32 v[18:19], v[18:19], v[138:139]
	v_pk_mul_f32 v[6:7], v[6:7], v[138:139]
	s_waitcnt vmcnt(0) lgkmcnt(0)
	v_mov_b32_e32 v171, v132
	v_mov_b32_e32 v132, v129
	v_pk_add_f32 v[128:129], v[170:171], v[132:133]
	v_mov_b32_e32 v132, v130
	v_mov_b32_e32 v133, v134
	v_mov_b32_e32 v134, v131
	v_pk_add_f32 v[130:131], v[132:133], v[134:135]
	v_lshlrev_b64 v[132:133], 1, v[156:157]
	v_pk_add_f32 v[128:129], v[128:129], v[130:131]
	v_pk_mul_f32 v[134:135], v[122:123], v[136:137]
	v_pk_fma_f32 v[128:129], v[128:129], s[82:83], v[160:161] op_sel_hi:[1,0,0]
	v_pk_mul_f32 v[122:123], v[120:121], v[154:155]
	v_mul_f32_e32 v130, 0x4b800000, v128
	v_cmp_gt_f32_e64 s[0:1], s67, v128
	v_cmp_gt_f32_e32 vcc, s67, v129
	v_cvt_pk_f16_f32 v120, v124, v125
	v_cndmask_b32_e64 v128, v128, v130, s[0:1]
	v_mul_f32_e32 v130, 0x4b800000, v129
	v_cndmask_b32_e32 v129, v129, v130, vcc
	v_rsq_f32_e32 v128, v128
	v_rsq_f32_e32 v129, v129
	v_cvt_pk_f16_f32 v121, v126, v127
	v_cvt_pk_f16_f32 v122, v122, v123
	v_cvt_pk_f16_f32 v123, v134, v135
	v_pk_mul_f32 v[130:131], v[128:129], s[88:89] op_sel_hi:[1,0]
	s_nop 0
	v_cndmask_b32_e32 v129, v129, v131, vcc
	v_cndmask_b32_e64 v128, v128, v130, s[0:1]
	v_lshlrev_b64 v[130:131], 17, v[152:153]
	v_lshl_add_u64 v[130:131], s[42:43], 0, v[130:131]
	v_lshl_add_u64 v[130:131], v[130:131], 0, v[132:133]
	global_store_dwordx4 v[130:131], v[120:123], off
	s_mov_b64 s[0:1], 0x1000000
	s_nop 0
	v_pk_mul_f32 v[120:121], v[110:111], v[128:129]
	v_pk_mul_f32 v[110:111], v[108:109], v[162:163]
	v_cvt_pk_f16_f32 v108, v116, v117
	v_cvt_pk_f16_f32 v109, v118, v119
	v_cvt_pk_f16_f32 v110, v110, v111
	v_cvt_pk_f16_f32 v111, v120, v121
	global_store_dwordx4 v[130:131], v[108:111], off offset:256
	s_nop 1
	v_or_b32_e32 v108, 16, v152
	v_ashrrev_i32_e32 v109, 31, v108
	v_lshlrev_b64 v[108:109], 17, v[108:109]
	v_lshl_add_u64 v[108:109], s[42:43], 0, v[108:109]
	v_pk_mul_f32 v[110:111], v[114:115], v[164:165]
	v_pk_mul_f32 v[114:115], v[106:107], v[136:137]
	v_pk_mul_f32 v[106:107], v[104:105], v[154:155]
	v_lshl_add_u64 v[108:109], v[108:109], 0, v[132:133]
	v_cvt_pk_f16_f32 v104, v112, v113
	v_cvt_pk_f16_f32 v105, v110, v111
	v_cvt_pk_f16_f32 v106, v106, v107
	v_cvt_pk_f16_f32 v107, v114, v115
	global_store_dwordx4 v[108:109], v[104:107], off
	s_nop 1
	v_pk_mul_f32 v[104:105], v[94:95], v[128:129]
	v_pk_mul_f32 v[94:95], v[92:93], v[162:163]
	v_cvt_pk_f16_f32 v92, v100, v101
	v_cvt_pk_f16_f32 v93, v102, v103
	v_cvt_pk_f16_f32 v94, v94, v95
	v_cvt_pk_f16_f32 v95, v104, v105
	global_store_dwordx4 v[108:109], v[92:95], off offset:256
	s_nop 1
	v_or_b32_e32 v92, 32, v152
	v_ashrrev_i32_e32 v93, 31, v92
	v_lshlrev_b64 v[92:93], 17, v[92:93]
	v_lshl_add_u64 v[92:93], s[42:43], 0, v[92:93]
	v_pk_mul_f32 v[94:95], v[98:99], v[164:165]
	v_pk_mul_f32 v[98:99], v[90:91], v[136:137]
	v_pk_mul_f32 v[90:91], v[88:89], v[154:155]
	v_lshl_add_u64 v[92:93], v[92:93], 0, v[132:133]
	v_cvt_pk_f16_f32 v88, v96, v97
	v_cvt_pk_f16_f32 v89, v94, v95
	v_cvt_pk_f16_f32 v90, v90, v91
	v_cvt_pk_f16_f32 v91, v98, v99
	global_store_dwordx4 v[92:93], v[88:91], off
	s_nop 1
	v_pk_mul_f32 v[88:89], v[78:79], v[128:129]
	v_pk_mul_f32 v[78:79], v[76:77], v[162:163]
	v_cvt_pk_f16_f32 v76, v84, v85
	v_cvt_pk_f16_f32 v77, v86, v87
	v_cvt_pk_f16_f32 v78, v78, v79
	v_cvt_pk_f16_f32 v79, v88, v89
	global_store_dwordx4 v[92:93], v[76:79], off offset:256
	s_nop 1
	v_or_b32_e32 v76, 48, v152
	v_ashrrev_i32_e32 v77, 31, v76
	v_lshlrev_b64 v[76:77], 17, v[76:77]
	v_lshl_add_u64 v[76:77], s[42:43], 0, v[76:77]
	v_pk_mul_f32 v[78:79], v[82:83], v[164:165]
	v_pk_mul_f32 v[82:83], v[74:75], v[136:137]
	v_pk_mul_f32 v[74:75], v[72:73], v[154:155]
	v_lshl_add_u64 v[76:77], v[76:77], 0, v[132:133]
	v_cvt_pk_f16_f32 v72, v80, v81
	v_cvt_pk_f16_f32 v73, v78, v79
	v_cvt_pk_f16_f32 v74, v74, v75
	v_cvt_pk_f16_f32 v75, v82, v83
	global_store_dwordx4 v[76:77], v[72:75], off
	s_nop 1
	v_pk_mul_f32 v[72:73], v[66:67], v[128:129]
	v_pk_mul_f32 v[66:67], v[64:65], v[162:163]
	v_cvt_pk_f16_f32 v64, v68, v69
	v_cvt_pk_f16_f32 v65, v70, v71
	v_cvt_pk_f16_f32 v66, v66, v67
	v_cvt_pk_f16_f32 v67, v72, v73
	global_store_dwordx4 v[76:77], v[64:67], off offset:256
	s_nop 1
	v_lshl_add_u64 v[64:65], v[130:131], 0, s[0:1]
	s_mov_b32 s0, 0x1000000
	v_pk_mul_f32 v[66:67], v[58:59], v[136:137]
	v_pk_mul_f32 v[58:59], v[56:57], v[154:155]
	v_cvt_pk_f16_f32 v56, v60, v61
	v_add_co_u32_e32 v60, vcc, s0, v130
	v_cvt_pk_f16_f32 v57, v62, v63
	v_cvt_pk_f16_f32 v58, v58, v59
	v_cvt_pk_f16_f32 v59, v66, v67
	v_addc_co_u32_e32 v61, vcc, 0, v131, vcc
	global_store_dwordx4 v[60:61], v[56:59], off
	s_mov_b64 s[0:1], 0x1200000
	s_nop 0
	v_pk_mul_f32 v[56:57], v[42:43], v[128:129]
	v_pk_mul_f32 v[42:43], v[40:41], v[162:163]
	v_cvt_pk_f16_f32 v40, v48, v49
	v_cvt_pk_f16_f32 v41, v50, v51
	v_cvt_pk_f16_f32 v42, v42, v43
	v_cvt_pk_f16_f32 v43, v56, v57
	global_store_dwordx4 v[64:65], v[40:43], off offset:256
	v_lshl_add_u64 v[48:49], v[130:131], 0, s[0:1]
	s_mov_b32 s0, 0x1200000
	v_pk_mul_f32 v[42:43], v[54:55], v[164:165]
	v_pk_mul_f32 v[40:41], v[52:53], v[150:151]
	s_nop 0
	v_cvt_pk_f16_f32 v40, v40, v41
	v_cvt_pk_f16_f32 v41, v42, v43
	v_cvt_pk_f16_f32 v42, v44, v45
	v_add_co_u32_e32 v44, vcc, s0, v130
	v_cvt_pk_f16_f32 v43, v46, v47
	s_nop 0
	v_addc_co_u32_e32 v45, vcc, 0, v131, vcc
	global_store_dwordx4 v[44:45], v[40:43], off
	s_mov_b64 s[0:1], 0x1400000
	s_nop 0
	v_pk_mul_f32 v[40:41], v[26:27], v[128:129]
	v_pk_mul_f32 v[26:27], v[24:25], v[162:163]
	v_cvt_pk_f16_f32 v24, v32, v33
	v_cvt_pk_f16_f32 v25, v34, v35
	v_cvt_pk_f16_f32 v26, v26, v27
	v_cvt_pk_f16_f32 v27, v40, v41
	global_store_dwordx4 v[48:49], v[24:27], off offset:256
	v_lshl_add_u64 v[32:33], v[130:131], 0, s[0:1]
	s_mov_b32 s0, 0x1400000
	v_pk_mul_f32 v[26:27], v[38:39], v[164:165]
	v_pk_mul_f32 v[24:25], v[36:37], v[150:151]
	s_nop 0
	v_cvt_pk_f16_f32 v24, v24, v25
	v_cvt_pk_f16_f32 v25, v26, v27
	v_cvt_pk_f16_f32 v26, v28, v29
	v_add_co_u32_e32 v28, vcc, s0, v130
	v_cvt_pk_f16_f32 v27, v30, v31
	s_nop 0
	v_addc_co_u32_e32 v29, vcc, 0, v131, vcc
	global_store_dwordx4 v[28:29], v[24:27], off
	s_mov_b64 s[0:1], 0x1600000
	s_nop 0
	v_pk_mul_f32 v[24:25], v[10:11], v[128:129]
	v_pk_mul_f32 v[10:11], v[8:9], v[162:163]
	v_cvt_pk_f16_f32 v8, v16, v17
	v_cvt_pk_f16_f32 v9, v18, v19
	v_cvt_pk_f16_f32 v10, v10, v11
	v_cvt_pk_f16_f32 v11, v24, v25
	global_store_dwordx4 v[32:33], v[8:11], off offset:256
	v_lshl_add_u64 v[16:17], v[130:131], 0, s[0:1]
	s_mov_b32 s0, 0x1600000
	v_pk_mul_f32 v[10:11], v[22:23], v[164:165]
	v_pk_mul_f32 v[8:9], v[20:21], v[150:151]
	s_nop 0
	v_cvt_pk_f16_f32 v8, v8, v9
	v_cvt_pk_f16_f32 v9, v10, v11
	v_cvt_pk_f16_f32 v10, v12, v13
	v_add_co_u32_e32 v12, vcc, s0, v130
	v_cvt_pk_f16_f32 v11, v14, v15
	s_nop 0
	v_addc_co_u32_e32 v13, vcc, 0, v131, vcc
	global_store_dwordx4 v[12:13], v[8:11], off
	s_mov_b64 s[0:1], -1
	s_andn2_b64 vcc, exec, s[2:3]
	v_pk_mul_f32 v[8:9], v[2:3], v[128:129]
	v_pk_mul_f32 v[2:3], v[0:1], v[162:163]
	v_cvt_pk_f16_f32 v0, v4, v5
	v_cvt_pk_f16_f32 v1, v6, v7
	v_cvt_pk_f16_f32 v2, v2, v3
	v_cvt_pk_f16_f32 v3, v8, v9
	global_store_dwordx4 v[16:17], v[0:3], off offset:256
	s_cbranch_vccnz .LBB0_749
	s_andn2_b64 vcc, exec, s[4:5]
	s_cbranch_vccnz .LBB0_748
	s_barrier
	s_branch .LBB0_748

.LBB0_785:
	s_lshl_b32 s23, s21, 8
	s_lshl_b32 s10, s20, 8
	v_or_b32_e32 v194, s10, v212
	v_add_u32_e32 v198, s23, v210
	v_ashrrev_i32_e32 v195, 31, v194
	v_ashrrev_i32_e32 v199, 31, v198
	v_lshl_add_u64 v[192:193], v[194:195], 1, s[44:45]
	v_lshlrev_b64 v[112:113], 11, v[198:199]
	v_lshl_add_u64 v[112:113], v[192:193], 0, v[112:113]
	global_load_dwordx4 v[172:175], v[112:113], off
	global_load_dwordx4 v[168:171], v[112:113], off offset:256
	v_or_b32_e32 v112, 16, v198
	v_ashrrev_i32_e32 v113, 31, v112
	v_lshlrev_b64 v[112:113], 11, v[112:113]
	v_lshl_add_u64 v[112:113], v[192:193], 0, v[112:113]
	global_load_dwordx4 v[164:167], v[112:113], off
	global_load_dwordx4 v[160:163], v[112:113], off offset:256
	v_or_b32_e32 v112, 32, v198
	v_ashrrev_i32_e32 v113, 31, v112
	v_lshlrev_b64 v[112:113], 11, v[112:113]
	v_lshl_add_u64 v[112:113], v[192:193], 0, v[112:113]
	global_load_dwordx4 v[156:159], v[112:113], off
	global_load_dwordx4 v[152:155], v[112:113], off offset:256
	v_or_b32_e32 v112, 48, v198
	v_ashrrev_i32_e32 v113, 31, v112
	v_lshlrev_b64 v[112:113], 11, v[112:113]
	v_lshl_add_u64 v[112:113], v[192:193], 0, v[112:113]
	global_load_dwordx4 v[148:151], v[112:113], off
	global_load_dwordx4 v[144:147], v[112:113], off offset:256
	v_and_b32_e32 v113, 64, v204
	v_xor_b32_e32 v112, 16, v204
	v_add_u32_e32 v113, 64, v113
	v_cmp_lt_i32_e32 vcc, v112, v113
	v_mul_f32_e32 v114, v143, v143
	v_fmac_f32_e32 v114, v142, v142
	v_cndmask_b32_e32 v112, v204, v112, vcc
	v_lshlrev_b32_e32 v236, 2, v112
	v_mul_f32_e32 v112, v141, v141
	v_fmac_f32_e32 v112, v140, v140
	v_add_f32_e32 v112, v112, v114
	v_mul_f32_e32 v114, v137, v137
	v_mul_f32_e32 v115, v139, v139
	v_fmac_f32_e32 v114, v136, v136
	v_fmac_f32_e32 v115, v138, v138
	v_add_f32_e32 v114, v114, v115
	v_add_f32_e32 v112, v112, v114
	v_mul_f32_e32 v114, v129, v129
	v_mul_f32_e32 v115, v131, v131
	v_fmac_f32_e32 v114, v128, v128
	v_fmac_f32_e32 v115, v130, v130
	v_add_f32_e32 v114, v114, v115
	v_add_f32_e32 v112, v112, v114
	v_mul_f32_e32 v114, v117, v117
	v_mul_f32_e32 v115, v119, v119
	v_fmac_f32_e32 v114, v116, v116
	v_fmac_f32_e32 v115, v118, v118
	v_add_f32_e32 v114, v114, v115
	v_add_f32_e32 v112, v112, v114
	ds_bpermute_b32 v114, v236, v112
	v_xor_b32_e32 v115, 32, v204
	v_cmp_lt_i32_e32 vcc, v115, v113
	s_waitcnt lgkmcnt(0)
	v_add_f32_e32 v112, v112, v114
	v_cndmask_b32_e32 v113, v204, v115, vcc
	v_lshlrev_b32_e32 v237, 2, v113
	ds_bpermute_b32 v113, v237, v112
	s_and_saveexec_b64 s[0:1], s[2:3]
	s_cbranch_execz .LBB0_787
	s_waitcnt lgkmcnt(0)
	v_add_f32_e32 v112, v112, v113
	v_add_u32_e32 v113, s85, v213
	ds_write_b32 v113, v112

.LBB0_801:
	s_or_b64 exec, exec, s[0:1]
	v_add_u32_e32 v114, s23, v214
	s_waitcnt lgkmcnt(0)
	s_barrier
	v_ashrrev_i32_e32 v115, 31, v114
	s_waitcnt lgkmcnt(0)
	v_lshlrev_b64 v[112:113], 5, v[114:115]
	v_lshl_add_u64 v[112:113], s[76:77], 0, v[112:113]
	s_and_saveexec_b64 s[0:1], s[4:5]
	s_cbranch_execz .LBB0_803
	v_add_u32_e32 v120, 0, v215
	v_add_u32_e32 v120, 0x20400, v120
	ds_read_b128 v[120:123], v120
	s_ashr_i32 s21, s20, 31
	s_waitcnt lgkmcnt(0)
	v_mov_b32_e32 v124, v121
	v_mov_b32_e32 v125, v122
	v_mov_b32_e32 v121, v123
	v_pk_add_f32 v[120:121], v[124:125], v[120:121]
	v_lshl_add_u64 v[122:123], s[20:21], 3, v[112:113]
	v_pk_add_f32 v[120:121], v[120:121], v[120:121] op_sel:[0,1] op_sel_hi:[1,0]
	s_nop 0
	v_mov_b32_e32 v121, s84
	s_waitcnt vmcnt(0)
	global_store_dwordx2 v[122:123], v[120:121], off sc1

.LBB0_805:
	s_waitcnt vmcnt(0)
	global_load_dwordx2 v[114:115], v[112:113], off sc1
	global_load_dwordx2 v[120:121], v[112:113], off offset:8 sc1
	global_load_dwordx2 v[124:125], v[112:113], off offset:16 sc1
	global_load_dwordx2 v[122:123], v[112:113], off offset:24 sc1
	s_waitcnt vmcnt(0) lgkmcnt(0)
	v_cmp_eq_u32_e32 vcc, s84, v115
	v_cmp_eq_u32_e64 s[0:1], s84, v121
	s_and_b64 s[0:1], vcc, s[0:1]
	v_cmp_eq_u32_e32 vcc, s84, v125
	s_and_b64 s[0:1], s[0:1], vcc
	v_cmp_eq_u32_e32 vcc, s84, v123
	s_and_b64 s[0:1], s[0:1], vcc
	v_cndmask_b32_e64 v115, 0, 1, s[0:1]
	v_cmp_ne_u32_e32 vcc, 0, v115
	s_cmp_eq_u64 vcc, exec
	s_cselect_b64 s[0:1], -1, 0
	v_subrev_co_u32_e32 v126, vcc, 1, v126
	s_or_b64 s[0:1], s[0:1], vcc
	s_and_b64 vcc, exec, s[0:1]
	s_cbranch_vccz .LBB0_804

.LBB0_809:
	s_or_b64 exec, exec, s[0:1]
	s_waitcnt vmcnt(0) lgkmcnt(0)
	s_barrier
	s_cmp_eq_u32 s20, s96
	s_cbranch_scc1 .LBB0_813
	s_barrier
	s_and_saveexec_b64 s[0:1], s[6:7]
	s_cbranch_execz .LBB0_812
	v_add_u32_e32 v112, s10, v216
	v_ashrrev_i32_e32 v113, 31, v112
	v_lshl_add_u64 v[112:113], v[112:113], 2, s[68:69]
	global_load_dword v112, v[112:113], off
	v_readlane_b32 s10, v255, 37
	s_nop 1
	v_lshl_add_u32 v113, v216, 2, s10
	s_waitcnt vmcnt(0) lgkmcnt(0)
	ds_write_b32 v113, v112

.LBB0_815:
	v_lshl_add_u64 v[172:173], v[198:199], 1, v[192:193]
	v_cvt_pk_f16_f32 v168, v140, v141
	v_cvt_pk_f16_f32 v169, v142, v143
	v_cvt_pk_f16_f32 v170, v136, v137
	v_cvt_pk_f16_f32 v171, v138, v139
	global_store_dwordx4 v[172:173], v[168:171], off
	s_nop 1
	v_cvt_pk_f16_f32 v168, v128, v129
	v_cvt_pk_f16_f32 v169, v130, v131
	v_cvt_pk_f16_f32 v170, v116, v117
	v_cvt_pk_f16_f32 v171, v118, v119
	global_store_dwordx4 v[172:173], v[168:171], off offset:256

.LBB0_820:
	v_lshl_add_u64 v[128:129], v[116:117], 1, v[192:193]
	v_cvt_pk_f16_f32 v116, v108, v109
	v_cvt_pk_f16_f32 v117, v110, v111
	v_cvt_pk_f16_f32 v118, v104, v105
	v_cvt_pk_f16_f32 v119, v106, v107
	global_store_dwordx4 v[128:129], v[116:119], off
	s_nop 1
	v_cvt_pk_f16_f32 v116, v100, v101
	v_cvt_pk_f16_f32 v117, v102, v103
	v_cvt_pk_f16_f32 v118, v96, v97
	v_cvt_pk_f16_f32 v119, v98, v99
	global_store_dwordx4 v[128:129], v[116:119], off offset:256

.LBB0_833:
	s_or_b64 exec, exec, s[0:1]
	v_add_u32_e32 v88, s23, v217
	v_ashrrev_i32_e32 v89, 31, v88
	s_waitcnt lgkmcnt(0)
	v_lshlrev_b64 v[64:65], 11, v[88:89]
	v_lshl_add_u64 v[64:65], v[192:193], 0, v[64:65]
	global_load_dwordx4 v[90:93], v[64:65], off
	global_load_dwordx4 v[94:97], v[64:65], off offset:256
	v_or_b32_e32 v66, 16, v88
	v_or_b32_e32 v68, 32, v88
	v_or_b32_e32 v64, 48, v88
	v_ashrrev_i32_e32 v67, 31, v66
	v_ashrrev_i32_e32 v69, 31, v68
	v_ashrrev_i32_e32 v65, 31, v64
	v_lshlrev_b64 v[66:67], 11, v[66:67]
	v_lshlrev_b64 v[68:69], 11, v[68:69]
	v_lshlrev_b64 v[64:65], 11, v[64:65]
	v_lshl_add_u64 v[66:67], v[192:193], 0, v[66:67]
	v_lshl_add_u64 v[68:69], v[192:193], 0, v[68:69]
	v_lshl_add_u64 v[64:65], v[192:193], 0, v[64:65]
	global_load_dwordx4 v[84:87], v[66:67], off
	global_load_dwordx4 v[80:83], v[66:67], off offset:256
	global_load_dwordx4 v[76:79], v[68:69], off
	global_load_dwordx4 v[72:75], v[68:69], off offset:256
	s_nop 0
	global_load_dwordx4 v[68:71], v[64:65], off
	s_nop 0
	global_load_dwordx4 v[64:67], v[64:65], off offset:256
	v_lshl_add_u32 v98, v217, 2, s63
	ds_read_b32 v98, v98
	s_and_b64 vcc, exec, s[10:11]
	v_lshlrev_b64 v[88:89], 10, v[88:89]
	s_waitcnt lgkmcnt(0)
	v_pk_mul_f32 v[62:63], v[62:63], v[98:99] op_sel_hi:[1,0]
	v_pk_mul_f32 v[60:61], v[60:61], v[98:99] op_sel_hi:[1,0]
	v_pk_mul_f32 v[58:59], v[58:59], v[98:99] op_sel_hi:[1,0]
	v_pk_mul_f32 v[56:57], v[56:57], v[98:99] op_sel_hi:[1,0]
	v_pk_mul_f32 v[54:55], v[54:55], v[98:99] op_sel_hi:[1,0]
	v_pk_mul_f32 v[52:53], v[52:53], v[98:99] op_sel_hi:[1,0]
	v_pk_mul_f32 v[50:51], v[50:51], v[98:99] op_sel_hi:[1,0]
	v_pk_mul_f32 v[48:49], v[48:49], v[98:99] op_sel_hi:[1,0]
	s_waitcnt vmcnt(0)
	v_cvt_f32_f16_e32 v98, v90
	v_cvt_f32_f16_sdwa v99, v90 dst_sel:DWORD dst_unused:UNUSED_PAD src0_sel:WORD_1
	v_cvt_f32_f16_e32 v90, v91
	v_cvt_f32_f16_sdwa v91, v91 dst_sel:DWORD dst_unused:UNUSED_PAD src0_sel:WORD_1
	v_cvt_f32_f16_e32 v100, v92
	v_cvt_f32_f16_sdwa v101, v92 dst_sel:DWORD dst_unused:UNUSED_PAD src0_sel:WORD_1
	v_cvt_f32_f16_e32 v92, v93
	v_cvt_f32_f16_sdwa v93, v93 dst_sel:DWORD dst_unused:UNUSED_PAD src0_sel:WORD_1
	v_cvt_f32_f16_e32 v102, v94
	v_cvt_f32_f16_sdwa v103, v94 dst_sel:DWORD dst_unused:UNUSED_PAD src0_sel:WORD_1
	v_cvt_f32_f16_e32 v94, v95
	v_cvt_f32_f16_sdwa v95, v95 dst_sel:DWORD dst_unused:UNUSED_PAD src0_sel:WORD_1
	v_cvt_f32_f16_e32 v104, v96
	v_cvt_f32_f16_sdwa v105, v96 dst_sel:DWORD dst_unused:UNUSED_PAD src0_sel:WORD_1
	v_cvt_f32_f16_e32 v96, v97
	v_cvt_f32_f16_sdwa v97, v97 dst_sel:DWORD dst_unused:UNUSED_PAD src0_sel:WORD_1
	v_pk_fma_f32 v[62:63], v[134:135], v[62:63], v[90:91]
	v_pk_fma_f32 v[60:61], v[132:133], v[60:61], v[98:99]
	v_pk_fma_f32 v[58:59], v[126:127], v[58:59], v[92:93]
	v_pk_fma_f32 v[56:57], v[124:125], v[56:57], v[100:101]
	v_pk_fma_f32 v[54:55], v[122:123], v[54:55], v[94:95]
	v_pk_fma_f32 v[52:53], v[120:121], v[52:53], v[102:103]
	v_pk_fma_f32 v[50:51], v[114:115], v[50:51], v[96:97]
	v_pk_fma_f32 v[48:49], v[112:113], v[48:49], v[104:105]
	s_cbranch_vccnz .LBB0_862
	v_lshl_add_u64 v[90:91], v[88:89], 0, v[194:195]
	v_lshl_add_u64 v[90:91], v[90:91], 2, s[38:39]
	global_store_dwordx4 v[90:91], v[60:63], off
	global_store_dwordx4 v[90:91], v[56:59], off offset:16
	global_store_dwordx4 v[90:91], v[52:55], off offset:512
	global_store_dwordx4 v[90:91], v[48:51], off offset:528
	s_cbranch_execnz .LBB0_836

.LBB0_853:
	s_or_b64 exec, exec, s[0:1]
	s_waitcnt lgkmcnt(0)
	s_barrier
	s_and_saveexec_b64 s[0:1], s[4:5]
	s_cbranch_execz .LBB0_855
	v_add_u32_e32 v0, 0, v215
	v_add_u32_e32 v0, 0x20400, v0
	s_waitcnt lgkmcnt(0)
	ds_read_b128 v[0:3], v0
	s_ashr_i32 s21, s20, 31
	v_lshl_add_u64 v[4:5], v[196:197], 2, s[46:47]
	s_waitcnt lgkmcnt(0)
	v_mov_b32_e32 v6, v1
	v_mov_b32_e32 v7, v2
	v_mov_b32_e32 v1, v3
	v_pk_add_f32 v[0:1], v[6:7], v[0:1]
	s_nop 0
	v_add_f32_e32 v2, v0, v1
	v_lshl_add_u64 v[0:1], s[20:21], 2, v[4:5]
	global_store_dword v[0:1], v2, off

.LBB0_885:
	s_lshl_b32 s16, s36, 8
	v_lshl_add_u32 v96, s37, 8, v190
	s_ashr_i32 s17, s16, 31
	s_lshl_b64 s[16:17], s[16:17], 1
	v_ashrrev_i32_e32 v97, 31, v96
	v_lshl_add_u64 v[174:175], v[168:169], 0, s[16:17]
	v_lshlrev_b64 v[182:183], 11, v[96:97]
	v_lshl_add_u64 v[98:99], v[174:175], 0, v[182:183]
	global_load_dwordx4 v[156:159], v[98:99], off
	global_load_dwordx4 v[152:155], v[98:99], off offset:256
	v_or_b32_e32 v98, 16, v96
	v_ashrrev_i32_e32 v99, 31, v98
	v_lshlrev_b64 v[188:189], 11, v[98:99]
	v_lshl_add_u64 v[98:99], v[174:175], 0, v[188:189]
	global_load_dwordx4 v[140:143], v[98:99], off
	global_load_dwordx4 v[132:135], v[98:99], off offset:256
	v_mul_f32_e32 v150, 0xbfb8aa3b, v150
	v_mul_f32_e32 v151, 0xbfb8aa3b, v151
	v_exp_f32_e32 v150, v150
	v_exp_f32_e32 v151, v151
	v_mul_f32_e32 v144, 0xbfb8aa3b, v144
	v_mul_f32_e32 v145, 0xbfb8aa3b, v145
	v_add_f32_e32 v150, 1.0, v150
	v_add_f32_e32 v151, 1.0, v151
	v_exp_f32_e32 v144, v144
	v_exp_f32_e32 v145, v145
	v_rcp_f32_e32 v150, v150
	v_rcp_f32_e32 v151, v151
	v_add_f32_e32 v144, 1.0, v144
	v_add_f32_e32 v145, 1.0, v145
	v_rcp_f32_e32 v144, v144
	v_rcp_f32_e32 v145, v145
	v_mul_f32_e32 v148, 0xbfb8aa3b, v148
	v_mul_f32_e32 v149, 0xbfb8aa3b, v149
	v_exp_f32_e32 v148, v148
	v_exp_f32_e32 v149, v149
	v_or_b32_e32 v98, 32, v96
	v_ashrrev_i32_e32 v99, 31, v98
	v_lshlrev_b64 v[186:187], 11, v[98:99]
	v_lshl_add_u64 v[98:99], v[174:175], 0, v[186:187]
	v_add_f32_e32 v148, 1.0, v148
	v_add_f32_e32 v149, 1.0, v149
	global_load_dwordx4 v[128:131], v[98:99], off
	global_load_dwordx4 v[120:123], v[98:99], off offset:256
	v_rcp_f32_e32 v148, v148
	v_rcp_f32_e32 v149, v149
	v_mul_f32_e32 v136, 0xbfb8aa3b, v136
	v_mul_f32_e32 v137, 0xbfb8aa3b, v137
	v_exp_f32_e32 v136, v136
	v_exp_f32_e32 v137, v137
	v_or_b32_e32 v96, 48, v96
	v_ashrrev_i32_e32 v97, 31, v96
	v_lshlrev_b64 v[184:185], 11, v[96:97]
	v_mul_f32_e32 v138, 0xbfb8aa3b, v138
	v_mul_f32_e32 v139, 0xbfb8aa3b, v139
	v_lshl_add_u64 v[96:97], v[174:175], 0, v[184:185]
	v_add_f32_e32 v136, 1.0, v136
	v_add_f32_e32 v137, 1.0, v137
	v_exp_f32_e32 v138, v138
	v_exp_f32_e32 v139, v139
	global_load_dwordx4 v[108:111], v[96:97], off
	s_nop 0
	global_load_dwordx4 v[96:99], v[96:97], off offset:256
	v_rcp_f32_e32 v136, v136
	v_rcp_f32_e32 v137, v137
	v_mul_f32_e32 v124, 0xbfb8aa3b, v124
	v_mul_f32_e32 v125, 0xbfb8aa3b, v125
	v_add_f32_e32 v138, 1.0, v138
	v_add_f32_e32 v139, 1.0, v139
	v_exp_f32_e32 v124, v124
	v_exp_f32_e32 v125, v125
	v_rcp_f32_e32 v138, v138
	v_rcp_f32_e32 v139, v139
	v_add_f32_e32 v124, 1.0, v124
	v_add_f32_e32 v125, 1.0, v125
	v_rcp_f32_e32 v124, v124
	v_rcp_f32_e32 v125, v125
	v_mul_f32_e32 v116, 0xbfb8aa3b, v116
	v_mul_f32_e32 v117, 0xbfb8aa3b, v117
	v_exp_f32_e32 v116, v116
	v_exp_f32_e32 v117, v117
	v_mul_f32_e32 v118, 0xbfb8aa3b, v118
	v_mul_f32_e32 v119, 0xbfb8aa3b, v119
	v_add_f32_e32 v116, 1.0, v116
	v_add_f32_e32 v117, 1.0, v117
	v_exp_f32_e32 v118, v118
	v_exp_f32_e32 v119, v119
	v_rcp_f32_e32 v116, v116
	v_rcp_f32_e32 v117, v117
	v_mul_f32_e32 v112, 0xbfb8aa3b, v112
	v_mul_f32_e32 v113, 0xbfb8aa3b, v113
	v_add_f32_e32 v118, 1.0, v118
	s_waitcnt vmcnt(0) lgkmcnt(0)
	v_cvt_f32_f16_e32 v194, v156
	v_cvt_f32_f16_sdwa v195, v156 dst_sel:DWORD dst_unused:UNUSED_PAD src0_sel:WORD_1
	v_cvt_f32_f16_e32 v156, v157
	v_cvt_f32_f16_sdwa v157, v157 dst_sel:DWORD dst_unused:UNUSED_PAD src0_sel:WORD_1
	v_add_f32_e32 v119, 1.0, v119
	v_pk_mul_f32 v[148:149], v[148:149], v[194:195]
	v_exp_f32_e32 v112, v112
	v_pk_mul_f32 v[150:151], v[150:151], v[156:157]
	v_cvt_f32_f16_e32 v156, v158
	v_cvt_f32_f16_sdwa v157, v158 dst_sel:DWORD dst_unused:UNUSED_PAD src0_sel:WORD_1
	v_exp_f32_e32 v113, v113
	v_rcp_f32_e32 v118, v118
	v_rcp_f32_e32 v119, v119
	v_pk_mul_f32 v[156:157], v[144:145], v[156:157]
	v_mul_f32_e32 v144, 0xbfb8aa3b, v146
	v_mul_f32_e32 v145, 0xbfb8aa3b, v147
	v_exp_f32_e32 v144, v144
	v_exp_f32_e32 v145, v145
	v_cvt_f32_f16_e32 v146, v159
	v_cvt_f32_f16_sdwa v147, v159 dst_sel:DWORD dst_unused:UNUSED_PAD src0_sel:WORD_1
	v_add_f32_e32 v144, 1.0, v144
	v_add_f32_e32 v145, 1.0, v145
	v_rcp_f32_e32 v144, v144
	v_rcp_f32_e32 v145, v145
	v_add_f32_e32 v112, 1.0, v112
	v_add_f32_e32 v113, 1.0, v113
	v_rcp_f32_e32 v112, v112
	v_pk_mul_f32 v[158:159], v[144:145], v[146:147]
	v_lshl_add_u64 v[144:145], s[78:79], 0, v[182:183]
	v_lshl_add_u64 v[144:145], v[144:145], 0, s[16:17]
	v_lshl_add_u64 v[144:145], v[144:145], 0, v[176:177]
	v_cvt_pk_f16_f32 v146, v148, v149
	v_cvt_pk_f16_f32 v147, v150, v151
	v_cvt_pk_f16_f32 v148, v156, v157
	v_cvt_pk_f16_f32 v149, v158, v159
	global_store_dwordx4 v[144:145], v[146:149], off
	v_rcp_f32_e32 v113, v113
	v_mul_f32_e32 v104, 0xbfb8aa3b, v104
	v_cvt_f32_f16_e32 v146, v152
	v_cvt_f32_f16_sdwa v147, v152 dst_sel:DWORD dst_unused:UNUSED_PAD src0_sel:WORD_1
	v_mul_f32_e32 v105, 0xbfb8aa3b, v105
	v_exp_f32_e32 v104, v104
	v_exp_f32_e32 v105, v105
	v_pk_mul_f32 v[136:137], v[136:137], v[146:147]
	v_cvt_f32_f16_e32 v146, v153
	v_cvt_f32_f16_sdwa v147, v153 dst_sel:DWORD dst_unused:UNUSED_PAD src0_sel:WORD_1
	v_mul_f32_e32 v106, 0xbfb8aa3b, v106
	v_mul_f32_e32 v107, 0xbfb8aa3b, v107
	v_add_f32_e32 v104, 1.0, v104
	v_pk_mul_f32 v[138:139], v[138:139], v[146:147]
	v_cvt_f32_f16_e32 v146, v154
	v_cvt_f32_f16_sdwa v147, v154 dst_sel:DWORD dst_unused:UNUSED_PAD src0_sel:WORD_1
	v_add_f32_e32 v105, 1.0, v105
	v_exp_f32_e32 v106, v106
	v_exp_f32_e32 v107, v107
	v_pk_mul_f32 v[146:147], v[124:125], v[146:147]
	v_mul_f32_e32 v124, 0xbfb8aa3b, v126
	v_mul_f32_e32 v125, 0xbfb8aa3b, v127
	v_exp_f32_e32 v124, v124
	v_exp_f32_e32 v125, v125
	v_cvt_f32_f16_e32 v126, v155
	v_cvt_f32_f16_sdwa v127, v155 dst_sel:DWORD dst_unused:UNUSED_PAD src0_sel:WORD_1
	v_add_f32_e32 v124, 1.0, v124
	v_add_f32_e32 v125, 1.0, v125
	v_rcp_f32_e32 v124, v124
	v_rcp_f32_e32 v125, v125
	v_rcp_f32_e32 v104, v104
	v_rcp_f32_e32 v105, v105
	v_mul_f32_e32 v100, 0xbfb8aa3b, v100
	v_pk_mul_f32 v[148:149], v[124:125], v[126:127]
	v_cvt_pk_f16_f32 v124, v136, v137
	v_cvt_pk_f16_f32 v125, v138, v139
	v_cvt_pk_f16_f32 v126, v146, v147
	v_cvt_pk_f16_f32 v127, v148, v149
	global_store_dwordx4 v[144:145], v[124:127], off offset:256
	v_mul_f32_e32 v101, 0xbfb8aa3b, v101
	v_add_f32_e32 v106, 1.0, v106
	v_cvt_f32_f16_e32 v124, v140
	v_cvt_f32_f16_sdwa v125, v140 dst_sel:DWORD dst_unused:UNUSED_PAD src0_sel:WORD_1
	v_add_f32_e32 v107, 1.0, v107
	v_exp_f32_e32 v100, v100
	v_exp_f32_e32 v101, v101
	v_pk_mul_f32 v[116:117], v[116:117], v[124:125]
	v_cvt_f32_f16_e32 v124, v141
	v_cvt_f32_f16_sdwa v125, v141 dst_sel:DWORD dst_unused:UNUSED_PAD src0_sel:WORD_1
	v_rcp_f32_e32 v106, v106
	v_rcp_f32_e32 v107, v107
	v_add_f32_e32 v100, 1.0, v100
	v_pk_mul_f32 v[118:119], v[118:119], v[124:125]
	v_cvt_f32_f16_e32 v124, v142
	v_cvt_f32_f16_sdwa v125, v142 dst_sel:DWORD dst_unused:UNUSED_PAD src0_sel:WORD_1
	v_add_f32_e32 v101, 1.0, v101
	v_rcp_f32_e32 v100, v100
	v_rcp_f32_e32 v101, v101
	v_pk_mul_f32 v[124:125], v[112:113], v[124:125]
	v_mul_f32_e32 v112, 0xbfb8aa3b, v114
	v_mul_f32_e32 v113, 0xbfb8aa3b, v115
	v_exp_f32_e32 v112, v112
	v_exp_f32_e32 v113, v113
	v_cvt_f32_f16_e32 v114, v143
	v_cvt_f32_f16_sdwa v115, v143 dst_sel:DWORD dst_unused:UNUSED_PAD src0_sel:WORD_1
	v_add_f32_e32 v112, 1.0, v112
	v_add_f32_e32 v113, 1.0, v113
	v_rcp_f32_e32 v112, v112
	v_rcp_f32_e32 v113, v113
	v_mul_f32_e32 v92, 0xbfb8aa3b, v92
	v_mul_f32_e32 v93, 0xbfb8aa3b, v93
	v_exp_f32_e32 v92, v92
	v_pk_mul_f32 v[126:127], v[112:113], v[114:115]
	v_lshl_add_u64 v[112:113], s[78:79], 0, v[188:189]
	v_lshl_add_u64 v[112:113], v[112:113], 0, s[16:17]
	v_lshl_add_u64 v[136:137], v[112:113], 0, v[176:177]
	v_cvt_pk_f16_f32 v112, v116, v117
	v_cvt_pk_f16_f32 v113, v118, v119
	v_cvt_pk_f16_f32 v114, v124, v125
	v_cvt_pk_f16_f32 v115, v126, v127
	global_store_dwordx4 v[136:137], v[112:115], off
	v_exp_f32_e32 v93, v93
	v_mul_f32_e32 v94, 0xbfb8aa3b, v94
	v_cvt_f32_f16_e32 v112, v132
	v_cvt_f32_f16_sdwa v113, v132 dst_sel:DWORD dst_unused:UNUSED_PAD src0_sel:WORD_1
	v_mul_f32_e32 v95, 0xbfb8aa3b, v95
	v_add_f32_e32 v92, 1.0, v92
	v_add_f32_e32 v93, 1.0, v93
	v_pk_mul_f32 v[104:105], v[104:105], v[112:113]
	v_cvt_f32_f16_e32 v112, v133
	v_cvt_f32_f16_sdwa v113, v133 dst_sel:DWORD dst_unused:UNUSED_PAD src0_sel:WORD_1
	v_exp_f32_e32 v94, v94
	v_exp_f32_e32 v95, v95
	v_rcp_f32_e32 v92, v92
	v_pk_mul_f32 v[106:107], v[106:107], v[112:113]
	v_cvt_f32_f16_e32 v112, v134
	v_cvt_f32_f16_sdwa v113, v134 dst_sel:DWORD dst_unused:UNUSED_PAD src0_sel:WORD_1
	v_rcp_f32_e32 v93, v93
	v_mul_f32_e32 v88, 0xbfb8aa3b, v88
	v_mul_f32_e32 v89, 0xbfb8aa3b, v89
	v_pk_mul_f32 v[112:113], v[100:101], v[112:113]
	v_mul_f32_e32 v100, 0xbfb8aa3b, v102
	v_mul_f32_e32 v101, 0xbfb8aa3b, v103
	v_exp_f32_e32 v100, v100
	v_exp_f32_e32 v101, v101
	v_cvt_f32_f16_e32 v102, v135
	v_cvt_f32_f16_sdwa v103, v135 dst_sel:DWORD dst_unused:UNUSED_PAD src0_sel:WORD_1
	v_add_f32_e32 v100, 1.0, v100
	v_add_f32_e32 v101, 1.0, v101
	v_rcp_f32_e32 v100, v100
	v_rcp_f32_e32 v101, v101
	v_add_f32_e32 v94, 1.0, v94
	v_add_f32_e32 v95, 1.0, v95
	v_exp_f32_e32 v88, v88
	v_pk_mul_f32 v[114:115], v[100:101], v[102:103]
	v_cvt_pk_f16_f32 v100, v104, v105
	v_cvt_pk_f16_f32 v101, v106, v107
	v_cvt_pk_f16_f32 v102, v112, v113
	v_cvt_pk_f16_f32 v103, v114, v115
	global_store_dwordx4 v[136:137], v[100:103], off offset:256
	v_exp_f32_e32 v89, v89
	v_rcp_f32_e32 v94, v94
	v_cvt_f32_f16_e32 v100, v128
	v_cvt_f32_f16_sdwa v101, v128 dst_sel:DWORD dst_unused:UNUSED_PAD src0_sel:WORD_1
	v_rcp_f32_e32 v95, v95
	v_add_f32_e32 v88, 1.0, v88
	v_add_f32_e32 v89, 1.0, v89
	v_pk_mul_f32 v[92:93], v[92:93], v[100:101]
	v_cvt_f32_f16_e32 v100, v129
	v_cvt_f32_f16_sdwa v101, v129 dst_sel:DWORD dst_unused:UNUSED_PAD src0_sel:WORD_1
	v_rcp_f32_e32 v88, v88
	v_rcp_f32_e32 v89, v89
	v_mul_f32_e32 v84, 0xbfb8aa3b, v84
	v_pk_mul_f32 v[94:95], v[94:95], v[100:101]
	v_cvt_f32_f16_e32 v100, v130
	v_cvt_f32_f16_sdwa v101, v130 dst_sel:DWORD dst_unused:UNUSED_PAD src0_sel:WORD_1
	v_mul_f32_e32 v85, 0xbfb8aa3b, v85
	v_exp_f32_e32 v84, v84
	v_exp_f32_e32 v85, v85
	v_pk_mul_f32 v[100:101], v[88:89], v[100:101]
	v_mul_f32_e32 v88, 0xbfb8aa3b, v90
	v_mul_f32_e32 v89, 0xbfb8aa3b, v91
	v_exp_f32_e32 v88, v88
	v_exp_f32_e32 v89, v89
	v_cvt_f32_f16_e32 v90, v131
	v_cvt_f32_f16_sdwa v91, v131 dst_sel:DWORD dst_unused:UNUSED_PAD src0_sel:WORD_1
	v_add_f32_e32 v88, 1.0, v88
	v_add_f32_e32 v89, 1.0, v89
	v_rcp_f32_e32 v88, v88
	v_rcp_f32_e32 v89, v89
	v_mul_f32_e32 v86, 0xbfb8aa3b, v86
	v_mul_f32_e32 v87, 0xbfb8aa3b, v87
	v_add_f32_e32 v84, 1.0, v84
	v_pk_mul_f32 v[102:103], v[88:89], v[90:91]
	v_lshl_add_u64 v[88:89], s[78:79], 0, v[186:187]
	v_lshl_add_u64 v[88:89], v[88:89], 0, s[16:17]
	v_lshl_add_u64 v[104:105], v[88:89], 0, v[176:177]
	v_cvt_pk_f16_f32 v88, v92, v93
	v_cvt_pk_f16_f32 v89, v94, v95
	v_cvt_pk_f16_f32 v90, v100, v101
	v_cvt_pk_f16_f32 v91, v102, v103
	v_add_f32_e32 v85, 1.0, v85
	v_exp_f32_e32 v86, v86
	v_exp_f32_e32 v87, v87
	global_store_dwordx4 v[104:105], v[88:91], off
	v_rcp_f32_e32 v84, v84
	v_rcp_f32_e32 v85, v85
	v_cvt_f32_f16_e32 v88, v120
	v_cvt_f32_f16_sdwa v89, v120 dst_sel:DWORD dst_unused:UNUSED_PAD src0_sel:WORD_1
	v_mul_f32_e32 v80, 0xbfb8aa3b, v80
	v_mul_f32_e32 v81, 0xbfb8aa3b, v81
	v_add_f32_e32 v86, 1.0, v86
	v_add_f32_e32 v87, 1.0, v87
	v_exp_f32_e32 v80, v80
	v_exp_f32_e32 v81, v81
	v_pk_mul_f32 v[84:85], v[84:85], v[88:89]
	v_rcp_f32_e32 v86, v86
	v_rcp_f32_e32 v87, v87
	v_cvt_f32_f16_e32 v88, v121
	v_cvt_f32_f16_sdwa v89, v121 dst_sel:DWORD dst_unused:UNUSED_PAD src0_sel:WORD_1
	v_add_f32_e32 v80, 1.0, v80
	v_add_f32_e32 v81, 1.0, v81
	v_rcp_f32_e32 v80, v80
	v_pk_mul_f32 v[86:87], v[86:87], v[88:89]
	v_rcp_f32_e32 v81, v81
	v_cvt_f32_f16_e32 v88, v122
	v_cvt_f32_f16_sdwa v89, v122 dst_sel:DWORD dst_unused:UNUSED_PAD src0_sel:WORD_1
	v_mul_f32_e32 v76, 0xbfb8aa3b, v76
	v_mul_f32_e32 v77, 0xbfb8aa3b, v77
	v_exp_f32_e32 v76, v76
	v_pk_mul_f32 v[88:89], v[80:81], v[88:89]
	v_mul_f32_e32 v80, 0xbfb8aa3b, v82
	v_mul_f32_e32 v81, 0xbfb8aa3b, v83
	v_exp_f32_e32 v80, v80
	v_exp_f32_e32 v81, v81
	v_cvt_f32_f16_e32 v82, v123
	v_cvt_f32_f16_sdwa v83, v123 dst_sel:DWORD dst_unused:UNUSED_PAD src0_sel:WORD_1
	v_add_f32_e32 v80, 1.0, v80
	v_add_f32_e32 v81, 1.0, v81
	v_rcp_f32_e32 v80, v80
	v_rcp_f32_e32 v81, v81
	v_exp_f32_e32 v77, v77
	v_mul_f32_e32 v78, 0xbfb8aa3b, v78
	v_mul_f32_e32 v79, 0xbfb8aa3b, v79
	v_pk_mul_f32 v[90:91], v[80:81], v[82:83]
	v_cvt_pk_f16_f32 v80, v84, v85
	v_cvt_pk_f16_f32 v81, v86, v87
	v_cvt_pk_f16_f32 v82, v88, v89
	v_cvt_pk_f16_f32 v83, v90, v91
	v_add_f32_e32 v76, 1.0, v76
	v_add_f32_e32 v77, 1.0, v77
	v_exp_f32_e32 v78, v78
	v_exp_f32_e32 v79, v79
	global_store_dwordx4 v[104:105], v[80:83], off offset:256
	v_rcp_f32_e32 v76, v76
	v_rcp_f32_e32 v77, v77
	v_cvt_f32_f16_e32 v80, v108
	v_cvt_f32_f16_sdwa v81, v108 dst_sel:DWORD dst_unused:UNUSED_PAD src0_sel:WORD_1
	v_mul_f32_e32 v72, 0xbfb8aa3b, v72
	v_mul_f32_e32 v73, 0xbfb8aa3b, v73
	v_add_f32_e32 v78, 1.0, v78
	v_add_f32_e32 v79, 1.0, v79
	v_exp_f32_e32 v72, v72
	v_exp_f32_e32 v73, v73
	v_pk_mul_f32 v[76:77], v[76:77], v[80:81]
	v_rcp_f32_e32 v78, v78
	v_rcp_f32_e32 v79, v79
	v_cvt_f32_f16_e32 v80, v109
	v_cvt_f32_f16_sdwa v81, v109 dst_sel:DWORD dst_unused:UNUSED_PAD src0_sel:WORD_1
	v_add_f32_e32 v72, 1.0, v72
	v_add_f32_e32 v73, 1.0, v73
	v_rcp_f32_e32 v72, v72
	v_pk_mul_f32 v[78:79], v[78:79], v[80:81]
	v_rcp_f32_e32 v73, v73
	v_cvt_f32_f16_e32 v80, v110
	v_cvt_f32_f16_sdwa v81, v110 dst_sel:DWORD dst_unused:UNUSED_PAD src0_sel:WORD_1
	v_mul_f32_e32 v68, 0xbfb8aa3b, v68
	v_mul_f32_e32 v69, 0xbfb8aa3b, v69
	v_exp_f32_e32 v68, v68
	v_pk_mul_f32 v[80:81], v[72:73], v[80:81]
	v_mul_f32_e32 v72, 0xbfb8aa3b, v74
	v_mul_f32_e32 v73, 0xbfb8aa3b, v75
	v_exp_f32_e32 v72, v72
	v_exp_f32_e32 v73, v73
	v_cvt_f32_f16_e32 v74, v111
	v_cvt_f32_f16_sdwa v75, v111 dst_sel:DWORD dst_unused:UNUSED_PAD src0_sel:WORD_1
	v_add_f32_e32 v72, 1.0, v72
	v_add_f32_e32 v73, 1.0, v73
	v_rcp_f32_e32 v72, v72
	v_rcp_f32_e32 v73, v73
	v_exp_f32_e32 v69, v69
	v_mul_f32_e32 v70, 0xbfb8aa3b, v70
	v_mul_f32_e32 v71, 0xbfb8aa3b, v71
	v_pk_mul_f32 v[82:83], v[72:73], v[74:75]
	v_lshl_add_u64 v[72:73], s[78:79], 0, v[184:185]
	v_lshl_add_u64 v[72:73], v[72:73], 0, s[16:17]
	v_lshl_add_u64 v[84:85], v[72:73], 0, v[176:177]
	v_cvt_pk_f16_f32 v72, v76, v77
	v_cvt_pk_f16_f32 v73, v78, v79
	v_cvt_pk_f16_f32 v74, v80, v81
	v_cvt_pk_f16_f32 v75, v82, v83
	v_add_f32_e32 v68, 1.0, v68
	v_add_f32_e32 v69, 1.0, v69
	v_exp_f32_e32 v70, v70
	v_exp_f32_e32 v71, v71
	global_store_dwordx4 v[84:85], v[72:75], off
	v_rcp_f32_e32 v68, v68
	v_rcp_f32_e32 v69, v69
	v_cvt_f32_f16_e32 v72, v96
	v_cvt_f32_f16_sdwa v73, v96 dst_sel:DWORD dst_unused:UNUSED_PAD src0_sel:WORD_1
	v_mul_f32_e32 v64, 0xbfb8aa3b, v64
	v_mul_f32_e32 v65, 0xbfb8aa3b, v65
	v_add_f32_e32 v70, 1.0, v70
	v_add_f32_e32 v71, 1.0, v71
	v_exp_f32_e32 v64, v64
	v_exp_f32_e32 v65, v65
	v_pk_mul_f32 v[68:69], v[68:69], v[72:73]
	v_rcp_f32_e32 v70, v70
	v_rcp_f32_e32 v71, v71
	v_cvt_f32_f16_e32 v72, v97
	v_cvt_f32_f16_sdwa v73, v97 dst_sel:DWORD dst_unused:UNUSED_PAD src0_sel:WORD_1
	v_add_f32_e32 v64, 1.0, v64
	v_add_f32_e32 v65, 1.0, v65
	v_rcp_f32_e32 v64, v64
	v_pk_mul_f32 v[70:71], v[70:71], v[72:73]
	v_rcp_f32_e32 v65, v65
	v_cvt_f32_f16_e32 v72, v98
	v_cvt_f32_f16_sdwa v73, v98 dst_sel:DWORD dst_unused:UNUSED_PAD src0_sel:WORD_1
	s_mov_b64 s[18:19], 0x40000
	v_lshl_add_u64 v[102:103], v[182:183], 0, s[18:19]
	s_mov_b64 s[18:19], 0x48000
	v_pk_mul_f32 v[72:73], v[64:65], v[72:73]
	v_mul_f32_e32 v64, 0xbfb8aa3b, v66
	v_mul_f32_e32 v65, 0xbfb8aa3b, v67
	v_exp_f32_e32 v64, v64
	v_exp_f32_e32 v65, v65
	v_cvt_f32_f16_e32 v66, v99
	v_cvt_f32_f16_sdwa v67, v99 dst_sel:DWORD dst_unused:UNUSED_PAD src0_sel:WORD_1
	v_add_f32_e32 v64, 1.0, v64
	v_add_f32_e32 v65, 1.0, v65
	v_rcp_f32_e32 v64, v64
	v_rcp_f32_e32 v65, v65
	v_lshl_add_u64 v[96:97], v[182:183], 0, s[18:19]
	v_mul_f32_e32 v62, 0xbfb8aa3b, v62
	v_mul_f32_e32 v63, 0xbfb8aa3b, v63
	v_pk_mul_f32 v[74:75], v[64:65], v[66:67]
	v_cvt_pk_f16_f32 v64, v68, v69
	v_cvt_pk_f16_f32 v65, v70, v71
	v_cvt_pk_f16_f32 v66, v72, v73
	v_cvt_pk_f16_f32 v67, v74, v75
	global_store_dwordx4 v[84:85], v[64:67], off offset:256
	v_exp_f32_e32 v62, v62
	v_exp_f32_e32 v63, v63
	v_lshl_add_u64 v[64:65], v[174:175], 0, v[102:103]
	global_load_dwordx4 v[98:101], v[64:65], off
	global_load_dwordx4 v[88:91], v[64:65], off offset:256
	v_lshl_add_u64 v[64:65], v[174:175], 0, v[96:97]
	global_load_dwordx4 v[84:87], v[64:65], off
	global_load_dwordx4 v[80:83], v[64:65], off offset:256
	v_mul_f32_e32 v56, 0xbfb8aa3b, v56
	v_mul_f32_e32 v57, 0xbfb8aa3b, v57
	v_add_f32_e32 v62, 1.0, v62
	v_add_f32_e32 v63, 1.0, v63
	v_exp_f32_e32 v56, v56
	v_exp_f32_e32 v57, v57
	v_rcp_f32_e32 v62, v62
	v_rcp_f32_e32 v63, v63
	v_add_f32_e32 v56, 1.0, v56
	v_add_f32_e32 v57, 1.0, v57
	v_rcp_f32_e32 v56, v56
	v_rcp_f32_e32 v57, v57
	v_mul_f32_e32 v60, 0xbfb8aa3b, v60
	v_mul_f32_e32 v61, 0xbfb8aa3b, v61
	v_exp_f32_e32 v60, v60
	v_exp_f32_e32 v61, v61
	s_mov_b64 s[18:19], 0x50000
	v_lshl_add_u64 v[94:95], v[182:183], 0, s[18:19]
	v_lshl_add_u64 v[64:65], v[174:175], 0, v[94:95]
	v_add_f32_e32 v60, 1.0, v60
	v_add_f32_e32 v61, 1.0, v61
	global_load_dwordx4 v[76:79], v[64:65], off
	global_load_dwordx4 v[72:75], v[64:65], off offset:256
	v_rcp_f32_e32 v60, v60
	v_rcp_f32_e32 v61, v61
	v_mul_f32_e32 v52, 0xbfb8aa3b, v52
	v_mul_f32_e32 v53, 0xbfb8aa3b, v53
	v_exp_f32_e32 v52, v52
	v_exp_f32_e32 v53, v53
	s_mov_b64 s[18:19], 0x58000
	v_lshl_add_u64 v[92:93], v[182:183], 0, s[18:19]
	v_mul_f32_e32 v54, 0xbfb8aa3b, v54
	v_mul_f32_e32 v55, 0xbfb8aa3b, v55
	v_lshl_add_u64 v[64:65], v[174:175], 0, v[92:93]
	v_add_f32_e32 v52, 1.0, v52
	v_add_f32_e32 v53, 1.0, v53
	v_exp_f32_e32 v54, v54
	v_exp_f32_e32 v55, v55
	global_load_dwordx4 v[68:71], v[64:65], off
	s_nop 0
	global_load_dwordx4 v[64:67], v[64:65], off offset:256
	v_rcp_f32_e32 v52, v52
	v_rcp_f32_e32 v53, v53
	v_mul_f32_e32 v48, 0xbfb8aa3b, v48
	v_mul_f32_e32 v49, 0xbfb8aa3b, v49
	v_add_f32_e32 v54, 1.0, v54
	v_add_f32_e32 v55, 1.0, v55
	v_exp_f32_e32 v48, v48
	v_exp_f32_e32 v49, v49
	v_rcp_f32_e32 v54, v54
	v_rcp_f32_e32 v55, v55
	v_add_f32_e32 v48, 1.0, v48
	v_add_f32_e32 v49, 1.0, v49
	v_rcp_f32_e32 v48, v48
	v_rcp_f32_e32 v49, v49
	v_mul_f32_e32 v44, 0xbfb8aa3b, v44
	v_mul_f32_e32 v45, 0xbfb8aa3b, v45
	v_exp_f32_e32 v44, v44
	v_exp_f32_e32 v45, v45
	v_mul_f32_e32 v46, 0xbfb8aa3b, v46
	v_mul_f32_e32 v47, 0xbfb8aa3b, v47
	v_add_f32_e32 v44, 1.0, v44
	v_add_f32_e32 v45, 1.0, v45
	v_exp_f32_e32 v46, v46
	v_exp_f32_e32 v47, v47
	v_rcp_f32_e32 v44, v44
	v_rcp_f32_e32 v45, v45
	v_mul_f32_e32 v40, 0xbfb8aa3b, v40
	v_mul_f32_e32 v41, 0xbfb8aa3b, v41
	v_add_f32_e32 v46, 1.0, v46
	v_add_f32_e32 v47, 1.0, v47
	v_exp_f32_e32 v40, v40
	v_exp_f32_e32 v41, v41
	v_rcp_f32_e32 v46, v46
	v_rcp_f32_e32 v47, v47
	v_add_f32_e32 v40, 1.0, v40
	v_add_f32_e32 v41, 1.0, v41
	v_rcp_f32_e32 v40, v40
	v_rcp_f32_e32 v41, v41
	s_waitcnt vmcnt(0) lgkmcnt(0)
	v_cvt_f32_f16_e32 v104, v98
	v_cvt_f32_f16_sdwa v105, v98 dst_sel:DWORD dst_unused:UNUSED_PAD src0_sel:WORD_1
	v_cvt_f32_f16_e32 v98, v99
	v_cvt_f32_f16_sdwa v99, v99 dst_sel:DWORD dst_unused:UNUSED_PAD src0_sel:WORD_1
	v_mul_f32_e32 v36, 0xbfb8aa3b, v36
	v_pk_mul_f32 v[60:61], v[60:61], v[104:105]
	v_mul_f32_e32 v37, 0xbfb8aa3b, v37
	v_pk_mul_f32 v[62:63], v[62:63], v[98:99]
	v_cvt_f32_f16_e32 v98, v100
	v_cvt_f32_f16_sdwa v99, v100 dst_sel:DWORD dst_unused:UNUSED_PAD src0_sel:WORD_1
	v_exp_f32_e32 v36, v36
	v_exp_f32_e32 v37, v37
	v_mul_f32_e32 v38, 0xbfb8aa3b, v38
	v_pk_mul_f32 v[98:99], v[56:57], v[98:99]
	v_mul_f32_e32 v56, 0xbfb8aa3b, v58
	v_mul_f32_e32 v57, 0xbfb8aa3b, v59
	v_exp_f32_e32 v56, v56
	v_exp_f32_e32 v57, v57
	v_cvt_f32_f16_e32 v58, v101
	v_cvt_f32_f16_sdwa v59, v101 dst_sel:DWORD dst_unused:UNUSED_PAD src0_sel:WORD_1
	v_add_f32_e32 v56, 1.0, v56
	v_add_f32_e32 v57, 1.0, v57
	v_rcp_f32_e32 v56, v56
	v_rcp_f32_e32 v57, v57
	v_mul_f32_e32 v39, 0xbfb8aa3b, v39
	v_add_f32_e32 v36, 1.0, v36
	v_add_f32_e32 v37, 1.0, v37
	v_pk_mul_f32 v[100:101], v[56:57], v[58:59]
	v_lshl_add_u64 v[56:57], s[78:79], 0, v[102:103]
	v_lshl_add_u64 v[56:57], v[56:57], 0, s[16:17]
	v_lshl_add_u64 v[102:103], v[56:57], 0, v[176:177]
	v_cvt_pk_f16_f32 v56, v60, v61
	v_cvt_pk_f16_f32 v57, v62, v63
	v_cvt_pk_f16_f32 v58, v98, v99
	v_cvt_pk_f16_f32 v59, v100, v101
	global_store_dwordx4 v[102:103], v[56:59], off
	v_exp_f32_e32 v38, v38
	v_exp_f32_e32 v39, v39
	v_cvt_f32_f16_e32 v56, v88
	v_cvt_f32_f16_sdwa v57, v88 dst_sel:DWORD dst_unused:UNUSED_PAD src0_sel:WORD_1
	v_rcp_f32_e32 v36, v36
	v_rcp_f32_e32 v37, v37
	v_mul_f32_e32 v32, 0xbfb8aa3b, v32
	v_pk_mul_f32 v[52:53], v[52:53], v[56:57]
	v_cvt_f32_f16_e32 v56, v89
	v_cvt_f32_f16_sdwa v57, v89 dst_sel:DWORD dst_unused:UNUSED_PAD src0_sel:WORD_1
	v_mul_f32_e32 v33, 0xbfb8aa3b, v33
	v_add_f32_e32 v38, 1.0, v38
	v_add_f32_e32 v39, 1.0, v39
	v_pk_mul_f32 v[54:55], v[54:55], v[56:57]
	v_cvt_f32_f16_e32 v56, v90
	v_cvt_f32_f16_sdwa v57, v90 dst_sel:DWORD dst_unused:UNUSED_PAD src0_sel:WORD_1
	v_exp_f32_e32 v32, v32
	v_exp_f32_e32 v33, v33
	v_rcp_f32_e32 v38, v38
	v_pk_mul_f32 v[56:57], v[48:49], v[56:57]
	v_mul_f32_e32 v48, 0xbfb8aa3b, v50
	v_mul_f32_e32 v49, 0xbfb8aa3b, v51
	v_exp_f32_e32 v48, v48
	v_exp_f32_e32 v49, v49
	v_cvt_f32_f16_e32 v50, v91
	v_cvt_f32_f16_sdwa v51, v91 dst_sel:DWORD dst_unused:UNUSED_PAD src0_sel:WORD_1
	v_add_f32_e32 v48, 1.0, v48
	v_add_f32_e32 v49, 1.0, v49
	v_rcp_f32_e32 v48, v48
	v_rcp_f32_e32 v49, v49
	v_rcp_f32_e32 v39, v39
	v_add_f32_e32 v32, 1.0, v32
	v_add_f32_e32 v33, 1.0, v33
	v_pk_mul_f32 v[58:59], v[48:49], v[50:51]
	v_cvt_pk_f16_f32 v48, v52, v53
	v_cvt_pk_f16_f32 v49, v54, v55
	v_cvt_pk_f16_f32 v50, v56, v57
	v_cvt_pk_f16_f32 v51, v58, v59
	global_store_dwordx4 v[102:103], v[48:51], off offset:256
	v_rcp_f32_e32 v32, v32
	v_rcp_f32_e32 v33, v33
	v_cvt_f32_f16_e32 v48, v84
	v_cvt_f32_f16_sdwa v49, v84 dst_sel:DWORD dst_unused:UNUSED_PAD src0_sel:WORD_1
	v_mul_f32_e32 v28, 0xbfb8aa3b, v28
	v_mul_f32_e32 v29, 0xbfb8aa3b, v29
	v_exp_f32_e32 v28, v28
	v_pk_mul_f32 v[44:45], v[44:45], v[48:49]
	v_cvt_f32_f16_e32 v48, v85
	v_cvt_f32_f16_sdwa v49, v85 dst_sel:DWORD dst_unused:UNUSED_PAD src0_sel:WORD_1
	v_exp_f32_e32 v29, v29
	v_mul_f32_e32 v30, 0xbfb8aa3b, v30
	v_mul_f32_e32 v31, 0xbfb8aa3b, v31
	v_pk_mul_f32 v[46:47], v[46:47], v[48:49]
	v_cvt_f32_f16_e32 v48, v86
	v_cvt_f32_f16_sdwa v49, v86 dst_sel:DWORD dst_unused:UNUSED_PAD src0_sel:WORD_1
	v_add_f32_e32 v28, 1.0, v28
	v_add_f32_e32 v29, 1.0, v29
	v_exp_f32_e32 v30, v30
	v_pk_mul_f32 v[48:49], v[40:41], v[48:49]
	v_mul_f32_e32 v40, 0xbfb8aa3b, v42
	v_mul_f32_e32 v41, 0xbfb8aa3b, v43
	v_exp_f32_e32 v40, v40
	v_exp_f32_e32 v41, v41
	v_cvt_f32_f16_e32 v42, v87
	v_cvt_f32_f16_sdwa v43, v87 dst_sel:DWORD dst_unused:UNUSED_PAD src0_sel:WORD_1
	v_add_f32_e32 v40, 1.0, v40
	v_add_f32_e32 v41, 1.0, v41
	v_rcp_f32_e32 v40, v40
	v_rcp_f32_e32 v41, v41
	v_exp_f32_e32 v31, v31
	v_rcp_f32_e32 v28, v28
	v_rcp_f32_e32 v29, v29
	v_pk_mul_f32 v[50:51], v[40:41], v[42:43]
	v_lshl_add_u64 v[40:41], s[78:79], 0, v[96:97]
	v_lshl_add_u64 v[40:41], v[40:41], 0, s[16:17]
	v_lshl_add_u64 v[52:53], v[40:41], 0, v[176:177]
	v_cvt_pk_f16_f32 v40, v44, v45
	v_cvt_pk_f16_f32 v41, v46, v47
	v_cvt_pk_f16_f32 v42, v48, v49
	v_cvt_pk_f16_f32 v43, v50, v51
	global_store_dwordx4 v[52:53], v[40:43], off
	v_mul_f32_e32 v24, 0xbfb8aa3b, v24
	v_mul_f32_e32 v25, 0xbfb8aa3b, v25
	v_cvt_f32_f16_e32 v40, v80
	v_cvt_f32_f16_sdwa v41, v80 dst_sel:DWORD dst_unused:UNUSED_PAD src0_sel:WORD_1
	v_add_f32_e32 v30, 1.0, v30
	v_add_f32_e32 v31, 1.0, v31
	v_exp_f32_e32 v24, v24
	v_pk_mul_f32 v[36:37], v[36:37], v[40:41]
	v_cvt_f32_f16_e32 v40, v81
	v_cvt_f32_f16_sdwa v41, v81 dst_sel:DWORD dst_unused:UNUSED_PAD src0_sel:WORD_1
	v_exp_f32_e32 v25, v25
	v_rcp_f32_e32 v30, v30
	v_rcp_f32_e32 v31, v31
	v_pk_mul_f32 v[38:39], v[38:39], v[40:41]
	v_cvt_f32_f16_e32 v40, v82
	v_cvt_f32_f16_sdwa v41, v82 dst_sel:DWORD dst_unused:UNUSED_PAD src0_sel:WORD_1
	v_add_f32_e32 v24, 1.0, v24
	v_add_f32_e32 v25, 1.0, v25
	v_rcp_f32_e32 v24, v24
	v_pk_mul_f32 v[40:41], v[32:33], v[40:41]
	v_mul_f32_e32 v32, 0xbfb8aa3b, v34
	v_mul_f32_e32 v33, 0xbfb8aa3b, v35
	v_exp_f32_e32 v32, v32
	v_exp_f32_e32 v33, v33
	v_cvt_f32_f16_e32 v34, v83
	v_cvt_f32_f16_sdwa v35, v83 dst_sel:DWORD dst_unused:UNUSED_PAD src0_sel:WORD_1
	v_add_f32_e32 v32, 1.0, v32
	v_add_f32_e32 v33, 1.0, v33
	v_rcp_f32_e32 v32, v32
	v_rcp_f32_e32 v33, v33
	v_rcp_f32_e32 v25, v25
	v_mul_f32_e32 v20, 0xbfb8aa3b, v20
	v_mul_f32_e32 v21, 0xbfb8aa3b, v21
	v_pk_mul_f32 v[42:43], v[32:33], v[34:35]
	v_cvt_pk_f16_f32 v32, v36, v37
	v_cvt_pk_f16_f32 v33, v38, v39
	v_cvt_pk_f16_f32 v34, v40, v41
	v_cvt_pk_f16_f32 v35, v42, v43
	global_store_dwordx4 v[52:53], v[32:35], off offset:256
	v_exp_f32_e32 v20, v20
	v_exp_f32_e32 v21, v21
	v_cvt_f32_f16_e32 v32, v76
	v_cvt_f32_f16_sdwa v33, v76 dst_sel:DWORD dst_unused:UNUSED_PAD src0_sel:WORD_1
	v_mul_f32_e32 v22, 0xbfb8aa3b, v22
	v_mul_f32_e32 v23, 0xbfb8aa3b, v23
	v_add_f32_e32 v20, 1.0, v20
	v_pk_mul_f32 v[28:29], v[28:29], v[32:33]
	v_cvt_f32_f16_e32 v32, v77
	v_cvt_f32_f16_sdwa v33, v77 dst_sel:DWORD dst_unused:UNUSED_PAD src0_sel:WORD_1
	v_add_f32_e32 v21, 1.0, v21
	v_exp_f32_e32 v22, v22
	v_exp_f32_e32 v23, v23
	v_pk_mul_f32 v[30:31], v[30:31], v[32:33]
	v_cvt_f32_f16_e32 v32, v78
	v_cvt_f32_f16_sdwa v33, v78 dst_sel:DWORD dst_unused:UNUSED_PAD src0_sel:WORD_1
	v_rcp_f32_e32 v20, v20
	v_rcp_f32_e32 v21, v21
	v_pk_mul_f32 v[32:33], v[24:25], v[32:33]
	v_mul_f32_e32 v24, 0xbfb8aa3b, v26
	v_mul_f32_e32 v25, 0xbfb8aa3b, v27
	v_exp_f32_e32 v24, v24
	v_exp_f32_e32 v25, v25
	v_cvt_f32_f16_e32 v26, v79
	v_cvt_f32_f16_sdwa v27, v79 dst_sel:DWORD dst_unused:UNUSED_PAD src0_sel:WORD_1
	v_add_f32_e32 v24, 1.0, v24
	v_add_f32_e32 v25, 1.0, v25
	v_rcp_f32_e32 v24, v24
	v_rcp_f32_e32 v25, v25
	v_mul_f32_e32 v16, 0xbfb8aa3b, v16
	v_mul_f32_e32 v17, 0xbfb8aa3b, v17
	v_add_f32_e32 v22, 1.0, v22
	v_pk_mul_f32 v[34:35], v[24:25], v[26:27]
	v_lshl_add_u64 v[24:25], s[78:79], 0, v[94:95]
	v_lshl_add_u64 v[24:25], v[24:25], 0, s[16:17]
	v_lshl_add_u64 v[36:37], v[24:25], 0, v[176:177]
	v_cvt_pk_f16_f32 v24, v28, v29
	v_cvt_pk_f16_f32 v25, v30, v31
	v_cvt_pk_f16_f32 v26, v32, v33
	v_cvt_pk_f16_f32 v27, v34, v35
	global_store_dwordx4 v[36:37], v[24:27], off
	v_add_f32_e32 v23, 1.0, v23
	v_exp_f32_e32 v16, v16
	v_cvt_f32_f16_e32 v24, v72
	v_cvt_f32_f16_sdwa v25, v72 dst_sel:DWORD dst_unused:UNUSED_PAD src0_sel:WORD_1
	v_exp_f32_e32 v17, v17
	v_rcp_f32_e32 v22, v22
	v_rcp_f32_e32 v23, v23
	v_pk_mul_f32 v[20:21], v[20:21], v[24:25]
	v_cvt_f32_f16_e32 v24, v73
	v_cvt_f32_f16_sdwa v25, v73 dst_sel:DWORD dst_unused:UNUSED_PAD src0_sel:WORD_1
	v_add_f32_e32 v16, 1.0, v16
	v_add_f32_e32 v17, 1.0, v17
	v_rcp_f32_e32 v16, v16
	v_pk_mul_f32 v[22:23], v[22:23], v[24:25]
	v_rcp_f32_e32 v17, v17
	v_cvt_f32_f16_e32 v24, v74
	v_cvt_f32_f16_sdwa v25, v74 dst_sel:DWORD dst_unused:UNUSED_PAD src0_sel:WORD_1
	v_mul_f32_e32 v12, 0xbfb8aa3b, v12
	v_mul_f32_e32 v13, 0xbfb8aa3b, v13
	v_exp_f32_e32 v12, v12
	v_pk_mul_f32 v[24:25], v[16:17], v[24:25]
	v_mul_f32_e32 v16, 0xbfb8aa3b, v18
	v_mul_f32_e32 v17, 0xbfb8aa3b, v19
	v_exp_f32_e32 v16, v16
	v_exp_f32_e32 v17, v17
	v_cvt_f32_f16_e32 v18, v75
	v_cvt_f32_f16_sdwa v19, v75 dst_sel:DWORD dst_unused:UNUSED_PAD src0_sel:WORD_1
	v_add_f32_e32 v16, 1.0, v16
	v_add_f32_e32 v17, 1.0, v17
	v_rcp_f32_e32 v16, v16
	v_rcp_f32_e32 v17, v17
	v_exp_f32_e32 v13, v13
	v_mul_f32_e32 v14, 0xbfb8aa3b, v14
	v_mul_f32_e32 v15, 0xbfb8aa3b, v15
	v_pk_mul_f32 v[26:27], v[16:17], v[18:19]
	v_cvt_pk_f16_f32 v16, v20, v21
	v_cvt_pk_f16_f32 v17, v22, v23
	v_cvt_pk_f16_f32 v18, v24, v25
	v_cvt_pk_f16_f32 v19, v26, v27
	v_add_f32_e32 v12, 1.0, v12
	v_add_f32_e32 v13, 1.0, v13
	v_exp_f32_e32 v14, v14
	v_exp_f32_e32 v15, v15
	global_store_dwordx4 v[36:37], v[16:19], off offset:256
	v_rcp_f32_e32 v12, v12
	v_rcp_f32_e32 v13, v13
	v_cvt_f32_f16_e32 v16, v68
	v_cvt_f32_f16_sdwa v17, v68 dst_sel:DWORD dst_unused:UNUSED_PAD src0_sel:WORD_1
	v_mul_f32_e32 v8, 0xbfb8aa3b, v8
	v_mul_f32_e32 v9, 0xbfb8aa3b, v9
	v_add_f32_e32 v14, 1.0, v14
	v_add_f32_e32 v15, 1.0, v15
	v_exp_f32_e32 v8, v8
	v_exp_f32_e32 v9, v9
	v_pk_mul_f32 v[12:13], v[12:13], v[16:17]
	v_rcp_f32_e32 v14, v14
	v_rcp_f32_e32 v15, v15
	v_cvt_f32_f16_e32 v16, v69
	v_cvt_f32_f16_sdwa v17, v69 dst_sel:DWORD dst_unused:UNUSED_PAD src0_sel:WORD_1
	v_add_f32_e32 v8, 1.0, v8
	v_add_f32_e32 v9, 1.0, v9
	v_rcp_f32_e32 v8, v8
	v_pk_mul_f32 v[14:15], v[14:15], v[16:17]
	v_rcp_f32_e32 v9, v9
	v_cvt_f32_f16_e32 v16, v70
	v_cvt_f32_f16_sdwa v17, v70 dst_sel:DWORD dst_unused:UNUSED_PAD src0_sel:WORD_1
	v_mul_f32_e32 v4, 0xbfb8aa3b, v4
	v_mul_f32_e32 v5, 0xbfb8aa3b, v5
	v_exp_f32_e32 v4, v4
	v_pk_mul_f32 v[16:17], v[8:9], v[16:17]
	v_mul_f32_e32 v8, 0xbfb8aa3b, v10
	v_mul_f32_e32 v9, 0xbfb8aa3b, v11
	v_exp_f32_e32 v8, v8
	v_exp_f32_e32 v9, v9
	v_cvt_f32_f16_e32 v10, v71
	v_cvt_f32_f16_sdwa v11, v71 dst_sel:DWORD dst_unused:UNUSED_PAD src0_sel:WORD_1
	v_add_f32_e32 v8, 1.0, v8
	v_add_f32_e32 v9, 1.0, v9
	v_rcp_f32_e32 v8, v8
	v_rcp_f32_e32 v9, v9
	v_exp_f32_e32 v5, v5
	v_mul_f32_e32 v6, 0xbfb8aa3b, v6
	v_mul_f32_e32 v7, 0xbfb8aa3b, v7
	v_pk_mul_f32 v[18:19], v[8:9], v[10:11]
	v_lshl_add_u64 v[8:9], s[78:79], 0, v[92:93]
	v_lshl_add_u64 v[8:9], v[8:9], 0, s[16:17]
	v_lshl_add_u64 v[20:21], v[8:9], 0, v[176:177]
	v_cvt_pk_f16_f32 v8, v12, v13
	v_cvt_pk_f16_f32 v9, v14, v15
	v_cvt_pk_f16_f32 v10, v16, v17
	v_cvt_pk_f16_f32 v11, v18, v19
	v_add_f32_e32 v4, 1.0, v4
	v_add_f32_e32 v5, 1.0, v5
	v_exp_f32_e32 v6, v6
	v_exp_f32_e32 v7, v7
	global_store_dwordx4 v[20:21], v[8:11], off
	v_rcp_f32_e32 v4, v4
	v_rcp_f32_e32 v5, v5
	v_cvt_f32_f16_e32 v8, v64
	v_cvt_f32_f16_sdwa v9, v64 dst_sel:DWORD dst_unused:UNUSED_PAD src0_sel:WORD_1
	v_mul_f32_e32 v0, 0xbfb8aa3b, v0
	v_mul_f32_e32 v1, 0xbfb8aa3b, v1
	v_add_f32_e32 v6, 1.0, v6
	v_add_f32_e32 v7, 1.0, v7
	v_exp_f32_e32 v0, v0
	v_exp_f32_e32 v1, v1
	v_pk_mul_f32 v[4:5], v[4:5], v[8:9]
	v_rcp_f32_e32 v6, v6
	v_rcp_f32_e32 v7, v7
	v_cvt_f32_f16_e32 v8, v65
	v_cvt_f32_f16_sdwa v9, v65 dst_sel:DWORD dst_unused:UNUSED_PAD src0_sel:WORD_1
	v_add_f32_e32 v0, 1.0, v0
	v_add_f32_e32 v1, 1.0, v1
	v_rcp_f32_e32 v0, v0
	v_pk_mul_f32 v[6:7], v[6:7], v[8:9]
	v_rcp_f32_e32 v1, v1
	v_cvt_f32_f16_e32 v8, v66
	v_cvt_f32_f16_sdwa v9, v66 dst_sel:DWORD dst_unused:UNUSED_PAD src0_sel:WORD_1
	s_mov_b64 s[16:17], -1
	s_andn2_b64 vcc, exec, s[2:3]
	v_pk_mul_f32 v[8:9], v[0:1], v[8:9]
	v_mul_f32_e32 v0, 0xbfb8aa3b, v2
	v_mul_f32_e32 v1, 0xbfb8aa3b, v3
	v_exp_f32_e32 v0, v0
	v_exp_f32_e32 v1, v1
	v_cvt_f32_f16_e32 v2, v67
	v_cvt_f32_f16_sdwa v3, v67 dst_sel:DWORD dst_unused:UNUSED_PAD src0_sel:WORD_1
	v_add_f32_e32 v0, 1.0, v0
	v_add_f32_e32 v1, 1.0, v1
	v_rcp_f32_e32 v0, v0
	v_rcp_f32_e32 v1, v1
	s_nop 0
	v_pk_mul_f32 v[10:11], v[0:1], v[2:3]
	v_cvt_pk_f16_f32 v0, v4, v5
	v_cvt_pk_f16_f32 v1, v6, v7
	v_cvt_pk_f16_f32 v2, v8, v9
	v_cvt_pk_f16_f32 v3, v10, v11
	global_store_dwordx4 v[20:21], v[0:3], off offset:256
	s_cbranch_vccnz .LBB0_874
	s_andn2_b64 vcc, exec, s[0:1]
	s_cbranch_vccnz .LBB0_873
	s_barrier
	s_branch .LBB0_873

.LBB0_908:
	s_lshl_b32 s10, s36, 4
	s_ashr_i32 s11, s10, 31
	s_mul_i32 s14, s36, 0x240000
	s_mul_hi_i32 s15, s36, 0x240000
	s_add_u32 s14, s12, s14
	s_addc_u32 s15, s13, s15
	v_lshl_add_u32 v188, s37, 8, v173
	s_lshl_b32 s16, s31, 8
	v_mov_b64_e32 v[190:191], s[14:15]
	s_ashr_i32 s17, s16, 31
	v_mad_i64_i32 v[64:65], s[14:15], v188, s52, v[190:191]
	s_lshl_b64 s[14:15], s[16:17], 1
	s_nop 0
	v_lshl_add_u64 v[64:65], v[64:65], 0, s[14:15]
	v_lshlrev_b32_e32 v176, 1, v172
	v_lshl_add_u64 v[136:137], v[64:65], 0, v[176:177]
	global_load_dwordx4 v[210:213], v[136:137], off offset:256
	v_lshl_add_u64 v[64:65], s[10:11], 2, v[174:175]
	global_load_dwordx4 v[72:75], v[64:65], off
	s_nop 0
	global_load_dwordx4 v[64:67], v[64:65], off offset:16
	v_or_b32_e32 v196, 16, v188
	v_or_b32_e32 v194, 32, v188
	v_or_b32_e32 v192, 48, v188
	v_or_b32_e32 v144, s16, v172
	v_mad_i64_i32 v[138:139], s[16:17], v196, s52, v[190:191]
	v_mad_i64_i32 v[140:141], s[16:17], v194, s52, v[190:191]
	v_mad_i64_i32 v[142:143], s[16:17], v192, s52, v[190:191]
	v_lshl_add_u64 v[138:139], v[138:139], 0, s[14:15]
	v_lshl_add_u64 v[140:141], v[140:141], 0, s[14:15]
	v_lshl_add_u64 v[142:143], v[142:143], 0, s[14:15]
	v_lshl_add_u64 v[138:139], v[138:139], 0, v[176:177]
	v_lshl_add_u64 v[140:141], v[140:141], 0, v[176:177]
	v_ashrrev_i32_e32 v216, 4, v144
	v_lshl_add_u64 v[218:219], v[142:143], 0, v[176:177]
	global_load_dwordx4 v[160:163], v[136:137], off offset:512
	global_load_dwordx4 v[156:159], v[138:139], off offset:256
	global_load_dwordx4 v[152:155], v[138:139], off offset:512
	global_load_dwordx4 v[148:151], v[140:141], off offset:256
	global_load_dwordx4 v[144:147], v[140:141], off offset:512
	s_nop 0
	global_load_dwordx4 v[140:143], v[218:219], off offset:256
	global_load_dwordx4 v[136:139], v[218:219], off offset:512
	v_ashrrev_i32_e32 v189, 31, v188
	v_lshlrev_b64 v[214:215], 17, v[188:189]
	v_lshl_add_u64 v[214:215], s[48:49], 0, v[214:215]
	s_lshl_b64 s[10:11], s[10:11], 1
	v_ashrrev_i32_e32 v197, 31, v196
	v_ashrrev_i32_e32 v195, 31, v194
	v_ashrrev_i32_e32 v193, 31, v192
	s_and_b64 vcc, exec, s[2:3]
	s_mov_b64 s[2:3], -1
	s_waitcnt vmcnt(0) lgkmcnt(0)
	v_cvt_f32_f16_e32 v218, v210
	v_cvt_f32_f16_sdwa v219, v210 dst_sel:DWORD dst_unused:UNUSED_PAD src0_sel:WORD_1
	v_cvt_f32_f16_e32 v210, v211
	v_cvt_f32_f16_sdwa v211, v211 dst_sel:DWORD dst_unused:UNUSED_PAD src0_sel:WORD_1
	v_cvt_f32_f16_e32 v220, v212
	v_pk_fma_f32 v[132:133], v[72:73], v[218:219], v[132:133]
	v_cvt_f32_f16_sdwa v221, v212 dst_sel:DWORD dst_unused:UNUSED_PAD src0_sel:WORD_1
	v_pk_fma_f32 v[134:135], v[74:75], v[210:211], v[134:135]
	v_mul_f32_e32 v189, 0x3d372713, v133
	v_mul_f32_e32 v209, 0x3d372713, v134
	v_mul_f32_e32 v189, v133, v189
	v_mul_f32_e32 v209, v134, v209
	v_fma_f32 v189, v133, v189, v133
	v_fma_f32 v209, v134, v209, v134
	v_mul_f32_e32 v189, 0x3fcc422a, v189
	v_pk_fma_f32 v[128:129], v[64:65], v[220:221], v[128:129]
	v_mul_f32_e32 v209, 0x3fcc422a, v209
	v_mul_f32_e32 v189, 0xbfb8aa3b, v189
	v_cvt_f32_f16_e32 v212, v213
	v_cvt_f32_f16_sdwa v213, v213 dst_sel:DWORD dst_unused:UNUSED_PAD src0_sel:WORD_1
	v_mul_f32_e32 v211, 0x3d372713, v128
	v_mul_f32_e32 v209, 0xbfb8aa3b, v209
	v_exp_f32_e32 v189, v189
	v_mul_f32_e32 v187, 0x3d372713, v132
	v_mul_f32_e32 v211, v128, v211
	v_exp_f32_e32 v209, v209
	v_mul_f32_e32 v210, 0x3d372713, v135
	v_mul_f32_e32 v187, v132, v187
	v_fma_f32 v211, v128, v211, v128
	v_mul_f32_e32 v217, 0x3d372713, v129
	v_mul_f32_e32 v210, v135, v210
	v_fma_f32 v187, v132, v187, v132
	v_mul_f32_e32 v211, 0x3fcc422a, v211
	v_mul_f32_e32 v217, v129, v217
	v_fma_f32 v210, v135, v210, v135
	v_mul_f32_e32 v187, 0x3fcc422a, v187
	v_mul_f32_e32 v211, 0xbfb8aa3b, v211
	v_add_f32_e32 v189, 1.0, v189
	v_pk_fma_f32 v[130:131], v[66:67], v[212:213], v[130:131]
	v_fma_f32 v217, v129, v217, v129
	v_mul_f32_e32 v210, 0x3fcc422a, v210
	v_mul_f32_e32 v187, 0xbfb8aa3b, v187
	v_exp_f32_e32 v220, v211
	v_add_f32_e32 v209, 1.0, v209
	v_rcp_f32_e32 v211, v189
	v_mul_f32_e32 v189, 0x3d372713, v130
	v_mul_f32_e32 v217, 0x3fcc422a, v217
	v_mul_f32_e32 v210, 0xbfb8aa3b, v210
	v_exp_f32_e32 v187, v187
	v_rcp_f32_e32 v218, v209
	v_mul_f32_e32 v189, v130, v189
	v_mul_f32_e32 v209, 0x3d372713, v131
	v_mul_f32_e32 v217, 0xbfb8aa3b, v217
	v_exp_f32_e32 v210, v210
	v_fma_f32 v189, v130, v189, v130
	v_mul_f32_e32 v209, v131, v209
	v_exp_f32_e32 v217, v217
	v_mul_f32_e32 v189, 0x3fcc422a, v189
	v_fma_f32 v209, v131, v209, v131
	v_mul_f32_e32 v189, 0xbfb8aa3b, v189
	v_mul_f32_e32 v209, 0x3fcc422a, v209
	v_add_f32_e32 v187, 1.0, v187
	v_exp_f32_e32 v189, v189
	v_mul_f32_e32 v209, 0xbfb8aa3b, v209
	v_add_f32_e32 v219, 1.0, v210
	v_rcp_f32_e32 v210, v187
	v_add_f32_e32 v187, 1.0, v220
	v_exp_f32_e32 v209, v209
	v_rcp_f32_e32 v220, v187
	v_add_f32_e32 v187, 1.0, v217
	v_rcp_f32_e32 v221, v187
	v_add_f32_e32 v187, 1.0, v189
	v_rcp_f32_e32 v212, v187
	v_add_f32_e32 v187, 1.0, v209
	v_rcp_f32_e32 v213, v187
	v_pk_mul_f32 v[132:133], v[132:133], v[210:211]
	v_pk_mul_f32 v[210:211], v[128:129], v[220:221]
	v_cvt_f32_f16_e32 v220, v160
	v_cvt_f32_f16_sdwa v221, v160 dst_sel:DWORD dst_unused:UNUSED_PAD src0_sel:WORD_1
	v_rcp_f32_e32 v219, v219
	v_ashrrev_i32_e32 v217, 31, v216
	v_lshlrev_b64 v[128:129], 11, v[216:217]
	v_pk_mul_f32 v[212:213], v[130:131], v[212:213]
	v_lshl_add_u64 v[130:131], v[214:215], 0, v[128:129]
	v_lshl_add_u64 v[130:131], v[130:131], 0, s[10:11]
	v_mov_b32_e32 v187, v177
	v_pk_fma_f32 v[124:125], v[72:73], v[220:221], v[124:125]
	v_pk_mul_f32 v[134:135], v[134:135], v[218:219]
	v_lshl_add_u64 v[218:219], v[130:131], 0, v[186:187]
	v_cvt_pk_f16_f32 v130, v132, v133
	v_mul_f32_e32 v133, 0x3d372713, v124
	v_mul_f32_e32 v133, v124, v133
	v_fma_f32 v133, v124, v133, v124
	v_mul_f32_e32 v133, 0x3fcc422a, v133
	v_mul_f32_e32 v133, 0xbfb8aa3b, v133
	v_cvt_pk_f16_f32 v131, v134, v135
	v_exp_f32_e32 v134, v133
	v_cvt_pk_f16_f32 v132, v210, v211
	v_cvt_pk_f16_f32 v133, v212, v213
	global_store_dwordx4 v[218:219], v[130:133], off
	s_nop 1
	v_mul_f32_e32 v132, 0x3d372713, v125
	v_mul_f32_e32 v132, v125, v132
	v_add_f32_e32 v131, 1.0, v134
	v_fma_f32 v134, v125, v132, v125
	v_cvt_f32_f16_e32 v132, v161
	v_cvt_f32_f16_sdwa v133, v161 dst_sel:DWORD dst_unused:UNUSED_PAD src0_sel:WORD_1
	v_mul_f32_e32 v134, 0x3fcc422a, v134
	v_mul_f32_e32 v134, 0xbfb8aa3b, v134
	v_exp_f32_e32 v134, v134
	v_pk_fma_f32 v[126:127], v[74:75], v[132:133], v[126:127]
	v_or_b32_e32 v130, 8, v216
	v_mul_f32_e32 v132, 0x3d372713, v126
	v_mul_f32_e32 v132, v126, v132
	v_fma_f32 v132, v126, v132, v126
	v_mul_f32_e32 v132, 0x3fcc422a, v132
	v_mul_f32_e32 v132, 0xbfb8aa3b, v132
	v_exp_f32_e32 v135, v132
	v_rcp_f32_e32 v132, v131
	v_add_f32_e32 v131, 1.0, v134
	v_mul_f32_e32 v134, 0x3d372713, v127
	v_mul_f32_e32 v134, v127, v134
	v_fma_f32 v134, v127, v134, v127
	v_mul_f32_e32 v134, 0x3fcc422a, v134
	v_mul_f32_e32 v134, 0xbfb8aa3b, v134
	v_rcp_f32_e32 v133, v131
	v_add_f32_e32 v131, 1.0, v135
	v_exp_f32_e32 v161, v134
	v_cvt_f32_f16_e32 v134, v162
	v_cvt_f32_f16_sdwa v135, v162 dst_sel:DWORD dst_unused:UNUSED_PAD src0_sel:WORD_1
	v_rcp_f32_e32 v160, v131
	v_add_f32_e32 v131, 1.0, v161
	v_rcp_f32_e32 v161, v131
	v_pk_fma_f32 v[120:121], v[64:65], v[134:135], v[120:121]
	v_cvt_f32_f16_sdwa v135, v163 dst_sel:DWORD dst_unused:UNUSED_PAD src0_sel:WORD_1
	v_mul_f32_e32 v134, 0x3d372713, v121
	v_mul_f32_e32 v134, v121, v134
	v_fma_f32 v134, v121, v134, v121
	v_mul_f32_e32 v134, 0x3fcc422a, v134
	v_mul_f32_e32 v134, 0xbfb8aa3b, v134
	v_exp_f32_e32 v189, v134
	v_cvt_f32_f16_e32 v134, v163
	v_mul_f32_e32 v131, 0x3d372713, v120
	v_mul_f32_e32 v131, v120, v131
	v_fma_f32 v131, v120, v131, v120
	v_pk_fma_f32 v[122:123], v[66:67], v[134:135], v[122:123]
	v_mul_f32_e32 v131, 0x3fcc422a, v131
	v_mul_f32_e32 v134, 0x3d372713, v122
	v_mul_f32_e32 v134, v122, v134
	v_mul_f32_e32 v135, 0x3d372713, v123
	v_mul_f32_e32 v131, 0xbfb8aa3b, v131
	v_fma_f32 v134, v122, v134, v122
	v_mul_f32_e32 v135, v123, v135
	v_exp_f32_e32 v131, v131
	v_mul_f32_e32 v134, 0x3fcc422a, v134
	v_fma_f32 v135, v123, v135, v123
	v_mul_f32_e32 v134, 0xbfb8aa3b, v134
	v_mul_f32_e32 v135, 0x3fcc422a, v135
	v_exp_f32_e32 v134, v134
	v_mul_f32_e32 v135, 0xbfb8aa3b, v135
	v_exp_f32_e32 v135, v135
	v_add_f32_e32 v131, 1.0, v131
	v_rcp_f32_e32 v162, v131
	v_add_f32_e32 v131, 1.0, v189
	v_rcp_f32_e32 v163, v131
	v_add_f32_e32 v131, 1.0, v134
	v_rcp_f32_e32 v134, v131
	v_add_f32_e32 v131, 1.0, v135
	v_rcp_f32_e32 v135, v131
	v_pk_mul_f32 v[126:127], v[126:127], v[160:161]
	v_ashrrev_i32_e32 v131, 31, v130
	v_cvt_f32_f16_e32 v160, v156
	v_cvt_f32_f16_sdwa v161, v156 dst_sel:DWORD dst_unused:UNUSED_PAD src0_sel:WORD_1
	v_pk_mul_f32 v[124:125], v[124:125], v[132:133]
	v_pk_mul_f32 v[132:133], v[120:121], v[162:163]
	v_lshlrev_b64 v[120:121], 11, v[130:131]
	v_pk_mul_f32 v[134:135], v[122:123], v[134:135]
	v_lshl_add_u64 v[122:123], v[214:215], 0, v[120:121]
	v_lshl_add_u64 v[122:123], v[122:123], 0, s[10:11]
	v_lshl_add_u64 v[130:131], v[122:123], 0, v[186:187]
	v_cvt_pk_f16_f32 v122, v124, v125
	v_cvt_pk_f16_f32 v123, v126, v127
	v_cvt_pk_f16_f32 v124, v132, v133
	v_cvt_pk_f16_f32 v125, v134, v135
	v_pk_fma_f32 v[116:117], v[72:73], v[160:161], v[116:117]
	global_store_dwordx4 v[130:131], v[122:125], off
	v_mul_f32_e32 v126, 0x3d372713, v116
	v_mul_f32_e32 v126, v116, v126
	v_mul_f32_e32 v124, 0x3d372713, v117
	v_mul_f32_e32 v124, v117, v124
	v_fma_f32 v127, v117, v124, v117
	v_cvt_f32_f16_e32 v124, v157
	v_cvt_f32_f16_sdwa v125, v157 dst_sel:DWORD dst_unused:UNUSED_PAD src0_sel:WORD_1
	v_fma_f32 v126, v116, v126, v116
	v_mul_f32_e32 v126, 0x3fcc422a, v126
	v_mul_f32_e32 v126, 0xbfb8aa3b, v126
	v_pk_fma_f32 v[118:119], v[74:75], v[124:125], v[118:119]
	v_exp_f32_e32 v126, v126
	v_mul_f32_e32 v124, 0x3d372713, v118
	v_mul_f32_e32 v124, v118, v124
	v_fma_f32 v124, v118, v124, v118
	v_mul_f32_e32 v124, 0x3fcc422a, v124
	v_add_f32_e32 v126, 1.0, v126
	v_mul_f32_e32 v127, 0x3fcc422a, v127
	v_mul_f32_e32 v124, 0xbfb8aa3b, v124
	v_mul_f32_e32 v127, 0xbfb8aa3b, v127
	v_exp_f32_e32 v130, v124
	v_rcp_f32_e32 v124, v126
	v_mul_f32_e32 v126, 0x3d372713, v119
	v_exp_f32_e32 v127, v127
	v_mul_f32_e32 v126, v119, v126
	v_fma_f32 v126, v119, v126, v119
	v_mul_f32_e32 v126, 0x3fcc422a, v126
	v_mul_f32_e32 v126, 0xbfb8aa3b, v126
	v_add_f32_e32 v125, 1.0, v127
	v_exp_f32_e32 v131, v126
	v_cvt_f32_f16_e32 v126, v158
	v_cvt_f32_f16_sdwa v127, v158 dst_sel:DWORD dst_unused:UNUSED_PAD src0_sel:WORD_1
	v_rcp_f32_e32 v125, v125
	v_add_f32_e32 v130, 1.0, v130
	v_add_f32_e32 v131, 1.0, v131
	v_pk_fma_f32 v[112:113], v[64:65], v[126:127], v[112:113]
	v_cvt_f32_f16_sdwa v127, v159 dst_sel:DWORD dst_unused:UNUSED_PAD src0_sel:WORD_1
	v_mul_f32_e32 v126, 0x3d372713, v112
	v_mul_f32_e32 v126, v112, v126
	v_fma_f32 v126, v112, v126, v112
	v_mul_f32_e32 v126, 0x3fcc422a, v126
	v_mul_f32_e32 v126, 0xbfb8aa3b, v126
	v_exp_f32_e32 v132, v126
	v_mul_f32_e32 v126, 0x3d372713, v113
	v_mul_f32_e32 v126, v113, v126
	v_fma_f32 v126, v113, v126, v113
	v_mul_f32_e32 v126, 0x3fcc422a, v126
	v_mul_f32_e32 v126, 0xbfb8aa3b, v126
	v_exp_f32_e32 v133, v126
	v_cvt_f32_f16_e32 v126, v159
	v_add_f32_e32 v132, 1.0, v132
	v_rcp_f32_e32 v132, v132
	v_add_f32_e32 v133, 1.0, v133
	v_pk_fma_f32 v[114:115], v[66:67], v[126:127], v[114:115]
	v_rcp_f32_e32 v133, v133
	v_mul_f32_e32 v126, 0x3d372713, v114
	v_mul_f32_e32 v127, 0x3d372713, v115
	v_mul_f32_e32 v126, v114, v126
	v_mul_f32_e32 v127, v115, v127
	v_fma_f32 v126, v114, v126, v114
	v_fma_f32 v127, v115, v127, v115
	v_mul_f32_e32 v126, 0x3fcc422a, v126
	v_mul_f32_e32 v127, 0x3fcc422a, v127
	v_mul_f32_e32 v126, 0xbfb8aa3b, v126
	v_mul_f32_e32 v127, 0xbfb8aa3b, v127
	v_exp_f32_e32 v126, v126
	v_exp_f32_e32 v127, v127
	v_rcp_f32_e32 v130, v130
	v_rcp_f32_e32 v131, v131
	v_add_f32_e32 v126, 1.0, v126
	v_add_f32_e32 v127, 1.0, v127
	v_rcp_f32_e32 v126, v126
	v_rcp_f32_e32 v127, v127
	v_lshlrev_b64 v[122:123], 17, v[196:197]
	v_lshl_add_u64 v[122:123], s[48:49], 0, v[122:123]
	v_pk_mul_f32 v[116:117], v[116:117], v[124:125]
	v_pk_mul_f32 v[126:127], v[114:115], v[126:127]
	v_cvt_f32_f16_e32 v114, v152
	v_cvt_f32_f16_sdwa v115, v152 dst_sel:DWORD dst_unused:UNUSED_PAD src0_sel:WORD_1
	v_pk_mul_f32 v[124:125], v[112:113], v[132:133]
	v_lshl_add_u64 v[112:113], v[122:123], 0, v[128:129]
	v_pk_mul_f32 v[118:119], v[118:119], v[130:131]
	v_pk_fma_f32 v[108:109], v[72:73], v[114:115], v[108:109]
	v_lshl_add_u64 v[112:113], v[112:113], 0, s[10:11]
	v_mul_f32_e32 v114, 0x3d372713, v108
	v_mul_f32_e32 v114, v108, v114
	v_fma_f32 v114, v108, v114, v108
	v_mul_f32_e32 v114, 0x3fcc422a, v114
	v_mul_f32_e32 v114, 0xbfb8aa3b, v114
	v_lshl_add_u64 v[130:131], v[112:113], 0, v[186:187]
	v_cvt_pk_f16_f32 v112, v116, v117
	v_cvt_pk_f16_f32 v113, v118, v119
	v_exp_f32_e32 v116, v114
	v_cvt_pk_f16_f32 v114, v124, v125
	v_cvt_pk_f16_f32 v115, v126, v127
	global_store_dwordx4 v[130:131], v[112:115], off
	s_nop 1
	v_mul_f32_e32 v112, 0x3d372713, v109
	v_mul_f32_e32 v112, v109, v112
	v_fma_f32 v115, v109, v112, v109
	v_cvt_f32_f16_e32 v112, v153
	v_cvt_f32_f16_sdwa v113, v153 dst_sel:DWORD dst_unused:UNUSED_PAD src0_sel:WORD_1
	v_add_f32_e32 v114, 1.0, v116
	v_mul_f32_e32 v115, 0x3fcc422a, v115
	v_mul_f32_e32 v115, 0xbfb8aa3b, v115
	v_pk_fma_f32 v[110:111], v[74:75], v[112:113], v[110:111]
	v_exp_f32_e32 v115, v115
	v_mul_f32_e32 v112, 0x3d372713, v110
	v_mul_f32_e32 v112, v110, v112
	v_fma_f32 v112, v110, v112, v110
	v_mul_f32_e32 v112, 0x3fcc422a, v112
	v_mul_f32_e32 v112, 0xbfb8aa3b, v112
	v_exp_f32_e32 v116, v112
	v_rcp_f32_e32 v112, v114
	v_mul_f32_e32 v114, 0x3d372713, v111
	v_mul_f32_e32 v114, v111, v114
	v_fma_f32 v114, v111, v114, v111
	v_mul_f32_e32 v114, 0x3fcc422a, v114
	v_mul_f32_e32 v114, 0xbfb8aa3b, v114
	v_add_f32_e32 v113, 1.0, v115
	v_exp_f32_e32 v117, v114
	v_cvt_f32_f16_e32 v114, v154
	v_cvt_f32_f16_sdwa v115, v154 dst_sel:DWORD dst_unused:UNUSED_PAD src0_sel:WORD_1
	v_rcp_f32_e32 v113, v113
	v_add_f32_e32 v116, 1.0, v116
	v_add_f32_e32 v117, 1.0, v117
	v_pk_fma_f32 v[104:105], v[64:65], v[114:115], v[104:105]
	v_cvt_f32_f16_sdwa v115, v155 dst_sel:DWORD dst_unused:UNUSED_PAD src0_sel:WORD_1
	v_mul_f32_e32 v114, 0x3d372713, v104
	v_mul_f32_e32 v114, v104, v114
	v_fma_f32 v114, v104, v114, v104
	v_mul_f32_e32 v114, 0x3fcc422a, v114
	v_mul_f32_e32 v114, 0xbfb8aa3b, v114
	v_exp_f32_e32 v118, v114
	v_mul_f32_e32 v114, 0x3d372713, v105
	v_mul_f32_e32 v114, v105, v114
	v_fma_f32 v114, v105, v114, v105
	v_mul_f32_e32 v114, 0x3fcc422a, v114
	v_mul_f32_e32 v114, 0xbfb8aa3b, v114
	v_exp_f32_e32 v119, v114
	v_cvt_f32_f16_e32 v114, v155
	v_add_f32_e32 v118, 1.0, v118
	v_rcp_f32_e32 v118, v118
	v_add_f32_e32 v119, 1.0, v119
	v_pk_fma_f32 v[106:107], v[66:67], v[114:115], v[106:107]
	v_rcp_f32_e32 v119, v119
	v_mul_f32_e32 v114, 0x3d372713, v106
	v_mul_f32_e32 v115, 0x3d372713, v107
	v_mul_f32_e32 v114, v106, v114
	v_mul_f32_e32 v115, v107, v115
	v_fma_f32 v114, v106, v114, v106
	v_fma_f32 v115, v107, v115, v107
	v_mul_f32_e32 v114, 0x3fcc422a, v114
	v_mul_f32_e32 v115, 0x3fcc422a, v115
	v_mul_f32_e32 v114, 0xbfb8aa3b, v114
	v_mul_f32_e32 v115, 0xbfb8aa3b, v115
	v_exp_f32_e32 v114, v114
	v_exp_f32_e32 v115, v115
	v_rcp_f32_e32 v116, v116
	v_rcp_f32_e32 v117, v117
	v_add_f32_e32 v114, 1.0, v114
	v_add_f32_e32 v115, 1.0, v115
	v_pk_mul_f32 v[108:109], v[108:109], v[112:113]
	v_pk_mul_f32 v[112:113], v[104:105], v[118:119]
	v_lshl_add_u64 v[104:105], v[122:123], 0, v[120:121]
	v_rcp_f32_e32 v114, v114
	v_rcp_f32_e32 v115, v115
	v_lshl_add_u64 v[104:105], v[104:105], 0, s[10:11]
	v_pk_mul_f32 v[110:111], v[110:111], v[116:117]
	v_lshl_add_u64 v[116:117], v[104:105], 0, v[186:187]
	v_cvt_pk_f16_f32 v104, v108, v109
	v_cvt_f32_f16_e32 v108, v148
	v_cvt_f32_f16_sdwa v109, v148 dst_sel:DWORD dst_unused:UNUSED_PAD src0_sel:WORD_1
	v_pk_mul_f32 v[114:115], v[106:107], v[114:115]
	v_cvt_pk_f16_f32 v105, v110, v111
	v_cvt_pk_f16_f32 v106, v112, v113
	v_cvt_pk_f16_f32 v107, v114, v115
	v_pk_fma_f32 v[100:101], v[72:73], v[108:109], v[100:101]
	global_store_dwordx4 v[116:117], v[104:107], off
	v_mul_f32_e32 v108, 0x3d372713, v100
	v_mul_f32_e32 v108, v100, v108
	v_mul_f32_e32 v106, 0x3d372713, v101
	v_mul_f32_e32 v106, v101, v106
	v_fma_f32 v109, v101, v106, v101
	v_cvt_f32_f16_e32 v106, v149
	v_cvt_f32_f16_sdwa v107, v149 dst_sel:DWORD dst_unused:UNUSED_PAD src0_sel:WORD_1
	v_fma_f32 v108, v100, v108, v100
	v_mul_f32_e32 v108, 0x3fcc422a, v108
	v_mul_f32_e32 v108, 0xbfb8aa3b, v108
	v_pk_fma_f32 v[102:103], v[74:75], v[106:107], v[102:103]
	v_exp_f32_e32 v108, v108
	v_mul_f32_e32 v106, 0x3d372713, v102
	v_mul_f32_e32 v106, v102, v106
	v_fma_f32 v106, v102, v106, v102
	v_mul_f32_e32 v106, 0x3fcc422a, v106
	v_add_f32_e32 v108, 1.0, v108
	v_mul_f32_e32 v109, 0x3fcc422a, v109
	v_mul_f32_e32 v106, 0xbfb8aa3b, v106
	v_mul_f32_e32 v109, 0xbfb8aa3b, v109
	v_exp_f32_e32 v110, v106
	v_rcp_f32_e32 v106, v108
	v_mul_f32_e32 v108, 0x3d372713, v103
	v_exp_f32_e32 v109, v109
	v_mul_f32_e32 v108, v103, v108
	v_fma_f32 v108, v103, v108, v103
	v_mul_f32_e32 v108, 0x3fcc422a, v108
	v_mul_f32_e32 v108, 0xbfb8aa3b, v108
	v_add_f32_e32 v107, 1.0, v109
	v_exp_f32_e32 v111, v108
	v_cvt_f32_f16_e32 v108, v150
	v_cvt_f32_f16_sdwa v109, v150 dst_sel:DWORD dst_unused:UNUSED_PAD src0_sel:WORD_1
	v_rcp_f32_e32 v107, v107
	v_add_f32_e32 v110, 1.0, v110
	v_add_f32_e32 v111, 1.0, v111
	v_pk_fma_f32 v[96:97], v[64:65], v[108:109], v[96:97]
	v_cvt_f32_f16_sdwa v109, v151 dst_sel:DWORD dst_unused:UNUSED_PAD src0_sel:WORD_1
	v_mul_f32_e32 v108, 0x3d372713, v96
	v_mul_f32_e32 v108, v96, v108
	v_fma_f32 v108, v96, v108, v96
	v_mul_f32_e32 v108, 0x3fcc422a, v108
	v_mul_f32_e32 v108, 0xbfb8aa3b, v108
	v_exp_f32_e32 v112, v108
	v_mul_f32_e32 v108, 0x3d372713, v97
	v_mul_f32_e32 v108, v97, v108
	v_fma_f32 v108, v97, v108, v97
	v_mul_f32_e32 v108, 0x3fcc422a, v108
	v_mul_f32_e32 v108, 0xbfb8aa3b, v108
	v_exp_f32_e32 v113, v108
	v_cvt_f32_f16_e32 v108, v151
	v_add_f32_e32 v112, 1.0, v112
	v_rcp_f32_e32 v112, v112
	v_add_f32_e32 v113, 1.0, v113
	v_pk_fma_f32 v[98:99], v[66:67], v[108:109], v[98:99]
	v_rcp_f32_e32 v113, v113
	v_mul_f32_e32 v108, 0x3d372713, v98
	v_mul_f32_e32 v109, 0x3d372713, v99
	v_mul_f32_e32 v108, v98, v108
	v_mul_f32_e32 v109, v99, v109
	v_fma_f32 v108, v98, v108, v98
	v_fma_f32 v109, v99, v109, v99
	v_mul_f32_e32 v108, 0x3fcc422a, v108
	v_mul_f32_e32 v109, 0x3fcc422a, v109
	v_mul_f32_e32 v108, 0xbfb8aa3b, v108
	v_mul_f32_e32 v109, 0xbfb8aa3b, v109
	v_exp_f32_e32 v108, v108
	v_exp_f32_e32 v109, v109
	v_rcp_f32_e32 v110, v110
	v_rcp_f32_e32 v111, v111
	v_add_f32_e32 v108, 1.0, v108
	v_add_f32_e32 v109, 1.0, v109
	v_rcp_f32_e32 v108, v108
	v_rcp_f32_e32 v109, v109
	v_lshlrev_b64 v[104:105], 17, v[194:195]
	v_lshl_add_u64 v[104:105], s[48:49], 0, v[104:105]
	v_pk_mul_f32 v[100:101], v[100:101], v[106:107]
	v_pk_mul_f32 v[108:109], v[98:99], v[108:109]
	v_cvt_f32_f16_e32 v98, v144
	v_cvt_f32_f16_sdwa v99, v144 dst_sel:DWORD dst_unused:UNUSED_PAD src0_sel:WORD_1
	v_pk_mul_f32 v[106:107], v[96:97], v[112:113]
	v_lshl_add_u64 v[96:97], v[104:105], 0, v[128:129]
	v_pk_mul_f32 v[102:103], v[102:103], v[110:111]
	v_pk_fma_f32 v[92:93], v[72:73], v[98:99], v[92:93]
	v_lshl_add_u64 v[96:97], v[96:97], 0, s[10:11]
	v_mul_f32_e32 v98, 0x3d372713, v92
	v_mul_f32_e32 v98, v92, v98
	v_fma_f32 v98, v92, v98, v92
	v_mul_f32_e32 v98, 0x3fcc422a, v98
	v_mul_f32_e32 v98, 0xbfb8aa3b, v98
	v_lshl_add_u64 v[110:111], v[96:97], 0, v[186:187]
	v_cvt_pk_f16_f32 v96, v100, v101
	v_cvt_pk_f16_f32 v97, v102, v103
	v_exp_f32_e32 v100, v98
	v_cvt_pk_f16_f32 v98, v106, v107
	v_cvt_pk_f16_f32 v99, v108, v109
	global_store_dwordx4 v[110:111], v[96:99], off
	v_add_u32_e32 v110, 0x80, v188
	v_ashrrev_i32_e32 v111, 31, v110
	v_mul_f32_e32 v96, 0x3d372713, v93
	v_mul_f32_e32 v96, v93, v96
	v_fma_f32 v99, v93, v96, v93
	v_cvt_f32_f16_e32 v96, v145
	v_cvt_f32_f16_sdwa v97, v145 dst_sel:DWORD dst_unused:UNUSED_PAD src0_sel:WORD_1
	v_add_f32_e32 v98, 1.0, v100
	v_mul_f32_e32 v99, 0x3fcc422a, v99
	v_mul_f32_e32 v99, 0xbfb8aa3b, v99
	v_pk_fma_f32 v[94:95], v[74:75], v[96:97], v[94:95]
	v_exp_f32_e32 v99, v99
	v_mul_f32_e32 v96, 0x3d372713, v94
	v_mul_f32_e32 v96, v94, v96
	v_fma_f32 v96, v94, v96, v94
	v_mul_f32_e32 v96, 0x3fcc422a, v96
	v_mul_f32_e32 v96, 0xbfb8aa3b, v96
	v_exp_f32_e32 v100, v96
	v_rcp_f32_e32 v96, v98
	v_mul_f32_e32 v98, 0x3d372713, v95
	v_mul_f32_e32 v98, v95, v98
	v_fma_f32 v98, v95, v98, v95
	v_mul_f32_e32 v98, 0x3fcc422a, v98
	v_mul_f32_e32 v98, 0xbfb8aa3b, v98
	v_add_f32_e32 v97, 1.0, v99
	v_exp_f32_e32 v101, v98
	v_cvt_f32_f16_e32 v98, v146
	v_cvt_f32_f16_sdwa v99, v146 dst_sel:DWORD dst_unused:UNUSED_PAD src0_sel:WORD_1
	v_rcp_f32_e32 v97, v97
	v_add_f32_e32 v100, 1.0, v100
	v_add_f32_e32 v101, 1.0, v101
	v_pk_fma_f32 v[88:89], v[64:65], v[98:99], v[88:89]
	v_cvt_f32_f16_sdwa v99, v147 dst_sel:DWORD dst_unused:UNUSED_PAD src0_sel:WORD_1
	v_mul_f32_e32 v98, 0x3d372713, v88
	v_mul_f32_e32 v98, v88, v98
	v_fma_f32 v98, v88, v98, v88
	v_mul_f32_e32 v98, 0x3fcc422a, v98
	v_mul_f32_e32 v98, 0xbfb8aa3b, v98
	v_exp_f32_e32 v102, v98
	v_mul_f32_e32 v98, 0x3d372713, v89
	v_mul_f32_e32 v98, v89, v98
	v_fma_f32 v98, v89, v98, v89
	v_mul_f32_e32 v98, 0x3fcc422a, v98
	v_mul_f32_e32 v98, 0xbfb8aa3b, v98
	v_exp_f32_e32 v103, v98
	v_cvt_f32_f16_e32 v98, v147
	v_add_f32_e32 v102, 1.0, v102
	v_rcp_f32_e32 v102, v102
	v_add_f32_e32 v103, 1.0, v103
	v_pk_fma_f32 v[90:91], v[66:67], v[98:99], v[90:91]
	v_rcp_f32_e32 v103, v103
	v_mul_f32_e32 v98, 0x3d372713, v90
	v_mul_f32_e32 v99, 0x3d372713, v91
	v_mul_f32_e32 v98, v90, v98
	v_mul_f32_e32 v99, v91, v99
	v_fma_f32 v98, v90, v98, v90
	v_fma_f32 v99, v91, v99, v91
	v_mul_f32_e32 v98, 0x3fcc422a, v98
	v_mul_f32_e32 v99, 0x3fcc422a, v99
	v_mul_f32_e32 v98, 0xbfb8aa3b, v98
	v_mul_f32_e32 v99, 0xbfb8aa3b, v99
	v_exp_f32_e32 v98, v98
	v_exp_f32_e32 v99, v99
	v_rcp_f32_e32 v100, v100
	v_rcp_f32_e32 v101, v101
	v_add_f32_e32 v98, 1.0, v98
	v_add_f32_e32 v99, 1.0, v99
	v_pk_mul_f32 v[92:93], v[92:93], v[96:97]
	v_pk_mul_f32 v[96:97], v[88:89], v[102:103]
	v_lshl_add_u64 v[88:89], v[104:105], 0, v[120:121]
	v_rcp_f32_e32 v98, v98
	v_rcp_f32_e32 v99, v99
	v_lshl_add_u64 v[88:89], v[88:89], 0, s[10:11]
	v_pk_mul_f32 v[94:95], v[94:95], v[100:101]
	v_lshl_add_u64 v[100:101], v[88:89], 0, v[186:187]
	v_cvt_pk_f16_f32 v88, v92, v93
	v_cvt_f32_f16_e32 v92, v140
	v_cvt_f32_f16_sdwa v93, v140 dst_sel:DWORD dst_unused:UNUSED_PAD src0_sel:WORD_1
	v_pk_mul_f32 v[98:99], v[90:91], v[98:99]
	v_cvt_pk_f16_f32 v89, v94, v95
	v_cvt_pk_f16_f32 v90, v96, v97
	v_cvt_pk_f16_f32 v91, v98, v99
	v_pk_fma_f32 v[84:85], v[72:73], v[92:93], v[84:85]
	global_store_dwordx4 v[100:101], v[88:91], off
	v_mul_f32_e32 v92, 0x3d372713, v84
	v_mul_f32_e32 v92, v84, v92
	v_mul_f32_e32 v90, 0x3d372713, v85
	v_mul_f32_e32 v90, v85, v90
	v_fma_f32 v93, v85, v90, v85
	v_cvt_f32_f16_e32 v90, v141
	v_cvt_f32_f16_sdwa v91, v141 dst_sel:DWORD dst_unused:UNUSED_PAD src0_sel:WORD_1
	v_fma_f32 v92, v84, v92, v84
	v_mul_f32_e32 v92, 0x3fcc422a, v92
	v_mul_f32_e32 v92, 0xbfb8aa3b, v92
	v_pk_fma_f32 v[86:87], v[74:75], v[90:91], v[86:87]
	v_exp_f32_e32 v92, v92
	v_mul_f32_e32 v90, 0x3d372713, v86
	v_mul_f32_e32 v90, v86, v90
	v_fma_f32 v90, v86, v90, v86
	v_mul_f32_e32 v90, 0x3fcc422a, v90
	v_add_f32_e32 v92, 1.0, v92
	v_mul_f32_e32 v93, 0x3fcc422a, v93
	v_mul_f32_e32 v90, 0xbfb8aa3b, v90
	v_mul_f32_e32 v93, 0xbfb8aa3b, v93
	v_exp_f32_e32 v94, v90
	v_rcp_f32_e32 v90, v92
	v_mul_f32_e32 v92, 0x3d372713, v87
	v_exp_f32_e32 v93, v93
	v_mul_f32_e32 v92, v87, v92
	v_fma_f32 v92, v87, v92, v87
	v_mul_f32_e32 v92, 0x3fcc422a, v92
	v_mul_f32_e32 v92, 0xbfb8aa3b, v92
	v_add_f32_e32 v91, 1.0, v93
	v_exp_f32_e32 v95, v92
	v_cvt_f32_f16_e32 v92, v142
	v_cvt_f32_f16_sdwa v93, v142 dst_sel:DWORD dst_unused:UNUSED_PAD src0_sel:WORD_1
	v_rcp_f32_e32 v91, v91
	v_add_f32_e32 v94, 1.0, v94
	v_add_f32_e32 v95, 1.0, v95
	v_pk_fma_f32 v[80:81], v[64:65], v[92:93], v[80:81]
	v_cvt_f32_f16_sdwa v93, v143 dst_sel:DWORD dst_unused:UNUSED_PAD src0_sel:WORD_1
	v_mul_f32_e32 v92, 0x3d372713, v80
	v_mul_f32_e32 v92, v80, v92
	v_fma_f32 v92, v80, v92, v80
	v_mul_f32_e32 v92, 0x3fcc422a, v92
	v_mul_f32_e32 v92, 0xbfb8aa3b, v92
	v_exp_f32_e32 v96, v92
	v_mul_f32_e32 v92, 0x3d372713, v81
	v_mul_f32_e32 v92, v81, v92
	v_fma_f32 v92, v81, v92, v81
	v_mul_f32_e32 v92, 0x3fcc422a, v92
	v_mul_f32_e32 v92, 0xbfb8aa3b, v92
	v_exp_f32_e32 v97, v92
	v_cvt_f32_f16_e32 v92, v143
	v_add_f32_e32 v96, 1.0, v96
	v_rcp_f32_e32 v96, v96
	v_add_f32_e32 v97, 1.0, v97
	v_pk_fma_f32 v[82:83], v[66:67], v[92:93], v[82:83]
	v_rcp_f32_e32 v97, v97
	v_mul_f32_e32 v92, 0x3d372713, v82
	v_mul_f32_e32 v93, 0x3d372713, v83
	v_mul_f32_e32 v92, v82, v92
	v_mul_f32_e32 v93, v83, v93
	v_fma_f32 v92, v82, v92, v82
	v_fma_f32 v93, v83, v93, v83
	v_mul_f32_e32 v92, 0x3fcc422a, v92
	v_mul_f32_e32 v93, 0x3fcc422a, v93
	v_mul_f32_e32 v92, 0xbfb8aa3b, v92
	v_mul_f32_e32 v93, 0xbfb8aa3b, v93
	v_exp_f32_e32 v92, v92
	v_exp_f32_e32 v93, v93
	v_rcp_f32_e32 v94, v94
	v_rcp_f32_e32 v95, v95
	v_add_f32_e32 v92, 1.0, v92
	v_add_f32_e32 v93, 1.0, v93
	v_rcp_f32_e32 v92, v92
	v_rcp_f32_e32 v93, v93
	v_lshlrev_b64 v[88:89], 17, v[192:193]
	v_lshl_add_u64 v[88:89], s[48:49], 0, v[88:89]
	v_pk_mul_f32 v[84:85], v[84:85], v[90:91]
	v_pk_mul_f32 v[92:93], v[82:83], v[92:93]
	v_cvt_f32_f16_e32 v82, v136
	v_cvt_f32_f16_sdwa v83, v136 dst_sel:DWORD dst_unused:UNUSED_PAD src0_sel:WORD_1
	v_pk_mul_f32 v[90:91], v[80:81], v[96:97]
	v_lshl_add_u64 v[80:81], v[88:89], 0, v[128:129]
	v_pk_mul_f32 v[86:87], v[86:87], v[94:95]
	v_pk_fma_f32 v[76:77], v[72:73], v[82:83], v[76:77]
	v_lshl_add_u64 v[80:81], v[80:81], 0, s[10:11]
	v_mul_f32_e32 v82, 0x3d372713, v76
	v_mul_f32_e32 v82, v76, v82
	v_fma_f32 v82, v76, v82, v76
	v_mul_f32_e32 v82, 0x3fcc422a, v82
	v_mul_f32_e32 v82, 0xbfb8aa3b, v82
	v_lshl_add_u64 v[94:95], v[80:81], 0, v[186:187]
	v_cvt_pk_f16_f32 v80, v84, v85
	v_cvt_pk_f16_f32 v81, v86, v87
	v_exp_f32_e32 v84, v82
	v_cvt_pk_f16_f32 v82, v90, v91
	v_cvt_pk_f16_f32 v83, v92, v93
	global_store_dwordx4 v[94:95], v[80:83], off
	v_add_u32_e32 v104, 0x90, v188
	v_add_u32_e32 v102, 0xa0, v188
	v_mul_f32_e32 v80, 0x3d372713, v77
	v_mul_f32_e32 v80, v77, v80
	v_fma_f32 v83, v77, v80, v77
	v_cvt_f32_f16_e32 v80, v137
	v_cvt_f32_f16_sdwa v81, v137 dst_sel:DWORD dst_unused:UNUSED_PAD src0_sel:WORD_1
	v_add_f32_e32 v82, 1.0, v84
	v_mul_f32_e32 v83, 0x3fcc422a, v83
	v_mul_f32_e32 v83, 0xbfb8aa3b, v83
	v_pk_fma_f32 v[78:79], v[74:75], v[80:81], v[78:79]
	v_exp_f32_e32 v83, v83
	v_mul_f32_e32 v80, 0x3d372713, v78
	v_mul_f32_e32 v80, v78, v80
	v_fma_f32 v80, v78, v80, v78
	v_mul_f32_e32 v80, 0x3fcc422a, v80
	v_mul_f32_e32 v80, 0xbfb8aa3b, v80
	v_exp_f32_e32 v84, v80
	v_rcp_f32_e32 v80, v82
	v_mul_f32_e32 v82, 0x3d372713, v79
	v_mul_f32_e32 v82, v79, v82
	v_fma_f32 v82, v79, v82, v79
	v_mul_f32_e32 v82, 0x3fcc422a, v82
	v_mul_f32_e32 v82, 0xbfb8aa3b, v82
	v_add_f32_e32 v81, 1.0, v83
	v_exp_f32_e32 v85, v82
	v_cvt_f32_f16_e32 v82, v138
	v_cvt_f32_f16_sdwa v83, v138 dst_sel:DWORD dst_unused:UNUSED_PAD src0_sel:WORD_1
	v_rcp_f32_e32 v81, v81
	v_add_f32_e32 v84, 1.0, v84
	v_add_f32_e32 v85, 1.0, v85
	v_pk_fma_f32 v[68:69], v[64:65], v[82:83], v[68:69]
	v_cvt_f32_f16_sdwa v83, v139 dst_sel:DWORD dst_unused:UNUSED_PAD src0_sel:WORD_1
	v_mul_f32_e32 v82, 0x3d372713, v68
	v_mul_f32_e32 v82, v68, v82
	v_fma_f32 v82, v68, v82, v68
	v_mul_f32_e32 v82, 0x3fcc422a, v82
	v_mul_f32_e32 v82, 0xbfb8aa3b, v82
	v_exp_f32_e32 v86, v82
	v_mul_f32_e32 v82, 0x3d372713, v69
	v_mul_f32_e32 v82, v69, v82
	v_fma_f32 v82, v69, v82, v69
	v_mul_f32_e32 v82, 0x3fcc422a, v82
	v_mul_f32_e32 v82, 0xbfb8aa3b, v82
	v_exp_f32_e32 v87, v82
	v_cvt_f32_f16_e32 v82, v139
	v_add_f32_e32 v86, 1.0, v86
	v_rcp_f32_e32 v86, v86
	v_add_f32_e32 v87, 1.0, v87
	v_pk_fma_f32 v[70:71], v[66:67], v[82:83], v[70:71]
	v_rcp_f32_e32 v87, v87
	v_mul_f32_e32 v82, 0x3d372713, v70
	v_mul_f32_e32 v83, 0x3d372713, v71
	v_mul_f32_e32 v82, v70, v82
	v_mul_f32_e32 v83, v71, v83
	v_fma_f32 v82, v70, v82, v70
	v_fma_f32 v83, v71, v83, v71
	v_mul_f32_e32 v82, 0x3fcc422a, v82
	v_mul_f32_e32 v83, 0x3fcc422a, v83
	v_mul_f32_e32 v82, 0xbfb8aa3b, v82
	v_mul_f32_e32 v83, 0xbfb8aa3b, v83
	v_exp_f32_e32 v82, v82
	v_exp_f32_e32 v83, v83
	v_rcp_f32_e32 v84, v84
	v_rcp_f32_e32 v85, v85
	v_add_f32_e32 v82, 1.0, v82
	v_add_f32_e32 v83, 1.0, v83
	v_rcp_f32_e32 v82, v82
	v_rcp_f32_e32 v83, v83
	v_pk_mul_f32 v[76:77], v[76:77], v[80:81]
	v_pk_mul_f32 v[80:81], v[68:69], v[86:87]
	v_lshl_add_u64 v[68:69], v[88:89], 0, v[120:121]
	v_pk_mul_f32 v[78:79], v[78:79], v[84:85]
	v_pk_mul_f32 v[82:83], v[70:71], v[82:83]
	v_lshl_add_u64 v[68:69], v[68:69], 0, s[10:11]
	v_lshl_add_u64 v[84:85], v[68:69], 0, v[186:187]
	v_cvt_pk_f16_f32 v68, v76, v77
	v_cvt_pk_f16_f32 v69, v78, v79
	v_cvt_pk_f16_f32 v70, v80, v81
	v_cvt_pk_f16_f32 v71, v82, v83
	global_store_dwordx4 v[84:85], v[68:71], off
	v_add_u32_e32 v100, 0xb0, v188
	v_ashrrev_i32_e32 v105, 31, v104
	v_mad_i64_i32 v[68:69], s[16:17], v110, s52, v[190:191]
	v_lshl_add_u64 v[68:69], v[68:69], 0, s[14:15]
	v_lshl_add_u64 v[68:69], v[68:69], 0, v[176:177]
	global_load_dwordx4 v[106:109], v[68:69], off offset:256
	global_load_dwordx4 v[96:99], v[68:69], off offset:512
	v_mad_i64_i32 v[68:69], s[16:17], v104, s52, v[190:191]
	v_lshl_add_u64 v[68:69], v[68:69], 0, s[14:15]
	v_lshl_add_u64 v[68:69], v[68:69], 0, v[176:177]
	global_load_dwordx4 v[92:95], v[68:69], off offset:256
	global_load_dwordx4 v[88:91], v[68:69], off offset:512
	v_mad_i64_i32 v[68:69], s[16:17], v102, s52, v[190:191]
	v_lshl_add_u64 v[68:69], v[68:69], 0, s[14:15]
	v_lshl_add_u64 v[68:69], v[68:69], 0, v[176:177]
	global_load_dwordx4 v[84:87], v[68:69], off offset:256
	global_load_dwordx4 v[80:83], v[68:69], off offset:512
	v_lshlrev_b64 v[110:111], 17, v[110:111]
	v_lshl_add_u64 v[110:111], s[48:49], 0, v[110:111]
	v_mad_i64_i32 v[70:71], s[16:17], v100, s52, v[190:191]
	v_lshl_add_u64 v[70:71], v[70:71], 0, s[14:15]
	v_lshl_add_u64 v[70:71], v[70:71], 0, v[176:177]
	v_ashrrev_i32_e32 v103, 31, v102
	v_ashrrev_i32_e32 v101, 31, v100
	s_waitcnt vmcnt(0) lgkmcnt(0)
	v_cvt_f32_f16_e32 v68, v106
	v_cvt_f32_f16_sdwa v69, v106 dst_sel:DWORD dst_unused:UNUSED_PAD src0_sel:WORD_1
	v_pk_fma_f32 v[60:61], v[72:73], v[68:69], v[60:61]
	s_nop 0
	v_mul_f32_e32 v68, 0x3d372713, v60
	v_mul_f32_e32 v68, v60, v68
	v_fma_f32 v68, v60, v68, v60
	v_mul_f32_e32 v68, 0x3fcc422a, v68
	v_mul_f32_e32 v68, 0xbfb8aa3b, v68
	v_exp_f32_e32 v106, v68
	global_load_dwordx4 v[76:79], v[70:71], off offset:256
	s_nop 0
	global_load_dwordx4 v[68:71], v[70:71], off offset:512
	v_add_f32_e32 v112, 1.0, v106
	v_mul_f32_e32 v106, 0x3d372713, v61
	v_mul_f32_e32 v106, v61, v106
	v_fma_f32 v113, v61, v106, v61
	v_cvt_f32_f16_e32 v106, v107
	v_cvt_f32_f16_sdwa v107, v107 dst_sel:DWORD dst_unused:UNUSED_PAD src0_sel:WORD_1
	v_mul_f32_e32 v113, 0x3fcc422a, v113
	v_mul_f32_e32 v113, 0xbfb8aa3b, v113
	v_exp_f32_e32 v113, v113
	v_pk_fma_f32 v[62:63], v[74:75], v[106:107], v[62:63]
	v_add_f32_e32 v107, 1.0, v113
	v_mul_f32_e32 v106, 0x3d372713, v62
	v_mul_f32_e32 v106, v62, v106
	v_fma_f32 v106, v62, v106, v62
	v_mul_f32_e32 v106, 0x3fcc422a, v106
	v_mul_f32_e32 v106, 0xbfb8aa3b, v106
	v_exp_f32_e32 v114, v106
	v_rcp_f32_e32 v106, v112
	v_mul_f32_e32 v112, 0x3d372713, v63
	v_mul_f32_e32 v112, v63, v112
	v_fma_f32 v112, v63, v112, v63
	v_mul_f32_e32 v112, 0x3fcc422a, v112
	v_mul_f32_e32 v112, 0xbfb8aa3b, v112
	v_exp_f32_e32 v115, v112
	v_cvt_f32_f16_e32 v112, v108
	v_cvt_f32_f16_sdwa v113, v108 dst_sel:DWORD dst_unused:UNUSED_PAD src0_sel:WORD_1
	v_rcp_f32_e32 v107, v107
	v_add_f32_e32 v108, 1.0, v115
	v_rcp_f32_e32 v115, v108
	v_pk_fma_f32 v[56:57], v[64:65], v[112:113], v[56:57]
	v_add_f32_e32 v114, 1.0, v114
	v_mul_f32_e32 v108, 0x3d372713, v56
	v_mul_f32_e32 v108, v56, v108
	v_fma_f32 v108, v56, v108, v56
	v_mul_f32_e32 v108, 0x3fcc422a, v108
	v_mul_f32_e32 v108, 0xbfb8aa3b, v108
	v_exp_f32_e32 v112, v108
	v_mul_f32_e32 v108, 0x3d372713, v57
	v_mul_f32_e32 v108, v57, v108
	v_fma_f32 v108, v57, v108, v57
	v_mul_f32_e32 v108, 0x3fcc422a, v108
	v_mul_f32_e32 v108, 0xbfb8aa3b, v108
	v_exp_f32_e32 v113, v108
	v_cvt_f32_f16_e32 v108, v109
	v_cvt_f32_f16_sdwa v109, v109 dst_sel:DWORD dst_unused:UNUSED_PAD src0_sel:WORD_1
	v_add_f32_e32 v112, 1.0, v112
	v_add_f32_e32 v113, 1.0, v113
	v_rcp_f32_e32 v112, v112
	v_pk_fma_f32 v[58:59], v[66:67], v[108:109], v[58:59]
	v_rcp_f32_e32 v113, v113
	v_mul_f32_e32 v108, 0x3d372713, v58
	v_mul_f32_e32 v109, 0x3d372713, v59
	v_mul_f32_e32 v108, v58, v108
	v_mul_f32_e32 v109, v59, v109
	v_fma_f32 v108, v58, v108, v58
	v_fma_f32 v109, v59, v109, v59
	v_mul_f32_e32 v108, 0x3fcc422a, v108
	v_mul_f32_e32 v109, 0x3fcc422a, v109
	v_mul_f32_e32 v108, 0xbfb8aa3b, v108
	v_mul_f32_e32 v109, 0xbfb8aa3b, v109
	v_exp_f32_e32 v108, v108
	v_exp_f32_e32 v109, v109
	v_rcp_f32_e32 v114, v114
	v_pk_mul_f32 v[60:61], v[60:61], v[106:107]
	v_add_f32_e32 v108, 1.0, v108
	v_add_f32_e32 v109, 1.0, v109
	v_rcp_f32_e32 v108, v108
	v_rcp_f32_e32 v109, v109
	v_pk_mul_f32 v[106:107], v[56:57], v[112:113]
	v_lshl_add_u64 v[56:57], v[110:111], 0, v[128:129]
	v_pk_mul_f32 v[62:63], v[62:63], v[114:115]
	v_pk_mul_f32 v[108:109], v[58:59], v[108:109]
	v_cvt_f32_f16_e32 v58, v96
	v_cvt_f32_f16_sdwa v59, v96 dst_sel:DWORD dst_unused:UNUSED_PAD src0_sel:WORD_1
	v_lshl_add_u64 v[56:57], v[56:57], 0, s[10:11]
	v_lshl_add_u64 v[112:113], v[56:57], 0, v[186:187]
	v_cvt_pk_f16_f32 v56, v60, v61
	v_pk_fma_f32 v[52:53], v[72:73], v[58:59], v[52:53]
	v_cvt_pk_f16_f32 v57, v62, v63
	v_mul_f32_e32 v58, 0x3d372713, v52
	v_mul_f32_e32 v58, v52, v58
	v_fma_f32 v58, v52, v58, v52
	v_mul_f32_e32 v58, 0x3fcc422a, v58
	v_mul_f32_e32 v58, 0xbfb8aa3b, v58
	v_exp_f32_e32 v60, v58
	v_cvt_pk_f16_f32 v58, v106, v107
	v_cvt_pk_f16_f32 v59, v108, v109
	global_store_dwordx4 v[112:113], v[56:59], off
	s_nop 1
	v_mul_f32_e32 v56, 0x3d372713, v53
	v_mul_f32_e32 v56, v53, v56
	v_fma_f32 v59, v53, v56, v53
	v_cvt_f32_f16_e32 v56, v97
	v_cvt_f32_f16_sdwa v57, v97 dst_sel:DWORD dst_unused:UNUSED_PAD src0_sel:WORD_1
	v_add_f32_e32 v58, 1.0, v60
	v_mul_f32_e32 v59, 0x3fcc422a, v59
	v_mul_f32_e32 v59, 0xbfb8aa3b, v59
	v_pk_fma_f32 v[54:55], v[74:75], v[56:57], v[54:55]
	v_exp_f32_e32 v59, v59
	v_mul_f32_e32 v56, 0x3d372713, v54
	v_mul_f32_e32 v56, v54, v56
	v_fma_f32 v56, v54, v56, v54
	v_mul_f32_e32 v56, 0x3fcc422a, v56
	v_mul_f32_e32 v56, 0xbfb8aa3b, v56
	v_exp_f32_e32 v60, v56
	v_rcp_f32_e32 v56, v58
	v_mul_f32_e32 v58, 0x3d372713, v55
	v_mul_f32_e32 v58, v55, v58
	v_fma_f32 v58, v55, v58, v55
	v_mul_f32_e32 v58, 0x3fcc422a, v58
	v_mul_f32_e32 v58, 0xbfb8aa3b, v58
	v_add_f32_e32 v57, 1.0, v59
	v_exp_f32_e32 v61, v58
	v_cvt_f32_f16_e32 v58, v98
	v_cvt_f32_f16_sdwa v59, v98 dst_sel:DWORD dst_unused:UNUSED_PAD src0_sel:WORD_1
	v_rcp_f32_e32 v57, v57
	v_add_f32_e32 v60, 1.0, v60
	v_add_f32_e32 v61, 1.0, v61
	v_pk_fma_f32 v[48:49], v[64:65], v[58:59], v[48:49]
	v_cvt_f32_f16_sdwa v59, v99 dst_sel:DWORD dst_unused:UNUSED_PAD src0_sel:WORD_1
	v_mul_f32_e32 v58, 0x3d372713, v48
	v_mul_f32_e32 v58, v48, v58
	v_fma_f32 v58, v48, v58, v48
	v_mul_f32_e32 v58, 0x3fcc422a, v58
	v_mul_f32_e32 v58, 0xbfb8aa3b, v58
	v_exp_f32_e32 v62, v58
	v_mul_f32_e32 v58, 0x3d372713, v49
	v_mul_f32_e32 v58, v49, v58
	v_fma_f32 v58, v49, v58, v49
	v_mul_f32_e32 v58, 0x3fcc422a, v58
	v_mul_f32_e32 v58, 0xbfb8aa3b, v58
	v_exp_f32_e32 v63, v58
	v_cvt_f32_f16_e32 v58, v99
	v_add_f32_e32 v62, 1.0, v62
	v_rcp_f32_e32 v62, v62
	v_add_f32_e32 v63, 1.0, v63
	v_pk_fma_f32 v[50:51], v[66:67], v[58:59], v[50:51]
	v_rcp_f32_e32 v63, v63
	v_mul_f32_e32 v58, 0x3d372713, v50
	v_mul_f32_e32 v59, 0x3d372713, v51
	v_mul_f32_e32 v58, v50, v58
	v_mul_f32_e32 v59, v51, v59
	v_fma_f32 v58, v50, v58, v50
	v_fma_f32 v59, v51, v59, v51
	v_mul_f32_e32 v58, 0x3fcc422a, v58
	v_mul_f32_e32 v59, 0x3fcc422a, v59
	v_mul_f32_e32 v58, 0xbfb8aa3b, v58
	v_mul_f32_e32 v59, 0xbfb8aa3b, v59
	v_exp_f32_e32 v58, v58
	v_exp_f32_e32 v59, v59
	v_rcp_f32_e32 v60, v60
	v_rcp_f32_e32 v61, v61
	v_add_f32_e32 v58, 1.0, v58
	v_add_f32_e32 v59, 1.0, v59
	v_pk_mul_f32 v[52:53], v[52:53], v[56:57]
	v_pk_mul_f32 v[56:57], v[48:49], v[62:63]
	v_lshl_add_u64 v[48:49], v[110:111], 0, v[120:121]
	v_rcp_f32_e32 v58, v58
	v_rcp_f32_e32 v59, v59
	v_lshl_add_u64 v[48:49], v[48:49], 0, s[10:11]
	v_pk_mul_f32 v[54:55], v[54:55], v[60:61]
	v_lshl_add_u64 v[60:61], v[48:49], 0, v[186:187]
	v_cvt_pk_f16_f32 v48, v52, v53
	v_cvt_f32_f16_e32 v52, v92
	v_cvt_f32_f16_sdwa v53, v92 dst_sel:DWORD dst_unused:UNUSED_PAD src0_sel:WORD_1
	v_pk_mul_f32 v[58:59], v[50:51], v[58:59]
	v_cvt_pk_f16_f32 v49, v54, v55
	v_cvt_pk_f16_f32 v50, v56, v57
	v_cvt_pk_f16_f32 v51, v58, v59
	v_pk_fma_f32 v[44:45], v[72:73], v[52:53], v[44:45]
	global_store_dwordx4 v[60:61], v[48:51], off
	v_mul_f32_e32 v52, 0x3d372713, v44
	v_mul_f32_e32 v52, v44, v52
	v_mul_f32_e32 v50, 0x3d372713, v45
	v_mul_f32_e32 v50, v45, v50
	v_fma_f32 v53, v45, v50, v45
	v_cvt_f32_f16_e32 v50, v93
	v_cvt_f32_f16_sdwa v51, v93 dst_sel:DWORD dst_unused:UNUSED_PAD src0_sel:WORD_1
	v_fma_f32 v52, v44, v52, v44
	v_mul_f32_e32 v52, 0x3fcc422a, v52
	v_mul_f32_e32 v52, 0xbfb8aa3b, v52
	v_pk_fma_f32 v[46:47], v[74:75], v[50:51], v[46:47]
	v_exp_f32_e32 v52, v52
	v_mul_f32_e32 v50, 0x3d372713, v46
	v_mul_f32_e32 v50, v46, v50
	v_fma_f32 v50, v46, v50, v46
	v_mul_f32_e32 v50, 0x3fcc422a, v50
	v_add_f32_e32 v52, 1.0, v52
	v_mul_f32_e32 v53, 0x3fcc422a, v53
	v_mul_f32_e32 v50, 0xbfb8aa3b, v50
	v_mul_f32_e32 v53, 0xbfb8aa3b, v53
	v_exp_f32_e32 v54, v50
	v_rcp_f32_e32 v50, v52
	v_mul_f32_e32 v52, 0x3d372713, v47
	v_exp_f32_e32 v53, v53
	v_mul_f32_e32 v52, v47, v52
	v_fma_f32 v52, v47, v52, v47
	v_mul_f32_e32 v52, 0x3fcc422a, v52
	v_mul_f32_e32 v52, 0xbfb8aa3b, v52
	v_add_f32_e32 v51, 1.0, v53
	v_exp_f32_e32 v55, v52
	v_cvt_f32_f16_e32 v52, v94
	v_cvt_f32_f16_sdwa v53, v94 dst_sel:DWORD dst_unused:UNUSED_PAD src0_sel:WORD_1
	v_rcp_f32_e32 v51, v51
	v_add_f32_e32 v54, 1.0, v54
	v_add_f32_e32 v55, 1.0, v55
	v_pk_fma_f32 v[40:41], v[64:65], v[52:53], v[40:41]
	v_cvt_f32_f16_sdwa v53, v95 dst_sel:DWORD dst_unused:UNUSED_PAD src0_sel:WORD_1
	v_mul_f32_e32 v52, 0x3d372713, v40
	v_mul_f32_e32 v52, v40, v52
	v_fma_f32 v52, v40, v52, v40
	v_mul_f32_e32 v52, 0x3fcc422a, v52
	v_mul_f32_e32 v52, 0xbfb8aa3b, v52
	v_exp_f32_e32 v56, v52
	v_mul_f32_e32 v52, 0x3d372713, v41
	v_mul_f32_e32 v52, v41, v52
	v_fma_f32 v52, v41, v52, v41
	v_mul_f32_e32 v52, 0x3fcc422a, v52
	v_mul_f32_e32 v52, 0xbfb8aa3b, v52
	v_exp_f32_e32 v57, v52
	v_cvt_f32_f16_e32 v52, v95
	v_add_f32_e32 v56, 1.0, v56
	v_rcp_f32_e32 v56, v56
	v_add_f32_e32 v57, 1.0, v57
	v_pk_fma_f32 v[42:43], v[66:67], v[52:53], v[42:43]
	v_rcp_f32_e32 v57, v57
	v_mul_f32_e32 v52, 0x3d372713, v42
	v_mul_f32_e32 v53, 0x3d372713, v43
	v_mul_f32_e32 v52, v42, v52
	v_mul_f32_e32 v53, v43, v53
	v_fma_f32 v52, v42, v52, v42
	v_fma_f32 v53, v43, v53, v43
	v_mul_f32_e32 v52, 0x3fcc422a, v52
	v_mul_f32_e32 v53, 0x3fcc422a, v53
	v_mul_f32_e32 v52, 0xbfb8aa3b, v52
	v_mul_f32_e32 v53, 0xbfb8aa3b, v53
	v_exp_f32_e32 v52, v52
	v_exp_f32_e32 v53, v53
	v_rcp_f32_e32 v54, v54
	v_rcp_f32_e32 v55, v55
	v_add_f32_e32 v52, 1.0, v52
	v_add_f32_e32 v53, 1.0, v53
	v_rcp_f32_e32 v52, v52
	v_rcp_f32_e32 v53, v53
	v_lshlrev_b64 v[48:49], 17, v[104:105]
	v_lshl_add_u64 v[48:49], s[48:49], 0, v[48:49]
	v_pk_mul_f32 v[44:45], v[44:45], v[50:51]
	v_pk_mul_f32 v[52:53], v[42:43], v[52:53]
	v_cvt_f32_f16_e32 v42, v88
	v_cvt_f32_f16_sdwa v43, v88 dst_sel:DWORD dst_unused:UNUSED_PAD src0_sel:WORD_1
	v_pk_mul_f32 v[50:51], v[40:41], v[56:57]
	v_lshl_add_u64 v[40:41], v[48:49], 0, v[128:129]
	v_pk_mul_f32 v[46:47], v[46:47], v[54:55]
	v_pk_fma_f32 v[36:37], v[72:73], v[42:43], v[36:37]
	v_lshl_add_u64 v[40:41], v[40:41], 0, s[10:11]
	v_mul_f32_e32 v42, 0x3d372713, v36
	v_mul_f32_e32 v42, v36, v42
	v_fma_f32 v42, v36, v42, v36
	v_mul_f32_e32 v42, 0x3fcc422a, v42
	v_mul_f32_e32 v42, 0xbfb8aa3b, v42
	v_lshl_add_u64 v[54:55], v[40:41], 0, v[186:187]
	v_cvt_pk_f16_f32 v40, v44, v45
	v_cvt_pk_f16_f32 v41, v46, v47
	v_exp_f32_e32 v44, v42
	v_cvt_pk_f16_f32 v42, v50, v51
	v_cvt_pk_f16_f32 v43, v52, v53
	global_store_dwordx4 v[54:55], v[40:43], off
	s_nop 1
	v_mul_f32_e32 v40, 0x3d372713, v37
	v_mul_f32_e32 v40, v37, v40
	v_fma_f32 v43, v37, v40, v37
	v_cvt_f32_f16_e32 v40, v89
	v_cvt_f32_f16_sdwa v41, v89 dst_sel:DWORD dst_unused:UNUSED_PAD src0_sel:WORD_1
	v_add_f32_e32 v42, 1.0, v44
	v_mul_f32_e32 v43, 0x3fcc422a, v43
	v_mul_f32_e32 v43, 0xbfb8aa3b, v43
	v_pk_fma_f32 v[38:39], v[74:75], v[40:41], v[38:39]
	v_exp_f32_e32 v43, v43
	v_mul_f32_e32 v40, 0x3d372713, v38
	v_mul_f32_e32 v40, v38, v40
	v_fma_f32 v40, v38, v40, v38
	v_mul_f32_e32 v40, 0x3fcc422a, v40
	v_mul_f32_e32 v40, 0xbfb8aa3b, v40
	v_exp_f32_e32 v44, v40
	v_rcp_f32_e32 v40, v42
	v_mul_f32_e32 v42, 0x3d372713, v39
	v_mul_f32_e32 v42, v39, v42
	v_fma_f32 v42, v39, v42, v39
	v_mul_f32_e32 v42, 0x3fcc422a, v42
	v_mul_f32_e32 v42, 0xbfb8aa3b, v42
	v_add_f32_e32 v41, 1.0, v43
	v_exp_f32_e32 v45, v42
	v_cvt_f32_f16_e32 v42, v90
	v_cvt_f32_f16_sdwa v43, v90 dst_sel:DWORD dst_unused:UNUSED_PAD src0_sel:WORD_1
	v_rcp_f32_e32 v41, v41
	v_add_f32_e32 v44, 1.0, v44
	v_add_f32_e32 v45, 1.0, v45
	v_pk_fma_f32 v[32:33], v[64:65], v[42:43], v[32:33]
	v_cvt_f32_f16_sdwa v43, v91 dst_sel:DWORD dst_unused:UNUSED_PAD src0_sel:WORD_1
	v_mul_f32_e32 v42, 0x3d372713, v32
	v_mul_f32_e32 v42, v32, v42
	v_fma_f32 v42, v32, v42, v32
	v_mul_f32_e32 v42, 0x3fcc422a, v42
	v_mul_f32_e32 v42, 0xbfb8aa3b, v42
	v_exp_f32_e32 v46, v42
	v_mul_f32_e32 v42, 0x3d372713, v33
	v_mul_f32_e32 v42, v33, v42
	v_fma_f32 v42, v33, v42, v33
	v_mul_f32_e32 v42, 0x3fcc422a, v42
	v_mul_f32_e32 v42, 0xbfb8aa3b, v42
	v_exp_f32_e32 v47, v42
	v_cvt_f32_f16_e32 v42, v91
	v_add_f32_e32 v46, 1.0, v46
	v_rcp_f32_e32 v46, v46
	v_add_f32_e32 v47, 1.0, v47
	v_pk_fma_f32 v[34:35], v[66:67], v[42:43], v[34:35]
	v_rcp_f32_e32 v47, v47
	v_mul_f32_e32 v42, 0x3d372713, v34
	v_mul_f32_e32 v43, 0x3d372713, v35
	v_mul_f32_e32 v42, v34, v42
	v_mul_f32_e32 v43, v35, v43
	v_fma_f32 v42, v34, v42, v34
	v_fma_f32 v43, v35, v43, v35
	v_mul_f32_e32 v42, 0x3fcc422a, v42
	v_mul_f32_e32 v43, 0x3fcc422a, v43
	v_mul_f32_e32 v42, 0xbfb8aa3b, v42
	v_mul_f32_e32 v43, 0xbfb8aa3b, v43
	v_exp_f32_e32 v42, v42
	v_exp_f32_e32 v43, v43
	v_rcp_f32_e32 v44, v44
	v_rcp_f32_e32 v45, v45
	v_add_f32_e32 v42, 1.0, v42
	v_add_f32_e32 v43, 1.0, v43
	v_pk_mul_f32 v[36:37], v[36:37], v[40:41]
	v_pk_mul_f32 v[40:41], v[32:33], v[46:47]
	v_lshl_add_u64 v[32:33], v[48:49], 0, v[120:121]
	v_rcp_f32_e32 v42, v42
	v_rcp_f32_e32 v43, v43
	v_lshl_add_u64 v[32:33], v[32:33], 0, s[10:11]
	v_pk_mul_f32 v[38:39], v[38:39], v[44:45]
	v_lshl_add_u64 v[44:45], v[32:33], 0, v[186:187]
	v_cvt_pk_f16_f32 v32, v36, v37
	v_cvt_f32_f16_e32 v36, v84
	v_cvt_f32_f16_sdwa v37, v84 dst_sel:DWORD dst_unused:UNUSED_PAD src0_sel:WORD_1
	v_pk_mul_f32 v[42:43], v[34:35], v[42:43]
	v_cvt_pk_f16_f32 v33, v38, v39
	v_cvt_pk_f16_f32 v34, v40, v41
	v_cvt_pk_f16_f32 v35, v42, v43
	v_pk_fma_f32 v[28:29], v[72:73], v[36:37], v[28:29]
	global_store_dwordx4 v[44:45], v[32:35], off
	v_mul_f32_e32 v36, 0x3d372713, v28
	v_mul_f32_e32 v36, v28, v36
	v_mul_f32_e32 v34, 0x3d372713, v29
	v_mul_f32_e32 v34, v29, v34
	v_fma_f32 v37, v29, v34, v29
	v_cvt_f32_f16_e32 v34, v85
	v_cvt_f32_f16_sdwa v35, v85 dst_sel:DWORD dst_unused:UNUSED_PAD src0_sel:WORD_1
	v_fma_f32 v36, v28, v36, v28
	v_mul_f32_e32 v36, 0x3fcc422a, v36
	v_mul_f32_e32 v36, 0xbfb8aa3b, v36
	v_pk_fma_f32 v[30:31], v[74:75], v[34:35], v[30:31]
	v_exp_f32_e32 v36, v36
	v_mul_f32_e32 v34, 0x3d372713, v30
	v_mul_f32_e32 v34, v30, v34
	v_fma_f32 v34, v30, v34, v30
	v_mul_f32_e32 v34, 0x3fcc422a, v34
	v_add_f32_e32 v36, 1.0, v36
	v_mul_f32_e32 v37, 0x3fcc422a, v37
	v_mul_f32_e32 v34, 0xbfb8aa3b, v34
	v_mul_f32_e32 v37, 0xbfb8aa3b, v37
	v_exp_f32_e32 v38, v34
	v_rcp_f32_e32 v34, v36
	v_mul_f32_e32 v36, 0x3d372713, v31
	v_exp_f32_e32 v37, v37
	v_mul_f32_e32 v36, v31, v36
	v_fma_f32 v36, v31, v36, v31
	v_mul_f32_e32 v36, 0x3fcc422a, v36
	v_mul_f32_e32 v36, 0xbfb8aa3b, v36
	v_add_f32_e32 v35, 1.0, v37
	v_exp_f32_e32 v39, v36
	v_cvt_f32_f16_e32 v36, v86
	v_cvt_f32_f16_sdwa v37, v86 dst_sel:DWORD dst_unused:UNUSED_PAD src0_sel:WORD_1
	v_rcp_f32_e32 v35, v35
	v_add_f32_e32 v38, 1.0, v38
	v_add_f32_e32 v39, 1.0, v39
	v_pk_fma_f32 v[24:25], v[64:65], v[36:37], v[24:25]
	v_cvt_f32_f16_sdwa v37, v87 dst_sel:DWORD dst_unused:UNUSED_PAD src0_sel:WORD_1
	v_mul_f32_e32 v36, 0x3d372713, v24
	v_mul_f32_e32 v36, v24, v36
	v_fma_f32 v36, v24, v36, v24
	v_mul_f32_e32 v36, 0x3fcc422a, v36
	v_mul_f32_e32 v36, 0xbfb8aa3b, v36
	v_exp_f32_e32 v40, v36
	v_mul_f32_e32 v36, 0x3d372713, v25
	v_mul_f32_e32 v36, v25, v36
	v_fma_f32 v36, v25, v36, v25
	v_mul_f32_e32 v36, 0x3fcc422a, v36
	v_mul_f32_e32 v36, 0xbfb8aa3b, v36
	v_exp_f32_e32 v41, v36
	v_cvt_f32_f16_e32 v36, v87
	v_add_f32_e32 v40, 1.0, v40
	v_rcp_f32_e32 v40, v40
	v_add_f32_e32 v41, 1.0, v41
	v_pk_fma_f32 v[26:27], v[66:67], v[36:37], v[26:27]
	v_rcp_f32_e32 v41, v41
	v_mul_f32_e32 v36, 0x3d372713, v26
	v_mul_f32_e32 v37, 0x3d372713, v27
	v_mul_f32_e32 v36, v26, v36
	v_mul_f32_e32 v37, v27, v37
	v_fma_f32 v36, v26, v36, v26
	v_fma_f32 v37, v27, v37, v27
	v_mul_f32_e32 v36, 0x3fcc422a, v36
	v_mul_f32_e32 v37, 0x3fcc422a, v37
	v_mul_f32_e32 v36, 0xbfb8aa3b, v36
	v_mul_f32_e32 v37, 0xbfb8aa3b, v37
	v_exp_f32_e32 v36, v36
	v_exp_f32_e32 v37, v37
	v_rcp_f32_e32 v38, v38
	v_rcp_f32_e32 v39, v39
	v_add_f32_e32 v36, 1.0, v36
	v_add_f32_e32 v37, 1.0, v37
	v_rcp_f32_e32 v36, v36
	v_rcp_f32_e32 v37, v37
	v_lshlrev_b64 v[32:33], 17, v[102:103]
	v_lshl_add_u64 v[32:33], s[48:49], 0, v[32:33]
	v_pk_mul_f32 v[28:29], v[28:29], v[34:35]
	v_pk_mul_f32 v[36:37], v[26:27], v[36:37]
	v_cvt_f32_f16_e32 v26, v80
	v_cvt_f32_f16_sdwa v27, v80 dst_sel:DWORD dst_unused:UNUSED_PAD src0_sel:WORD_1
	v_pk_mul_f32 v[34:35], v[24:25], v[40:41]
	v_lshl_add_u64 v[24:25], v[32:33], 0, v[128:129]
	v_pk_mul_f32 v[30:31], v[30:31], v[38:39]
	v_pk_fma_f32 v[20:21], v[72:73], v[26:27], v[20:21]
	v_lshl_add_u64 v[24:25], v[24:25], 0, s[10:11]
	v_mul_f32_e32 v26, 0x3d372713, v20
	v_mul_f32_e32 v26, v20, v26
	v_fma_f32 v26, v20, v26, v20
	v_mul_f32_e32 v26, 0x3fcc422a, v26
	v_mul_f32_e32 v26, 0xbfb8aa3b, v26
	v_lshl_add_u64 v[38:39], v[24:25], 0, v[186:187]
	v_cvt_pk_f16_f32 v24, v28, v29
	v_cvt_pk_f16_f32 v25, v30, v31
	v_exp_f32_e32 v28, v26
	v_cvt_pk_f16_f32 v26, v34, v35
	v_cvt_pk_f16_f32 v27, v36, v37
	global_store_dwordx4 v[38:39], v[24:27], off
	s_nop 1
	v_mul_f32_e32 v24, 0x3d372713, v21
	v_mul_f32_e32 v24, v21, v24
	v_fma_f32 v27, v21, v24, v21
	v_cvt_f32_f16_e32 v24, v81
	v_cvt_f32_f16_sdwa v25, v81 dst_sel:DWORD dst_unused:UNUSED_PAD src0_sel:WORD_1
	v_add_f32_e32 v26, 1.0, v28
	v_mul_f32_e32 v27, 0x3fcc422a, v27
	v_mul_f32_e32 v27, 0xbfb8aa3b, v27
	v_pk_fma_f32 v[22:23], v[74:75], v[24:25], v[22:23]
	v_exp_f32_e32 v27, v27
	v_mul_f32_e32 v24, 0x3d372713, v22
	v_mul_f32_e32 v24, v22, v24
	v_fma_f32 v24, v22, v24, v22
	v_mul_f32_e32 v24, 0x3fcc422a, v24
	v_mul_f32_e32 v24, 0xbfb8aa3b, v24
	v_exp_f32_e32 v28, v24
	v_rcp_f32_e32 v24, v26
	v_mul_f32_e32 v26, 0x3d372713, v23
	v_mul_f32_e32 v26, v23, v26
	v_fma_f32 v26, v23, v26, v23
	v_mul_f32_e32 v26, 0x3fcc422a, v26
	v_mul_f32_e32 v26, 0xbfb8aa3b, v26
	v_add_f32_e32 v25, 1.0, v27
	v_exp_f32_e32 v29, v26
	v_cvt_f32_f16_e32 v26, v82
	v_cvt_f32_f16_sdwa v27, v82 dst_sel:DWORD dst_unused:UNUSED_PAD src0_sel:WORD_1
	v_rcp_f32_e32 v25, v25
	v_add_f32_e32 v28, 1.0, v28
	v_add_f32_e32 v29, 1.0, v29
	v_pk_fma_f32 v[16:17], v[64:65], v[26:27], v[16:17]
	v_cvt_f32_f16_sdwa v27, v83 dst_sel:DWORD dst_unused:UNUSED_PAD src0_sel:WORD_1
	v_mul_f32_e32 v26, 0x3d372713, v16
	v_mul_f32_e32 v26, v16, v26
	v_fma_f32 v26, v16, v26, v16
	v_mul_f32_e32 v26, 0x3fcc422a, v26
	v_mul_f32_e32 v26, 0xbfb8aa3b, v26
	v_exp_f32_e32 v30, v26
	v_mul_f32_e32 v26, 0x3d372713, v17
	v_mul_f32_e32 v26, v17, v26
	v_fma_f32 v26, v17, v26, v17
	v_mul_f32_e32 v26, 0x3fcc422a, v26
	v_mul_f32_e32 v26, 0xbfb8aa3b, v26
	v_exp_f32_e32 v31, v26
	v_cvt_f32_f16_e32 v26, v83
	v_add_f32_e32 v30, 1.0, v30
	v_rcp_f32_e32 v30, v30
	v_add_f32_e32 v31, 1.0, v31
	v_pk_fma_f32 v[18:19], v[66:67], v[26:27], v[18:19]
	v_rcp_f32_e32 v31, v31
	v_mul_f32_e32 v26, 0x3d372713, v18
	v_mul_f32_e32 v27, 0x3d372713, v19
	v_mul_f32_e32 v26, v18, v26
	v_mul_f32_e32 v27, v19, v27
	v_fma_f32 v26, v18, v26, v18
	v_fma_f32 v27, v19, v27, v19
	v_mul_f32_e32 v26, 0x3fcc422a, v26
	v_mul_f32_e32 v27, 0x3fcc422a, v27
	v_mul_f32_e32 v26, 0xbfb8aa3b, v26
	v_mul_f32_e32 v27, 0xbfb8aa3b, v27
	v_exp_f32_e32 v26, v26
	v_exp_f32_e32 v27, v27
	v_rcp_f32_e32 v28, v28
	v_rcp_f32_e32 v29, v29
	v_add_f32_e32 v26, 1.0, v26
	v_add_f32_e32 v27, 1.0, v27
	v_pk_mul_f32 v[20:21], v[20:21], v[24:25]
	v_pk_mul_f32 v[24:25], v[16:17], v[30:31]
	v_lshl_add_u64 v[16:17], v[32:33], 0, v[120:121]
	v_rcp_f32_e32 v26, v26
	v_rcp_f32_e32 v27, v27
	v_lshl_add_u64 v[16:17], v[16:17], 0, s[10:11]
	v_pk_mul_f32 v[22:23], v[22:23], v[28:29]
	v_lshl_add_u64 v[28:29], v[16:17], 0, v[186:187]
	v_cvt_pk_f16_f32 v16, v20, v21
	s_waitcnt vmcnt(0) lgkmcnt(0)
	v_cvt_f32_f16_e32 v20, v76
	v_cvt_f32_f16_sdwa v21, v76 dst_sel:DWORD dst_unused:UNUSED_PAD src0_sel:WORD_1
	v_pk_mul_f32 v[26:27], v[18:19], v[26:27]
	v_cvt_pk_f16_f32 v17, v22, v23
	v_cvt_pk_f16_f32 v18, v24, v25
	v_cvt_pk_f16_f32 v19, v26, v27
	v_pk_fma_f32 v[12:13], v[72:73], v[20:21], v[12:13]
	global_store_dwordx4 v[28:29], v[16:19], off
	v_mul_f32_e32 v20, 0x3d372713, v12
	v_mul_f32_e32 v20, v12, v20
	v_mul_f32_e32 v18, 0x3d372713, v13
	v_mul_f32_e32 v18, v13, v18
	v_fma_f32 v21, v13, v18, v13
	v_cvt_f32_f16_e32 v18, v77
	v_cvt_f32_f16_sdwa v19, v77 dst_sel:DWORD dst_unused:UNUSED_PAD src0_sel:WORD_1
	v_fma_f32 v20, v12, v20, v12
	v_mul_f32_e32 v20, 0x3fcc422a, v20
	v_mul_f32_e32 v20, 0xbfb8aa3b, v20
	v_pk_fma_f32 v[14:15], v[74:75], v[18:19], v[14:15]
	v_exp_f32_e32 v20, v20
	v_mul_f32_e32 v18, 0x3d372713, v14
	v_mul_f32_e32 v18, v14, v18
	v_fma_f32 v18, v14, v18, v14
	v_mul_f32_e32 v18, 0x3fcc422a, v18
	v_add_f32_e32 v20, 1.0, v20
	v_mul_f32_e32 v21, 0x3fcc422a, v21
	v_mul_f32_e32 v18, 0xbfb8aa3b, v18
	v_mul_f32_e32 v21, 0xbfb8aa3b, v21
	v_exp_f32_e32 v22, v18
	v_rcp_f32_e32 v18, v20
	v_mul_f32_e32 v20, 0x3d372713, v15
	v_exp_f32_e32 v21, v21
	v_mul_f32_e32 v20, v15, v20
	v_fma_f32 v20, v15, v20, v15
	v_mul_f32_e32 v20, 0x3fcc422a, v20
	v_mul_f32_e32 v20, 0xbfb8aa3b, v20
	v_add_f32_e32 v19, 1.0, v21
	v_exp_f32_e32 v23, v20
	v_cvt_f32_f16_e32 v20, v78
	v_cvt_f32_f16_sdwa v21, v78 dst_sel:DWORD dst_unused:UNUSED_PAD src0_sel:WORD_1
	v_rcp_f32_e32 v19, v19
	v_add_f32_e32 v22, 1.0, v22
	v_add_f32_e32 v23, 1.0, v23
	v_pk_fma_f32 v[8:9], v[64:65], v[20:21], v[8:9]
	v_cvt_f32_f16_sdwa v21, v79 dst_sel:DWORD dst_unused:UNUSED_PAD src0_sel:WORD_1
	v_mul_f32_e32 v20, 0x3d372713, v8
	v_mul_f32_e32 v20, v8, v20
	v_fma_f32 v20, v8, v20, v8
	v_mul_f32_e32 v20, 0x3fcc422a, v20
	v_mul_f32_e32 v20, 0xbfb8aa3b, v20
	v_exp_f32_e32 v24, v20
	v_mul_f32_e32 v20, 0x3d372713, v9
	v_mul_f32_e32 v20, v9, v20
	v_fma_f32 v20, v9, v20, v9
	v_mul_f32_e32 v20, 0x3fcc422a, v20
	v_mul_f32_e32 v20, 0xbfb8aa3b, v20
	v_exp_f32_e32 v25, v20
	v_cvt_f32_f16_e32 v20, v79
	v_add_f32_e32 v24, 1.0, v24
	v_rcp_f32_e32 v24, v24
	v_add_f32_e32 v25, 1.0, v25
	v_pk_fma_f32 v[10:11], v[66:67], v[20:21], v[10:11]
	v_rcp_f32_e32 v25, v25
	v_mul_f32_e32 v20, 0x3d372713, v10
	v_mul_f32_e32 v21, 0x3d372713, v11
	v_mul_f32_e32 v20, v10, v20
	v_mul_f32_e32 v21, v11, v21
	v_fma_f32 v20, v10, v20, v10
	v_fma_f32 v21, v11, v21, v11
	v_mul_f32_e32 v20, 0x3fcc422a, v20
	v_mul_f32_e32 v21, 0x3fcc422a, v21
	v_mul_f32_e32 v20, 0xbfb8aa3b, v20
	v_mul_f32_e32 v21, 0xbfb8aa3b, v21
	v_exp_f32_e32 v20, v20
	v_exp_f32_e32 v21, v21
	v_rcp_f32_e32 v22, v22
	v_rcp_f32_e32 v23, v23
	v_add_f32_e32 v20, 1.0, v20
	v_add_f32_e32 v21, 1.0, v21
	v_rcp_f32_e32 v20, v20
	v_rcp_f32_e32 v21, v21
	v_lshlrev_b64 v[16:17], 17, v[100:101]
	v_lshl_add_u64 v[16:17], s[48:49], 0, v[16:17]
	v_pk_mul_f32 v[12:13], v[12:13], v[18:19]
	v_pk_mul_f32 v[20:21], v[10:11], v[20:21]
	v_cvt_f32_f16_e32 v10, v68
	v_cvt_f32_f16_sdwa v11, v68 dst_sel:DWORD dst_unused:UNUSED_PAD src0_sel:WORD_1
	v_pk_mul_f32 v[18:19], v[8:9], v[24:25]
	v_lshl_add_u64 v[8:9], v[16:17], 0, v[128:129]
	v_pk_mul_f32 v[14:15], v[14:15], v[22:23]
	v_pk_fma_f32 v[4:5], v[72:73], v[10:11], v[4:5]
	v_lshl_add_u64 v[8:9], v[8:9], 0, s[10:11]
	v_mul_f32_e32 v10, 0x3d372713, v4
	v_mul_f32_e32 v10, v4, v10
	v_fma_f32 v10, v4, v10, v4
	v_mul_f32_e32 v10, 0x3fcc422a, v10
	v_mul_f32_e32 v10, 0xbfb8aa3b, v10
	v_lshl_add_u64 v[22:23], v[8:9], 0, v[186:187]
	v_cvt_pk_f16_f32 v8, v12, v13
	v_cvt_pk_f16_f32 v9, v14, v15
	v_exp_f32_e32 v12, v10
	v_cvt_pk_f16_f32 v10, v18, v19
	v_cvt_pk_f16_f32 v11, v20, v21
	global_store_dwordx4 v[22:23], v[8:11], off
	s_nop 1
	v_mul_f32_e32 v8, 0x3d372713, v5
	v_mul_f32_e32 v8, v5, v8
	v_fma_f32 v11, v5, v8, v5
	v_cvt_f32_f16_e32 v8, v69
	v_cvt_f32_f16_sdwa v9, v69 dst_sel:DWORD dst_unused:UNUSED_PAD src0_sel:WORD_1
	v_add_f32_e32 v10, 1.0, v12
	v_mul_f32_e32 v11, 0x3fcc422a, v11
	v_mul_f32_e32 v11, 0xbfb8aa3b, v11
	v_pk_fma_f32 v[6:7], v[74:75], v[8:9], v[6:7]
	v_exp_f32_e32 v11, v11
	v_mul_f32_e32 v8, 0x3d372713, v6
	v_mul_f32_e32 v8, v6, v8
	v_fma_f32 v8, v6, v8, v6
	v_mul_f32_e32 v8, 0x3fcc422a, v8
	v_mul_f32_e32 v8, 0xbfb8aa3b, v8
	v_exp_f32_e32 v12, v8
	v_rcp_f32_e32 v8, v10
	v_mul_f32_e32 v10, 0x3d372713, v7
	v_mul_f32_e32 v10, v7, v10
	v_fma_f32 v10, v7, v10, v7
	v_mul_f32_e32 v10, 0x3fcc422a, v10
	v_mul_f32_e32 v10, 0xbfb8aa3b, v10
	v_add_f32_e32 v9, 1.0, v11
	v_exp_f32_e32 v13, v10
	v_cvt_f32_f16_e32 v10, v70
	v_cvt_f32_f16_sdwa v11, v70 dst_sel:DWORD dst_unused:UNUSED_PAD src0_sel:WORD_1
	v_rcp_f32_e32 v9, v9
	v_add_f32_e32 v12, 1.0, v12
	v_add_f32_e32 v13, 1.0, v13
	v_pk_fma_f32 v[0:1], v[64:65], v[10:11], v[0:1]
	v_cvt_f32_f16_sdwa v11, v71 dst_sel:DWORD dst_unused:UNUSED_PAD src0_sel:WORD_1
	v_mul_f32_e32 v10, 0x3d372713, v0
	v_mul_f32_e32 v10, v0, v10
	v_fma_f32 v10, v0, v10, v0
	v_mul_f32_e32 v10, 0x3fcc422a, v10
	v_mul_f32_e32 v10, 0xbfb8aa3b, v10
	v_exp_f32_e32 v14, v10
	v_mul_f32_e32 v10, 0x3d372713, v1
	v_mul_f32_e32 v10, v1, v10
	v_fma_f32 v10, v1, v10, v1
	v_mul_f32_e32 v10, 0x3fcc422a, v10
	v_mul_f32_e32 v10, 0xbfb8aa3b, v10
	v_exp_f32_e32 v15, v10
	v_cvt_f32_f16_e32 v10, v71
	v_add_f32_e32 v14, 1.0, v14
	v_rcp_f32_e32 v14, v14
	v_add_f32_e32 v15, 1.0, v15
	v_pk_fma_f32 v[2:3], v[66:67], v[10:11], v[2:3]
	v_rcp_f32_e32 v15, v15
	v_mul_f32_e32 v10, 0x3d372713, v2
	v_mul_f32_e32 v11, 0x3d372713, v3
	v_mul_f32_e32 v10, v2, v10
	v_mul_f32_e32 v11, v3, v11
	v_fma_f32 v10, v2, v10, v2
	v_fma_f32 v11, v3, v11, v3
	v_mul_f32_e32 v10, 0x3fcc422a, v10
	v_mul_f32_e32 v11, 0x3fcc422a, v11
	v_mul_f32_e32 v10, 0xbfb8aa3b, v10
	v_mul_f32_e32 v11, 0xbfb8aa3b, v11
	v_exp_f32_e32 v10, v10
	v_exp_f32_e32 v11, v11
	v_rcp_f32_e32 v12, v12
	v_rcp_f32_e32 v13, v13
	v_add_f32_e32 v10, 1.0, v10
	v_add_f32_e32 v11, 1.0, v11
	v_rcp_f32_e32 v10, v10
	v_rcp_f32_e32 v11, v11
	v_pk_mul_f32 v[4:5], v[4:5], v[8:9]
	v_pk_mul_f32 v[8:9], v[0:1], v[14:15]
	v_lshl_add_u64 v[0:1], v[16:17], 0, v[120:121]
	v_pk_mul_f32 v[6:7], v[6:7], v[12:13]
	v_pk_mul_f32 v[10:11], v[2:3], v[10:11]
	v_lshl_add_u64 v[0:1], v[0:1], 0, s[10:11]
	v_lshl_add_u64 v[12:13], v[0:1], 0, v[186:187]
	v_cvt_pk_f16_f32 v0, v4, v5
	v_cvt_pk_f16_f32 v1, v6, v7
	v_cvt_pk_f16_f32 v2, v8, v9
	v_cvt_pk_f16_f32 v3, v10, v11
	global_store_dwordx4 v[12:13], v[0:3], off
	s_cbranch_vccnz .LBB0_896
	s_andn2_b64 vcc, exec, s[4:5]
	s_cbranch_vccnz .LBB0_895
	s_barrier
	s_branch .LBB0_895

.LBB0_929:
	v_lshl_add_u32 v80, s19, 8, v76
	s_ashr_i32 s19, s18, 31
	s_lshl_b64 s[0:1], s[18:19], 19
	v_ashrrev_i32_e32 v81, 31, v80
	s_add_u32 s0, s43, s0
	s_addc_u32 s1, s48, s1
	v_lshlrev_b64 v[82:83], 9, v[80:81]
	v_lshl_add_u64 v[82:83], s[0:1], 0, v[82:83]
	v_lshl_add_u64 v[82:83], v[82:83], 0, v[176:177]
	global_store_dwordx4 v[82:83], v[60:63], off
	global_store_dwordx4 v[82:83], v[56:59], off offset:16
	s_nop 1
	v_or_b32_e32 v56, 16, v80
	v_ashrrev_i32_e32 v57, 31, v56
	v_lshlrev_b64 v[56:57], 9, v[56:57]
	v_lshl_add_u64 v[56:57], s[0:1], 0, v[56:57]
	v_lshl_add_u64 v[56:57], v[56:57], 0, v[176:177]
	global_store_dwordx4 v[56:57], v[52:55], off
	global_store_dwordx4 v[56:57], v[48:51], off offset:16
	s_nop 1
	v_or_b32_e32 v48, 32, v80
	v_ashrrev_i32_e32 v49, 31, v48
	v_lshlrev_b64 v[48:49], 9, v[48:49]
	v_lshl_add_u64 v[48:49], s[0:1], 0, v[48:49]
	v_lshl_add_u64 v[48:49], v[48:49], 0, v[176:177]
	global_store_dwordx4 v[48:49], v[44:47], off
	global_store_dwordx4 v[48:49], v[40:43], off offset:16
	s_nop 1
	v_or_b32_e32 v40, 48, v80
	v_ashrrev_i32_e32 v41, 31, v40
	v_lshlrev_b64 v[40:41], 9, v[40:41]
	v_lshl_add_u64 v[40:41], s[0:1], 0, v[40:41]
	v_lshl_add_u64 v[40:41], v[40:41], 0, v[176:177]
	s_mov_b64 s[0:1], 0x10000
	global_store_dwordx4 v[40:41], v[36:39], off
	global_store_dwordx4 v[40:41], v[32:35], off offset:16
	s_nop 1
	v_lshl_add_u64 v[32:33], v[82:83], 0, s[0:1]
	s_mov_b32 s0, 0x10000
	v_add_co_u32_e32 v34, vcc, s0, v82
	s_mov_b64 s[0:1], 0x12000
	s_nop 0
	v_addc_co_u32_e32 v35, vcc, 0, v83, vcc
	global_store_dwordx4 v[34:35], v[28:31], off
	global_store_dwordx4 v[32:33], v[24:27], off offset:16
	s_nop 1
	v_lshl_add_u64 v[24:25], v[82:83], 0, s[0:1]
	s_mov_b32 s0, 0x12000
	v_add_co_u32_e32 v26, vcc, s0, v82
	s_mov_b64 s[0:1], 0x14000
	s_nop 0
	v_addc_co_u32_e32 v27, vcc, 0, v83, vcc
	global_store_dwordx4 v[26:27], v[20:23], off
	global_store_dwordx4 v[24:25], v[16:19], off offset:16
	s_nop 1
	v_add_co_u32_e32 v18, vcc, 0x14000, v82
	v_lshl_add_u64 v[16:17], v[82:83], 0, s[0:1]
	s_nop 0
	v_addc_co_u32_e32 v19, vcc, 0, v83, vcc
	global_store_dwordx4 v[18:19], v[12:15], off
	global_store_dwordx4 v[16:17], v[8:11], off offset:16
	s_mov_b64 s[0:1], 0x16000
	s_nop 0
	v_add_co_u32_e32 v10, vcc, 0x16000, v82
	v_lshl_add_u64 v[8:9], v[82:83], 0, s[0:1]
	s_nop 0
	v_addc_co_u32_e32 v11, vcc, 0, v83, vcc
	global_store_dwordx4 v[10:11], v[4:7], off
	global_store_dwordx4 v[8:9], v[0:3], off offset:16
	s_and_b64 vcc, exec, s[4:5]
	s_mov_b64 s[0:1], -1
	s_cbranch_vccnz .LBB0_920
	s_andn2_b64 vcc, exec, s[6:7]
	s_cbranch_vccnz .LBB0_919
	s_barrier
	s_branch .LBB0_919

.LBB0_936:
	s_and_saveexec_b64 s[0:1], s[2:3]
	s_cbranch_execz .LBB0_935
	s_and_b32 s7, s5, 0x300
	s_ashr_i32 s8, s6, 2
	v_add_u32_e32 v10, s7, v3
	s_add_i32 s7, s8, s4
	s_mul_i32 s10, s7, 0x41
	s_ashr_i32 s11, s10, 31
	s_lshl_b64 s[10:11], s[10:11], 9
	v_lshl_add_u64 v[6:7], v[0:1], 0, s[10:11]
	v_add_co_u32_e32 v6, vcc, 0x8000, v6
	s_ashr_i32 s9, s8, 31
	s_nop 0
	v_addc_co_u32_e32 v7, vcc, 0, v7, vcc
	global_load_dwordx2 v[6:7], v[6:7], off
	s_mul_hi_i32 s7, s8, 0x240000
	s_mul_i32 s10, s8, 0x240000
	v_ashrrev_i32_e32 v11, 31, v10
	s_lshl_b64 s[8:9], s[8:9], 19
	v_mov_b32_e32 v15, s7
	v_or_b32_e32 v14, s10, v2
	v_lshlrev_b64 v[12:13], 9, v[10:11]
	v_mad_i64_i32 v[10:11], s[10:11], v10, s52, v[14:15]
	v_mov_b32_e32 v15, s9
	v_or_b32_e32 v14, s8, v4
	v_lshl_add_u64 v[12:13], v[14:15], 0, v[12:13]
	v_mov_b32_e32 v14, 0
	s_mov_b32 s7, 64
	v_mov_b32_e32 v15, v14
	s_waitcnt vmcnt(0) lgkmcnt(0)
	v_pk_mov_b32 v[8:9], v[6:7], v[6:7] op_sel:[1,0]
.LBB0_938:
	v_cvt_f16_f32_e32 v5, v14
	v_lshl_add_u64 v[16:17], s[60:61], 0, v[10:11]
	v_add_co_u32_e32 v18, vcc, 0x34000000, v16
	v_lshl_add_u64 v[20:21], s[60:61], 0, v[12:13]
	s_nop 0
	v_addc_co_u32_e32 v19, vcc, 0, v17, vcc
	global_store_short v[18:19], v5, off
	v_cvt_f16_f32_e32 v5, v15
	v_add_co_u32_e32 v20, vcc, 0x32000000, v20
	v_pk_mul_f32 v[24:25], v[8:9], v[14:15] op_sel:[0,1]
	global_store_short v[18:19], v5, off offset:128
	v_addc_co_u32_e32 v21, vcc, 0, v21, vcc
	global_load_dword v22, v[20:21], off
	global_load_dword v23, v[20:21], off offset:256
	v_pk_fma_f32 v[26:27], v[6:7], v[14:15], v[24:25] neg_lo:[0,0,1] neg_hi:[0,0,1]
	v_pk_fma_f32 v[14:15], v[6:7], v[14:15], v[24:25] op_sel_hi:[1,0,1]
	s_mov_b32 s8, 0x34001000
	v_mov_b32_e32 v27, v15
	s_add_i32 s7, s7, -8
	s_cmp_lg_u32 s7, 0
	s_waitcnt vmcnt(0) lgkmcnt(0)
	v_pk_add_f32 v[14:15], v[26:27], v[22:23]
	s_nop 0
	v_cvt_f16_f32_e32 v5, v14
	v_pk_mul_f32 v[22:23], v[8:9], v[14:15] op_sel:[0,1]
	global_store_short v[18:19], v5, off offset:2304
	v_cvt_f16_f32_e32 v5, v15
	v_pk_fma_f32 v[24:25], v[6:7], v[14:15], v[22:23] neg_lo:[0,0,1] neg_hi:[0,0,1]
	v_pk_fma_f32 v[14:15], v[6:7], v[14:15], v[22:23] op_sel_hi:[1,0,1]
	global_store_short v[18:19], v5, off offset:2432
	global_load_dword v18, v[20:21], off offset:512
	s_nop 0
	global_load_dword v19, v[20:21], off offset:768
	v_mov_b32_e32 v25, v15
	s_waitcnt vmcnt(0) lgkmcnt(0)
	v_pk_add_f32 v[14:15], v[24:25], v[18:19]
	s_nop 0
	v_cvt_f16_f32_e32 v5, v14
	v_add_co_u32_e32 v18, vcc, s8, v16
	v_pk_mul_f32 v[24:25], v[8:9], v[14:15] op_sel:[0,1]
	s_nop 0
	v_addc_co_u32_e32 v19, vcc, 0, v17, vcc
	global_store_short v[18:19], v5, off offset:512
	v_cvt_f16_f32_e32 v5, v15
	v_pk_fma_f32 v[26:27], v[6:7], v[14:15], v[24:25] neg_lo:[0,0,1] neg_hi:[0,0,1]
	v_pk_fma_f32 v[14:15], v[6:7], v[14:15], v[24:25] op_sel_hi:[1,0,1]
	s_mov_b32 s8, 0x34002000
	global_store_short v[18:19], v5, off offset:640
	global_load_dword v22, v[20:21], off offset:1024
	global_load_dword v23, v[20:21], off offset:1280
	v_mov_b32_e32 v27, v15
	s_waitcnt vmcnt(0) lgkmcnt(0)
	v_pk_add_f32 v[14:15], v[26:27], v[22:23]
	s_nop 0
	v_cvt_f16_f32_e32 v5, v14
	v_pk_mul_f32 v[22:23], v[8:9], v[14:15] op_sel:[0,1]
	global_store_short v[18:19], v5, off offset:2816
	v_cvt_f16_f32_e32 v5, v15
	v_pk_fma_f32 v[24:25], v[6:7], v[14:15], v[22:23] neg_lo:[0,0,1] neg_hi:[0,0,1]
	v_pk_fma_f32 v[14:15], v[6:7], v[14:15], v[22:23] op_sel_hi:[1,0,1]
	global_store_short v[18:19], v5, off offset:2944
	global_load_dword v18, v[20:21], off offset:1536
	s_nop 0
	global_load_dword v19, v[20:21], off offset:1792
	v_mov_b32_e32 v25, v15
	s_waitcnt vmcnt(0) lgkmcnt(0)
	v_pk_add_f32 v[14:15], v[24:25], v[18:19]
	s_nop 0
	v_cvt_f16_f32_e32 v5, v14
	v_add_co_u32_e32 v18, vcc, s8, v16
	v_pk_mul_f32 v[24:25], v[8:9], v[14:15] op_sel:[0,1]
	s_nop 0
	v_addc_co_u32_e32 v19, vcc, 0, v17, vcc
	global_store_short v[18:19], v5, off offset:1024
	v_cvt_f16_f32_e32 v5, v15
	v_pk_fma_f32 v[26:27], v[6:7], v[14:15], v[24:25] neg_lo:[0,0,1] neg_hi:[0,0,1]
	v_pk_fma_f32 v[14:15], v[6:7], v[14:15], v[24:25] op_sel_hi:[1,0,1]
	s_mov_b32 s8, 0x34003000
	global_store_short v[18:19], v5, off offset:1152
	global_load_dword v22, v[20:21], off offset:2048
	global_load_dword v23, v[20:21], off offset:2304
	v_mov_b32_e32 v27, v15
	v_add_co_u32_e32 v16, vcc, s8, v16
	s_mov_b64 s[8:9], 0x4800
	s_nop 0
	v_addc_co_u32_e32 v17, vcc, 0, v17, vcc
	v_lshl_add_u64 v[10:11], v[10:11], 0, s[8:9]
	s_mov_b64 s[8:9], 0x1000
	v_lshl_add_u64 v[12:13], v[12:13], 0, s[8:9]
	s_waitcnt vmcnt(0) lgkmcnt(0)
	v_pk_add_f32 v[14:15], v[26:27], v[22:23]
	s_nop 0
	v_cvt_f16_f32_e32 v5, v14
	v_pk_mul_f32 v[22:23], v[8:9], v[14:15] op_sel:[0,1]
	global_store_short v[18:19], v5, off offset:3328
	v_cvt_f16_f32_e32 v5, v15
	v_pk_fma_f32 v[24:25], v[6:7], v[14:15], v[22:23] neg_lo:[0,0,1] neg_hi:[0,0,1]
	v_pk_fma_f32 v[14:15], v[6:7], v[14:15], v[22:23] op_sel_hi:[1,0,1]
	global_store_short v[18:19], v5, off offset:3456
	global_load_dword v18, v[20:21], off offset:2560
	s_nop 0
	global_load_dword v19, v[20:21], off offset:2816
	v_mov_b32_e32 v25, v15
	s_waitcnt vmcnt(0) lgkmcnt(0)
	v_pk_add_f32 v[14:15], v[24:25], v[18:19]
	s_nop 0
	v_cvt_f16_f32_e32 v5, v14
	v_pk_mul_f32 v[22:23], v[8:9], v[14:15] op_sel:[0,1]
	global_store_short v[16:17], v5, off offset:1536
	v_cvt_f16_f32_e32 v5, v15
	v_pk_fma_f32 v[24:25], v[6:7], v[14:15], v[22:23] neg_lo:[0,0,1] neg_hi:[0,0,1]
	v_pk_fma_f32 v[14:15], v[6:7], v[14:15], v[22:23] op_sel_hi:[1,0,1]
	global_store_short v[16:17], v5, off offset:1664
	global_load_dword v18, v[20:21], off offset:3072
	global_load_dword v19, v[20:21], off offset:3328
	v_mov_b32_e32 v25, v15
	s_waitcnt vmcnt(0) lgkmcnt(0)
	v_pk_add_f32 v[14:15], v[24:25], v[18:19]
	s_nop 0
	v_cvt_f16_f32_e32 v5, v14
	v_pk_mul_f32 v[18:19], v[8:9], v[14:15] op_sel:[0,1]
	global_store_short v[16:17], v5, off offset:3840
	v_cvt_f16_f32_e32 v5, v15
	global_store_short v[16:17], v5, off offset:3968
	global_load_dword v16, v[20:21], off offset:3584
	s_nop 0
	global_load_dword v17, v[20:21], off offset:3840
	v_pk_fma_f32 v[20:21], v[6:7], v[14:15], v[18:19] neg_lo:[0,0,1] neg_hi:[0,0,1]
	v_pk_fma_f32 v[14:15], v[6:7], v[14:15], v[18:19] op_sel_hi:[1,0,1]
	s_nop 0
	v_mov_b32_e32 v21, v15
	s_waitcnt vmcnt(0) lgkmcnt(0)
	v_pk_add_f32 v[14:15], v[20:21], v[16:17]
	s_cbranch_scc1 .LBB0_938
	s_branch .LBB0_935

.LBB0_957:
	s_lshl_b32 s9, s39, 8
	s_cmp_eq_u32 s39, s37
	s_cbranch_scc1 .LBB0_961
	s_barrier
	s_and_saveexec_b64 s[18:19], s[2:3]
	s_cbranch_execz .LBB0_960
	v_add_u32_e32 v148, s9, v150
	v_ashrrev_i32_e32 v149, 31, v148
	v_lshl_add_u64 v[148:149], v[148:149], 4, s[46:47]
	global_load_dwordx4 v[156:159], v[148:149], off
	s_waitcnt vmcnt(0) lgkmcnt(0)
	v_mov_b32_e32 v148, v157
	v_mov_b32_e32 v149, v158
	v_mov_b32_e32 v157, v159
	v_pk_add_f32 v[148:149], v[148:149], v[156:157]
	s_nop 0
	v_add_f32_e32 v148, v148, v149
	v_fmamk_f32 v148, v148, 0x3a800000, v205
	v_mul_f32_e32 v149, 0x4b800000, v148
	v_cmp_gt_f32_e32 vcc, s67, v148
	s_nop 1
	v_cndmask_b32_e32 v148, v148, v149, vcc
	v_rsq_f32_e32 v148, v148
	s_nop 0
	v_mul_f32_e32 v149, 0x45800000, v148
	v_cndmask_b32_e32 v148, v148, v149, vcc
	ds_write_b32 v151, v148

.LBB0_961:
	s_add_i32 s9, s9, s29
	ds_read2_b32 v[156:157], v152 offset1:16
	ds_read2_b32 v[158:159], v152 offset0:32 offset1:48
	s_ashr_i32 s11, s9, 6
	s_mul_hi_i32 s20, s11, 0x480
	s_mulk_i32 s11, 0x480
	v_lshl_or_b32 v148, s38, 8, v153
	v_mov_b32_e32 v163, s20
	v_or_b32_e32 v162, s11, v136
	v_ashrrev_i32_e32 v148, 4, v148
	v_mov_b64_e32 v[160:161], s[12:13]
	s_mov_b32 s21, 0x240000
	v_lshl_add_u64 v[164:165], v[162:163], 0, v[134:135]
	v_or_b32_e32 v155, 8, v148
	v_mad_i64_i32 v[148:149], s[18:19], v148, s21, v[160:161]
	v_lshlrev_b64 v[164:165], 1, v[164:165]
	s_waitcnt lgkmcnt(0)
	v_pk_mul_f32 v[126:127], v[126:127], v[156:157] op_sel_hi:[1,0]
	v_pk_mul_f32 v[124:125], v[124:125], v[156:157] op_sel_hi:[1,0]
	v_pk_mul_f32 v[168:169], v[122:123], v[156:157] op_sel_hi:[1,0]
	v_pk_mul_f32 v[122:123], v[120:121], v[156:157] op_sel_hi:[1,0]
	v_lshl_add_u64 v[166:167], v[148:149], 0, v[164:165]
	v_cvt_pk_f16_f32 v120, v124, v125
	v_cvt_pk_f16_f32 v121, v126, v127
	v_cvt_pk_f16_f32 v122, v122, v123
	v_cvt_pk_f16_f32 v123, v168, v169
	global_store_dwordx4 v[166:167], v[120:123], off offset:256
	v_pk_mul_f32 v[114:115], v[114:115], v[156:157] op_sel_hi:[1,0]
	v_pk_mul_f32 v[112:113], v[112:113], v[156:157] op_sel_hi:[1,0]
	v_mad_i64_i32 v[120:121], s[18:19], v155, s21, v[160:161]
	v_pk_mul_f32 v[124:125], v[106:107], v[156:157] op_sel_hi:[1,0]
	v_pk_mul_f32 v[106:107], v[104:105], v[156:157] op_sel_hi:[1,0]
	v_lshl_add_u64 v[122:123], v[120:121], 0, v[164:165]
	v_cvt_pk_f16_f32 v104, v112, v113
	v_cvt_pk_f16_f32 v105, v114, v115
	v_cvt_pk_f16_f32 v106, v106, v107
	v_cvt_pk_f16_f32 v107, v124, v125
	global_store_dwordx4 v[122:123], v[104:107], off offset:256
	v_mov_b32_e32 v122, v157
	v_pk_mul_f32 v[110:111], v[110:111], v[122:123] op_sel_hi:[1,0]
	v_lshl_add_u64 v[104:105], v[162:163], 0, v[138:139]
	v_lshlrev_b64 v[112:113], 1, v[104:105]
	v_pk_mul_f32 v[106:107], v[118:119], v[122:123] op_sel_hi:[1,0]
	v_pk_mul_f32 v[104:105], v[116:117], v[122:123] op_sel_hi:[1,0]
	v_pk_mul_f32 v[108:109], v[108:109], v[122:123] op_sel_hi:[1,0]
	v_lshl_add_u64 v[114:115], v[148:149], 0, v[112:113]
	v_cvt_pk_f16_f32 v104, v104, v105
	v_cvt_pk_f16_f32 v105, v106, v107
	v_cvt_pk_f16_f32 v106, v108, v109
	v_cvt_pk_f16_f32 v107, v110, v111
	global_store_dwordx4 v[114:115], v[104:107], off offset:256
	v_pk_mul_f32 v[98:99], v[98:99], v[122:123] op_sel_hi:[1,0]
	v_pk_mul_f32 v[96:97], v[96:97], v[122:123] op_sel_hi:[1,0]
	v_pk_mul_f32 v[106:107], v[90:91], v[122:123] op_sel_hi:[1,0]
	v_pk_mul_f32 v[90:91], v[88:89], v[122:123] op_sel_hi:[1,0]
	v_lshl_add_u64 v[104:105], v[120:121], 0, v[112:113]
	v_cvt_pk_f16_f32 v88, v96, v97
	v_cvt_pk_f16_f32 v89, v98, v99
	v_cvt_pk_f16_f32 v90, v90, v91
	v_cvt_pk_f16_f32 v91, v106, v107
	global_store_dwordx4 v[104:105], v[88:91], off offset:256
	v_pk_mul_f32 v[94:95], v[94:95], v[158:159] op_sel_hi:[1,0]
	v_pk_mul_f32 v[92:93], v[92:93], v[158:159] op_sel_hi:[1,0]
	v_lshl_add_u64 v[88:89], v[162:163], 0, v[140:141]
	v_lshlrev_b64 v[96:97], 1, v[88:89]
	v_pk_mul_f32 v[90:91], v[102:103], v[158:159] op_sel_hi:[1,0]
	v_pk_mul_f32 v[88:89], v[100:101], v[158:159] op_sel_hi:[1,0]
	v_lshl_add_u64 v[98:99], v[148:149], 0, v[96:97]
	v_cvt_pk_f16_f32 v88, v88, v89
	v_cvt_pk_f16_f32 v89, v90, v91
	v_cvt_pk_f16_f32 v90, v92, v93
	v_cvt_pk_f16_f32 v91, v94, v95
	global_store_dwordx4 v[98:99], v[88:91], off offset:256
	v_pk_mul_f32 v[82:83], v[82:83], v[158:159] op_sel_hi:[1,0]
	v_pk_mul_f32 v[80:81], v[80:81], v[158:159] op_sel_hi:[1,0]
	v_pk_mul_f32 v[90:91], v[74:75], v[158:159] op_sel_hi:[1,0]
	v_pk_mul_f32 v[74:75], v[72:73], v[158:159] op_sel_hi:[1,0]
	v_lshl_add_u64 v[88:89], v[120:121], 0, v[96:97]
	v_cvt_pk_f16_f32 v72, v80, v81
	v_cvt_pk_f16_f32 v73, v82, v83
	v_cvt_pk_f16_f32 v74, v74, v75
	v_cvt_pk_f16_f32 v75, v90, v91
	global_store_dwordx4 v[88:89], v[72:75], off offset:256
	v_mov_b32_e32 v88, v159
	v_pk_mul_f32 v[78:79], v[78:79], v[88:89] op_sel_hi:[1,0]
	v_lshl_add_u64 v[72:73], v[162:163], 0, v[142:143]
	v_lshlrev_b64 v[80:81], 1, v[72:73]
	v_pk_mul_f32 v[74:75], v[86:87], v[88:89] op_sel_hi:[1,0]
	v_pk_mul_f32 v[72:73], v[84:85], v[88:89] op_sel_hi:[1,0]
	v_pk_mul_f32 v[76:77], v[76:77], v[88:89] op_sel_hi:[1,0]
	v_lshl_add_u64 v[82:83], v[148:149], 0, v[80:81]
	v_cvt_pk_f16_f32 v72, v72, v73
	v_cvt_pk_f16_f32 v73, v74, v75
	v_cvt_pk_f16_f32 v74, v76, v77
	v_cvt_pk_f16_f32 v75, v78, v79
	global_store_dwordx4 v[82:83], v[72:75], off offset:256
	v_pk_mul_f32 v[70:71], v[70:71], v[88:89] op_sel_hi:[1,0]
	v_pk_mul_f32 v[68:69], v[68:69], v[88:89] op_sel_hi:[1,0]
	v_pk_mul_f32 v[74:75], v[66:67], v[88:89] op_sel_hi:[1,0]
	v_pk_mul_f32 v[66:67], v[64:65], v[88:89] op_sel_hi:[1,0]
	v_lshl_add_u64 v[72:73], v[120:121], 0, v[80:81]
	v_cvt_pk_f16_f32 v64, v68, v69
	v_cvt_pk_f16_f32 v65, v70, v71
	v_cvt_pk_f16_f32 v66, v66, v67
	v_cvt_pk_f16_f32 v67, v74, v75
	global_store_dwordx4 v[72:73], v[64:67], off offset:256
	s_addk_i32 s9, 0x80
	ds_read2_b32 v[64:65], v152 offset0:128 offset1:144
	ds_read2_b32 v[66:67], v152 offset0:160 offset1:176
	s_ashr_i32 s9, s9, 6
	s_mul_hi_i32 s11, s9, 0x480
	s_mulk_i32 s9, 0x480
	v_mov_b32_e32 v69, s11
	v_or_b32_e32 v68, s9, v136
	v_lshl_add_u64 v[70:71], v[68:69], 0, v[134:135]
	v_lshlrev_b64 v[70:71], 1, v[70:71]
	s_waitcnt lgkmcnt(0)
	v_pk_mul_f32 v[62:63], v[62:63], v[64:65] op_sel_hi:[1,0]
	v_pk_mul_f32 v[60:61], v[60:61], v[64:65] op_sel_hi:[1,0]
	v_pk_mul_f32 v[74:75], v[58:59], v[64:65] op_sel_hi:[1,0]
	v_pk_mul_f32 v[58:59], v[56:57], v[64:65] op_sel_hi:[1,0]
	v_lshl_add_u64 v[72:73], v[148:149], 0, v[70:71]
	v_cvt_pk_f16_f32 v56, v60, v61
	v_cvt_pk_f16_f32 v57, v62, v63
	v_cvt_pk_f16_f32 v58, v58, v59
	v_cvt_pk_f16_f32 v59, v74, v75
	global_store_dwordx4 v[72:73], v[56:59], off offset:256
	v_pk_mul_f32 v[50:51], v[50:51], v[64:65] op_sel_hi:[1,0]
	v_pk_mul_f32 v[48:49], v[48:49], v[64:65] op_sel_hi:[1,0]
	v_pk_mul_f32 v[58:59], v[42:43], v[64:65] op_sel_hi:[1,0]
	v_pk_mul_f32 v[42:43], v[40:41], v[64:65] op_sel_hi:[1,0]
	v_lshl_add_u64 v[56:57], v[120:121], 0, v[70:71]
	v_cvt_pk_f16_f32 v40, v48, v49
	v_cvt_pk_f16_f32 v41, v50, v51
	v_cvt_pk_f16_f32 v42, v42, v43
	v_cvt_pk_f16_f32 v43, v58, v59
	global_store_dwordx4 v[56:57], v[40:43], off offset:256
	v_mov_b32_e32 v56, v65
	v_pk_mul_f32 v[46:47], v[46:47], v[56:57] op_sel_hi:[1,0]
	v_lshl_add_u64 v[40:41], v[68:69], 0, v[138:139]
	v_lshlrev_b64 v[48:49], 1, v[40:41]
	v_pk_mul_f32 v[42:43], v[54:55], v[56:57] op_sel_hi:[1,0]
	v_pk_mul_f32 v[40:41], v[52:53], v[56:57] op_sel_hi:[1,0]
	v_pk_mul_f32 v[44:45], v[44:45], v[56:57] op_sel_hi:[1,0]
	v_lshl_add_u64 v[50:51], v[148:149], 0, v[48:49]
	v_cvt_pk_f16_f32 v40, v40, v41
	v_cvt_pk_f16_f32 v41, v42, v43
	v_cvt_pk_f16_f32 v42, v44, v45
	v_cvt_pk_f16_f32 v43, v46, v47
	global_store_dwordx4 v[50:51], v[40:43], off offset:256
	v_pk_mul_f32 v[34:35], v[34:35], v[56:57] op_sel_hi:[1,0]
	v_pk_mul_f32 v[32:33], v[32:33], v[56:57] op_sel_hi:[1,0]
	v_pk_mul_f32 v[42:43], v[26:27], v[56:57] op_sel_hi:[1,0]
	v_pk_mul_f32 v[26:27], v[24:25], v[56:57] op_sel_hi:[1,0]
	v_lshl_add_u64 v[40:41], v[120:121], 0, v[48:49]
	v_cvt_pk_f16_f32 v24, v32, v33
	v_cvt_pk_f16_f32 v25, v34, v35
	v_cvt_pk_f16_f32 v26, v26, v27
	v_cvt_pk_f16_f32 v27, v42, v43
	global_store_dwordx4 v[40:41], v[24:27], off offset:256
	v_pk_mul_f32 v[30:31], v[30:31], v[66:67] op_sel_hi:[1,0]
	v_pk_mul_f32 v[28:29], v[28:29], v[66:67] op_sel_hi:[1,0]
	v_lshl_add_u64 v[24:25], v[68:69], 0, v[140:141]
	v_lshlrev_b64 v[32:33], 1, v[24:25]
	v_pk_mul_f32 v[26:27], v[38:39], v[66:67] op_sel_hi:[1,0]
	v_pk_mul_f32 v[24:25], v[36:37], v[66:67] op_sel_hi:[1,0]
	v_lshl_add_u64 v[34:35], v[148:149], 0, v[32:33]
	v_cvt_pk_f16_f32 v24, v24, v25
	v_cvt_pk_f16_f32 v25, v26, v27
	v_cvt_pk_f16_f32 v26, v28, v29
	v_cvt_pk_f16_f32 v27, v30, v31
	global_store_dwordx4 v[34:35], v[24:27], off offset:256
	v_pk_mul_f32 v[18:19], v[18:19], v[66:67] op_sel_hi:[1,0]
	v_pk_mul_f32 v[16:17], v[16:17], v[66:67] op_sel_hi:[1,0]
	v_pk_mul_f32 v[26:27], v[10:11], v[66:67] op_sel_hi:[1,0]
	v_pk_mul_f32 v[10:11], v[8:9], v[66:67] op_sel_hi:[1,0]
	v_lshl_add_u64 v[24:25], v[120:121], 0, v[32:33]
	v_cvt_pk_f16_f32 v8, v16, v17
	v_cvt_pk_f16_f32 v9, v18, v19
	v_cvt_pk_f16_f32 v10, v10, v11
	v_cvt_pk_f16_f32 v11, v26, v27
	global_store_dwordx4 v[24:25], v[8:11], off offset:256
	v_mov_b32_e32 v24, v67
	v_pk_mul_f32 v[14:15], v[14:15], v[24:25] op_sel_hi:[1,0]
	v_lshl_add_u64 v[8:9], v[68:69], 0, v[142:143]
	v_lshlrev_b64 v[16:17], 1, v[8:9]
	v_pk_mul_f32 v[10:11], v[22:23], v[24:25] op_sel_hi:[1,0]
	v_pk_mul_f32 v[8:9], v[20:21], v[24:25] op_sel_hi:[1,0]
	v_pk_mul_f32 v[12:13], v[12:13], v[24:25] op_sel_hi:[1,0]
	v_lshl_add_u64 v[18:19], v[148:149], 0, v[16:17]
	v_cvt_pk_f16_f32 v8, v8, v9
	v_cvt_pk_f16_f32 v9, v10, v11
	v_cvt_pk_f16_f32 v10, v12, v13
	v_cvt_pk_f16_f32 v11, v14, v15
	global_store_dwordx4 v[18:19], v[8:11], off offset:256
	v_pk_mul_f32 v[6:7], v[6:7], v[24:25] op_sel_hi:[1,0]
	v_pk_mul_f32 v[4:5], v[4:5], v[24:25] op_sel_hi:[1,0]
	v_pk_mul_f32 v[10:11], v[2:3], v[24:25] op_sel_hi:[1,0]
	v_pk_mul_f32 v[2:3], v[0:1], v[24:25] op_sel_hi:[1,0]
	v_lshl_add_u64 v[8:9], v[120:121], 0, v[16:17]
	v_cvt_pk_f16_f32 v0, v4, v5
	v_cvt_pk_f16_f32 v1, v6, v7
	v_cvt_pk_f16_f32 v2, v2, v3
	v_cvt_pk_f16_f32 v3, v10, v11
	global_store_dwordx4 v[8:9], v[0:3], off offset:256
	s_andn2_b64 vcc, exec, s[4:5]
	s_mov_b64 s[4:5], -1
	s_cbranch_vccnz .LBB0_946
	s_andn2_b64 vcc, exec, s[0:1]
	s_cbranch_vccnz .LBB0_945
	s_barrier
	s_branch .LBB0_945

.LBB0_969:
	v_ashrrev_i32_e32 v11, 7, v3
	v_lshrrev_b32_e32 v13, 3, v11
	v_and_b32_e32 v13, 0x60, v13
	v_add_u32_e32 v13, 32, v13
	v_cmp_lt_u32_e64 s[0:1], v9, v13
	s_and_saveexec_b64 s[10:11], s[0:1]
	s_cbranch_execz .LBB0_968
	v_bfe_u32 v13, v11, 4, 6
	v_sub_u32_e32 v13, v13, v10
	v_ashrrev_i32_e32 v14, 11, v3
	v_cmp_gt_i32_e64 s[0:1], 0, v13
	v_max_i32_e32 v13, 0, v13
	v_and_b32_e32 v14, 0xffffffc0, v14
	v_add3_u32 v14, v14, s12, v13
	v_ashrrev_i32_e32 v15, 31, v14
	v_lshlrev_b64 v[14:15], 10, v[14:15]
	v_lshlrev_b32_e32 v13, 6, v11
	v_and_b32_e32 v16, 8, v7
	v_lshl_add_u64 v[14:15], s[4:5], 0, v[14:15]
	v_and_b32_e32 v176, 0x3c0, v13
	v_lshl_add_u64 v[14:15], v[14:15], 0, v[176:177]
	v_lshlrev_b32_e32 v176, 2, v16
	v_lshl_add_u64 v[18:19], v[14:15], 0, v[176:177]
	global_load_dwordx4 v[14:17], v[18:19], off
	s_nop 0
	global_load_dwordx4 v[18:21], v[18:19], off offset:16
	s_waitcnt vmcnt(0) lgkmcnt(0)
	v_cndmask_b32_e64 v17, v17, 0, s[0:1]
	v_cndmask_b32_e64 v13, v21, 0, s[0:1]
	v_cndmask_b32_e64 v20, v20, 0, s[0:1]
	v_cndmask_b32_e64 v21, v19, 0, s[0:1]
	v_cndmask_b32_e64 v22, v18, 0, s[0:1]
	v_cndmask_b32_e64 v16, v16, 0, s[0:1]
	v_cndmask_b32_e64 v15, v15, 0, s[0:1]
	v_cndmask_b32_e64 v14, v14, 0, s[0:1]
	v_mad_i64_i32 v[18:19], s[0:1], v11, s52, v[0:1]
	v_cvt_pk_f16_f32 v14, v14, v15
	v_cvt_pk_f16_f32 v15, v16, v17
	v_cvt_pk_f16_f32 v16, v22, v21
	v_cvt_pk_f16_f32 v17, v20, v13
	global_store_dwordx4 v[18:19], v[14:17], off offset:256
	s_branch .LBB0_968

.LBB0_975:
	v_ashrrev_i32_e32 v5, 7, v3
	v_lshrrev_b32_e32 v6, 3, v5
	v_and_b32_e32 v6, 0x60, v6
	v_add_u32_e32 v6, 32, v6
	v_cmp_lt_u32_e32 vcc, v9, v6
	s_and_saveexec_b64 s[6:7], vcc
	s_cbranch_execz .LBB0_977
	v_bfe_u32 v6, v5, 4, 6
	v_sub_u32_e32 v6, v6, v10
	v_ashrrev_i32_e32 v7, 11, v3
	v_cmp_gt_i32_e32 vcc, 0, v6
	v_max_i32_e32 v6, 0, v6
	v_and_b32_e32 v7, 0xffffffc0, v7
	v_add3_u32 v6, v7, s12, v6
	v_ashrrev_i32_e32 v7, 31, v6
	v_lshlrev_b64 v[6:7], 10, v[6:7]
	v_lshlrev_b32_e32 v13, 6, v5
	v_and_b32_e32 v11, 8, v4
	v_lshl_add_u64 v[6:7], s[4:5], 0, v[6:7]
	v_and_b32_e32 v176, 0x3c0, v13
	v_lshl_add_u64 v[6:7], v[6:7], 0, v[176:177]
	v_lshlrev_b32_e32 v176, 2, v11
	v_lshl_add_u64 v[6:7], v[6:7], 0, v[176:177]
	global_load_dwordx4 v[14:17], v[6:7], off
	global_load_dwordx4 v[18:21], v[6:7], off offset:16
	v_mad_i64_i32 v[6:7], s[8:9], v5, s52, v[0:1]
	s_waitcnt vmcnt(0) lgkmcnt(0)
	v_cndmask_b32_e64 v17, v17, 0, vcc
	v_cndmask_b32_e64 v11, v21, 0, vcc
	v_cndmask_b32_e64 v13, v20, 0, vcc
	v_cndmask_b32_e64 v19, v19, 0, vcc
	v_cndmask_b32_e64 v18, v18, 0, vcc
	v_cndmask_b32_e64 v16, v16, 0, vcc
	v_cndmask_b32_e64 v15, v15, 0, vcc
	v_cndmask_b32_e64 v14, v14, 0, vcc
	v_cvt_pk_f16_f32 v14, v14, v15
	v_cvt_pk_f16_f32 v15, v16, v17
	v_cvt_pk_f16_f32 v16, v18, v19
	v_cvt_pk_f16_f32 v17, v13, v11
	global_store_dwordx4 v[6:7], v[14:17], off offset:256
.LBB0_977:
	s_or_b64 exec, exec, s[6:7]
	v_add_u32_e32 v5, s74, v3
	v_ashrrev_i32_e32 v6, 7, v5
	v_lshrrev_b32_e32 v7, 3, v6
	v_and_b32_e32 v7, 0x60, v7
	v_add_u32_e32 v7, 32, v7
	v_cmp_lt_u32_e32 vcc, v9, v7
	s_and_saveexec_b64 s[6:7], vcc
	s_cbranch_execz .LBB0_979
	v_bfe_u32 v7, v6, 4, 6
	v_sub_u32_e32 v7, v7, v10
	v_ashrrev_i32_e32 v13, 11, v5
	v_cmp_gt_i32_e32 vcc, 0, v7
	v_max_i32_e32 v7, 0, v7
	v_and_b32_e32 v13, 0xffffffc0, v13
	v_add3_u32 v14, v13, s12, v7
	v_ashrrev_i32_e32 v15, 31, v14
	v_lshlrev_b64 v[14:15], 10, v[14:15]
	v_lshlrev_b32_e32 v7, 6, v6
	v_and_b32_e32 v11, 8, v4
	v_lshl_add_u64 v[14:15], s[4:5], 0, v[14:15]
	v_and_b32_e32 v176, 0x3c0, v7
	v_lshl_add_u64 v[14:15], v[14:15], 0, v[176:177]
	v_lshlrev_b32_e32 v176, 2, v11
	v_lshl_add_u64 v[18:19], v[14:15], 0, v[176:177]
	global_load_dwordx4 v[14:17], v[18:19], off
	s_nop 0
	global_load_dwordx4 v[18:21], v[18:19], off offset:16
	v_mad_i64_i32 v[6:7], s[8:9], v6, s52, v[0:1]
	s_waitcnt vmcnt(0) lgkmcnt(0)
	v_cndmask_b32_e64 v17, v17, 0, vcc
	v_cndmask_b32_e64 v11, v21, 0, vcc
	v_cndmask_b32_e64 v13, v20, 0, vcc
	v_cndmask_b32_e64 v19, v19, 0, vcc
	v_cndmask_b32_e64 v18, v18, 0, vcc
	v_cndmask_b32_e64 v16, v16, 0, vcc
	v_cndmask_b32_e64 v15, v15, 0, vcc
	v_cndmask_b32_e64 v14, v14, 0, vcc
	v_cvt_pk_f16_f32 v14, v14, v15
	v_cvt_pk_f16_f32 v15, v16, v17
	v_cvt_pk_f16_f32 v16, v18, v19
	v_cvt_pk_f16_f32 v17, v13, v11
	global_store_dwordx4 v[6:7], v[14:17], off offset:256
.LBB0_979:
	s_or_b64 exec, exec, s[6:7]
	v_readlane_b32 s6, v255, 36
	s_nop 1
	v_add_u32_e32 v7, s6, v3
	v_ashrrev_i32_e32 v6, 7, v7
	v_lshrrev_b32_e32 v11, 3, v6
	v_and_b32_e32 v11, 0x60, v11
	v_add_u32_e32 v11, 32, v11
	v_cmp_lt_u32_e32 vcc, v9, v11
	s_and_saveexec_b64 s[6:7], vcc
	s_cbranch_execz .LBB0_981
	v_bfe_u32 v11, v6, 4, 6
	v_sub_u32_e32 v11, v11, v10
	v_ashrrev_i32_e32 v7, 11, v7
	v_cmp_gt_i32_e32 vcc, 0, v11
	v_max_i32_e32 v11, 0, v11
	v_and_b32_e32 v7, 0xffffffc0, v7
	v_add3_u32 v14, v7, s12, v11
	v_ashrrev_i32_e32 v15, 31, v14
	v_lshlrev_b64 v[14:15], 10, v[14:15]
	v_lshlrev_b32_e32 v7, 6, v6
	v_and_b32_e32 v13, 8, v4
	v_lshl_add_u64 v[14:15], s[4:5], 0, v[14:15]
	v_and_b32_e32 v176, 0x3c0, v7
	v_lshl_add_u64 v[14:15], v[14:15], 0, v[176:177]
	v_lshlrev_b32_e32 v176, 2, v13
	v_lshl_add_u64 v[18:19], v[14:15], 0, v[176:177]
	global_load_dwordx4 v[14:17], v[18:19], off
	s_nop 0
	global_load_dwordx4 v[18:21], v[18:19], off offset:16
	v_mad_i64_i32 v[6:7], s[8:9], v6, s52, v[0:1]
	s_waitcnt vmcnt(0) lgkmcnt(0)
	v_cndmask_b32_e64 v17, v17, 0, vcc
	v_cndmask_b32_e64 v11, v21, 0, vcc
	v_cndmask_b32_e64 v13, v20, 0, vcc
	v_cndmask_b32_e64 v19, v19, 0, vcc
	v_cndmask_b32_e64 v18, v18, 0, vcc
	v_cndmask_b32_e64 v16, v16, 0, vcc
	v_cndmask_b32_e64 v15, v15, 0, vcc
	v_cndmask_b32_e64 v14, v14, 0, vcc
	v_cvt_pk_f16_f32 v14, v14, v15
	v_cvt_pk_f16_f32 v15, v16, v17
	v_cvt_pk_f16_f32 v16, v18, v19
	v_cvt_pk_f16_f32 v17, v13, v11
	global_store_dwordx4 v[6:7], v[14:17], off offset:256
.LBB0_981:
	s_or_b64 exec, exec, s[6:7]
	s_mul_i32 s6, s58, 0x600
	v_add_u32_e32 v6, s6, v3
	v_ashrrev_i32_e32 v3, 7, v6
	v_lshrrev_b32_e32 v7, 3, v3
	v_and_b32_e32 v7, 0x60, v7
	v_add_u32_e32 v7, 32, v7
	v_cmp_lt_u32_e32 vcc, v9, v7
	s_and_saveexec_b64 s[6:7], vcc
	s_cbranch_execz .LBB0_974
	v_bfe_u32 v7, v3, 4, 6
	v_sub_u32_e32 v7, v7, v10
	v_ashrrev_i32_e32 v6, 11, v6
	v_cmp_gt_i32_e32 vcc, 0, v7
	v_max_i32_e32 v7, 0, v7
	v_and_b32_e32 v6, 0xffffffc0, v6
	v_add3_u32 v6, v6, s12, v7
	v_ashrrev_i32_e32 v7, 31, v6
	v_lshlrev_b64 v[6:7], 10, v[6:7]
	v_lshlrev_b32_e32 v13, 6, v3
	v_and_b32_e32 v11, 8, v4
	v_lshl_add_u64 v[6:7], s[4:5], 0, v[6:7]
	v_and_b32_e32 v176, 0x3c0, v13
	v_lshl_add_u64 v[6:7], v[6:7], 0, v[176:177]
	v_lshlrev_b32_e32 v176, 2, v11
	v_lshl_add_u64 v[6:7], v[6:7], 0, v[176:177]
	global_load_dwordx4 v[14:17], v[6:7], off
	global_load_dwordx4 v[18:21], v[6:7], off offset:16
	v_mad_i64_i32 v[6:7], s[8:9], v3, s52, v[0:1]
	s_waitcnt vmcnt(0) lgkmcnt(0)
	v_cndmask_b32_e64 v17, v17, 0, vcc
	v_cndmask_b32_e64 v11, v21, 0, vcc
	v_cndmask_b32_e64 v13, v20, 0, vcc
	v_cndmask_b32_e64 v19, v19, 0, vcc
	v_cndmask_b32_e64 v18, v18, 0, vcc
	v_cndmask_b32_e64 v16, v16, 0, vcc
	v_cndmask_b32_e64 v15, v15, 0, vcc
	v_cndmask_b32_e64 v14, v14, 0, vcc
	v_cvt_pk_f16_f32 v14, v14, v15
	v_cvt_pk_f16_f32 v15, v16, v17
	v_cvt_pk_f16_f32 v16, v18, v19
	v_cvt_pk_f16_f32 v17, v13, v11
	global_store_dwordx4 v[6:7], v[14:17], off offset:256
	s_branch .LBB0_974
.LBB0_983:
	s_or_b64 exec, exec, s[2:3]
	s_mov_b32 s0, 0x100000
	v_cmp_gt_i32_e32 vcc, s0, v12
	s_and_saveexec_b64 s[4:5], vcc
	s_cbranch_execz .LBB0_1090
	v_max_i32_e32 v3, 0x100000, v2
	v_cmp_gt_i32_e64 s[2:3], s0, v2
	v_mov_b32_e32 v2, 0x100000
	v_readlane_b32 s0, v255, 9
	v_cndmask_b32_e64 v11, 1, v2, s[2:3]
	s_add_u32 s6, s60, 0x3d400000
	v_mov_b32_e32 v2, s0
	v_addc_co_u32_e64 v2, s[0:1], v2, v8, s[2:3]
	v_sub_u32_e32 v13, v3, v2
	v_mul_hi_u32 v2, v13, v202
	v_mul_lo_u32 v3, v2, s74
	v_sub_u32_e32 v3, v13, v3
	v_add_u32_e32 v4, 1, v2
	v_cmp_le_u32_e64 s[0:1], s74, v3
	s_addc_u32 s7, s61, 0
	s_add_u32 s8, s60, 0x3d128200
	v_cndmask_b32_e64 v2, v2, v4, s[0:1]
	v_subrev_u32_e32 v4, s74, v3
	v_cndmask_b32_e64 v3, v3, v4, s[0:1]
	v_add_u32_e32 v4, 1, v2
	v_cmp_le_u32_e64 s[0:1], s74, v3
	s_addc_u32 s9, s61, 0
	s_lshl_b32 s14, s80, 6
	v_cndmask_b32_e64 v2, v2, v4, s[0:1]
	v_and_b32_e32 v0, 15, v8
	v_add_u32_e32 v3, v11, v2
	s_add_u32 s10, s60, 0x3d1a8200
	v_lshlrev_b32_e32 v176, 4, v0
	v_and_b32_e32 v3, 1, v3
	s_addc_u32 s11, s61, 0
	v_cmp_lt_u32_e32 vcc, 7, v0
	s_waitcnt lgkmcnt(0)
	v_lshl_add_u64 v[0:1], s[50:51], 0, v[176:177]
	v_cmp_eq_u32_e64 s[0:1], 1, v3
	v_mov_b32_e32 v4, v12
	s_and_saveexec_b64 s[12:13], s[0:1]
	s_cbranch_execz .LBB0_986
	v_ashrrev_i32_e32 v3, 4, v12
	v_ashrrev_i32_e32 v4, 14, v12
	v_add_u32_e32 v16, s14, v4
	v_lshlrev_b32_e32 v4, 6, v3
	v_and_b32_e32 v4, 0x3c0, v4
	v_lshlrev_b32_e32 v5, 3, v8
	v_lshl_or_b32 v4, v16, 10, v4
	v_and_b32_e32 v15, 56, v5
	v_ashrrev_i32_e32 v5, 31, v4
	v_lshlrev_b64 v[4:5], 2, v[4:5]
	v_lshl_add_u64 v[6:7], s[8:9], 0, v[4:5]
	v_lshlrev_b32_e32 v176, 2, v15
	v_lshl_add_u64 v[4:5], s[10:11], 0, v[4:5]
	v_bfe_u32 v14, v3, 4, 6
	v_lshl_add_u64 v[24:25], v[4:5], 0, v[176:177]
	v_lshl_add_u32 v4, v16, 6, v16
	v_add3_u32 v4, v14, v4, 1
	v_ashrrev_i32_e32 v5, 31, v4
	v_lshlrev_b64 v[4:5], 9, v[4:5]
	v_lshl_add_u64 v[22:23], v[6:7], 0, v[176:177]
	v_lshl_add_u64 v[4:5], s[6:7], 0, v[4:5]
	v_lshlrev_b32_e32 v176, 3, v15
	v_lshl_add_u64 v[26:27], v[4:5], 0, v[176:177]
	global_load_dwordx4 v[4:7], v[24:25], off
	global_load_dwordx4 v[14:17], v[26:27], off
	global_load_dwordx4 v[18:21], v[22:23], off
	s_waitcnt vmcnt(0) lgkmcnt(0)
	v_mov_b32_e32 v29, v16
	v_mov_b32_e32 v16, v15
	v_mov_b32_e32 v28, v14
	v_pk_mul_f32 v[14:15], v[18:19], v[16:17]
	s_nop 0
	v_pk_fma_f32 v[14:15], v[4:5], v[28:29], v[14:15]
	v_pk_mul_f32 v[4:5], v[4:5], v[16:17]
	s_nop 0
	v_pk_fma_f32 v[4:5], v[28:29], v[18:19], v[4:5] neg_lo:[0,0,1] neg_hi:[0,0,1]
	s_nop 0
	v_cndmask_b32_e64 v28, v5, -v15, vcc
	v_cndmask_b32_e64 v29, v4, -v14, vcc
	global_load_dwordx4 v[14:17], v[26:27], off offset:16
	s_waitcnt vmcnt(0) lgkmcnt(0)
	v_mov_b32_e32 v5, v16
	v_mov_b32_e32 v16, v15
	v_mov_b32_e32 v4, v14
	v_pk_mul_f32 v[14:15], v[20:21], v[16:17]
	s_nop 0
	v_pk_fma_f32 v[14:15], v[6:7], v[4:5], v[14:15]
	v_pk_mul_f32 v[6:7], v[6:7], v[16:17]
	s_nop 0
	v_pk_fma_f32 v[4:5], v[4:5], v[20:21], v[6:7] neg_lo:[0,0,1] neg_hi:[0,0,1]
	s_nop 0
	v_cndmask_b32_e64 v30, v5, -v15, vcc
	v_cndmask_b32_e64 v31, v4, -v14, vcc
	global_load_dwordx4 v[4:7], v[24:25], off offset:16
	global_load_dwordx4 v[14:17], v[26:27], off offset:32
	global_load_dwordx4 v[18:21], v[22:23], off offset:16
	s_waitcnt vmcnt(0) lgkmcnt(0)
	v_mov_b32_e32 v25, v16
	v_mov_b32_e32 v16, v15
	v_mov_b32_e32 v24, v14
	v_pk_mul_f32 v[14:15], v[18:19], v[16:17]
	s_nop 0
	v_pk_fma_f32 v[14:15], v[4:5], v[24:25], v[14:15]
	v_pk_mul_f32 v[4:5], v[4:5], v[16:17]
	s_nop 0
	v_pk_fma_f32 v[4:5], v[24:25], v[18:19], v[4:5] neg_lo:[0,0,1] neg_hi:[0,0,1]
	s_nop 0
	v_cndmask_b32_e64 v18, v5, -v15, vcc
	v_cndmask_b32_e64 v19, v4, -v14, vcc
	global_load_dwordx4 v[14:17], v[26:27], off offset:48
	s_waitcnt vmcnt(0) lgkmcnt(0)
	v_mov_b32_e32 v5, v16
	v_mov_b32_e32 v16, v15
	v_mov_b32_e32 v4, v14
	v_pk_mul_f32 v[14:15], v[20:21], v[16:17]
	s_nop 0
	v_pk_fma_f32 v[14:15], v[6:7], v[4:5], v[14:15]
	v_pk_mul_f32 v[6:7], v[6:7], v[16:17]
	s_nop 0
	v_pk_fma_f32 v[4:5], v[4:5], v[20:21], v[6:7] neg_lo:[0,0,1] neg_hi:[0,0,1]
	v_cvt_pk_f16_f32 v6, v19, v18
	v_cndmask_b32_e64 v7, v5, -v15, vcc
	v_cndmask_b32_e64 v16, v4, -v14, vcc
	v_mad_i64_i32 v[14:15], s[0:1], v3, s52, v[0:1]
	v_cvt_pk_f16_f32 v4, v29, v28
	v_cvt_pk_f16_f32 v5, v31, v30
	v_cvt_pk_f16_f32 v7, v16, v7
	global_store_dwordx4 v[14:15], v[4:7], off
	s_nop 1
	v_add_u32_e32 v4, s74, v12

.LBB0_988:
	v_ashrrev_i32_e32 v5, 4, v4
	v_ashrrev_i32_e32 v2, 14, v4
	v_add_u32_e32 v17, s14, v2
	v_lshlrev_b32_e32 v2, 6, v5
	v_and_b32_e32 v2, 0x3c0, v2
	v_lshl_or_b32 v2, v17, 10, v2
	v_ashrrev_i32_e32 v3, 31, v2
	v_and_b32_e32 v18, 56, v15
	v_lshlrev_b64 v[2:3], 2, v[2:3]
	v_lshl_add_u64 v[6:7], s[8:9], 0, v[2:3]
	v_lshlrev_b32_e32 v176, 2, v18
	v_lshl_add_u64 v[2:3], s[10:11], 0, v[2:3]
	v_bfe_u32 v16, v5, 4, 6
	v_lshl_add_u64 v[28:29], v[2:3], 0, v[176:177]
	v_lshl_add_u32 v2, v17, 6, v17
	v_add3_u32 v2, v16, v2, 1
	v_ashrrev_i32_e32 v3, 31, v2
	v_lshlrev_b64 v[2:3], 9, v[2:3]
	v_lshl_add_u64 v[16:17], s[6:7], 0, v[2:3]
	v_lshlrev_b32_e32 v2, 3, v18
	v_mov_b32_e32 v3, v177
	v_lshl_add_u64 v[6:7], v[6:7], 0, v[176:177]
	v_lshl_add_u64 v[30:31], v[16:17], 0, v[2:3]
	global_load_dwordx4 v[16:19], v[28:29], off
	global_load_dwordx4 v[20:23], v[30:31], off
	global_load_dwordx4 v[24:27], v[6:7], off
	v_add_u32_e32 v15, s15, v15
	s_waitcnt vmcnt(0) lgkmcnt(0)
	v_mov_b32_e32 v33, v22
	v_mov_b32_e32 v22, v21
	v_mov_b32_e32 v32, v20
	v_pk_mul_f32 v[20:21], v[24:25], v[22:23]
	s_nop 0
	v_pk_fma_f32 v[20:21], v[16:17], v[32:33], v[20:21]
	v_pk_mul_f32 v[16:17], v[16:17], v[22:23]
	s_nop 0
	v_pk_fma_f32 v[16:17], v[32:33], v[24:25], v[16:17] neg_lo:[0,0,1] neg_hi:[0,0,1]
	s_nop 0
	v_cndmask_b32_e64 v32, v17, -v21, vcc
	v_cndmask_b32_e64 v33, v16, -v20, vcc
	global_load_dwordx4 v[20:23], v[30:31], off offset:16
	s_waitcnt vmcnt(0) lgkmcnt(0)
	v_mov_b32_e32 v17, v22
	v_mov_b32_e32 v22, v21
	v_mov_b32_e32 v16, v20
	v_pk_mul_f32 v[20:21], v[26:27], v[22:23]
	s_nop 0
	v_pk_fma_f32 v[20:21], v[18:19], v[16:17], v[20:21]
	v_pk_mul_f32 v[18:19], v[18:19], v[22:23]
	s_nop 0
	v_pk_fma_f32 v[16:17], v[16:17], v[26:27], v[18:19] neg_lo:[0,0,1] neg_hi:[0,0,1]
	s_nop 0
	v_cndmask_b32_e64 v34, v17, -v21, vcc
	v_cndmask_b32_e64 v35, v16, -v20, vcc
	global_load_dwordx4 v[16:19], v[28:29], off offset:16
	global_load_dwordx4 v[20:23], v[30:31], off offset:32
	global_load_dwordx4 v[24:27], v[6:7], off offset:16
	s_waitcnt vmcnt(0) lgkmcnt(0)
	v_mov_b32_e32 v29, v22
	v_mov_b32_e32 v22, v21
	v_mov_b32_e32 v28, v20
	v_pk_mul_f32 v[6:7], v[24:25], v[22:23]
	s_nop 0
	v_pk_fma_f32 v[6:7], v[16:17], v[28:29], v[6:7]
	v_pk_mul_f32 v[16:17], v[16:17], v[22:23]
	global_load_dwordx4 v[20:23], v[30:31], off offset:48
	v_pk_fma_f32 v[16:17], v[28:29], v[24:25], v[16:17] neg_lo:[0,0,1] neg_hi:[0,0,1]
	s_nop 0
	v_cndmask_b32_e64 v24, v17, -v7, vcc
	v_cndmask_b32_e64 v25, v16, -v6, vcc
	s_waitcnt vmcnt(0) lgkmcnt(0)
	v_mov_b32_e32 v7, v22
	v_mov_b32_e32 v22, v21
	v_mov_b32_e32 v6, v20
	v_pk_mul_f32 v[16:17], v[26:27], v[22:23]
	s_nop 0
	v_pk_fma_f32 v[16:17], v[18:19], v[6:7], v[16:17]
	v_pk_mul_f32 v[18:19], v[18:19], v[22:23]
	s_nop 0
	v_pk_fma_f32 v[6:7], v[6:7], v[26:27], v[18:19] neg_lo:[0,0,1] neg_hi:[0,0,1]
	v_cvt_pk_f16_f32 v18, v25, v24
	v_cndmask_b32_e64 v19, v7, -v17, vcc
	v_cndmask_b32_e64 v20, v6, -v16, vcc
	v_mad_i64_i32 v[6:7], s[0:1], v5, s52, v[0:1]
	v_cvt_pk_f16_f32 v16, v33, v32
	v_cvt_pk_f16_f32 v17, v35, v34
	v_cvt_pk_f16_f32 v19, v20, v19
	global_store_dwordx4 v[6:7], v[16:19], off
	s_nop 1
	v_add_u32_e32 v16, s74, v4
	v_ashrrev_i32_e32 v17, 4, v16
	v_ashrrev_i32_e32 v4, 14, v16
	v_add_u32_e32 v19, s14, v4
	v_lshlrev_b32_e32 v4, 6, v17
	v_and_b32_e32 v4, 0x3c0, v4
	v_bfe_u32 v18, v17, 4, 6
	v_lshl_or_b32 v4, v19, 10, v4
	v_lshl_add_u32 v19, v19, 6, v19
	v_ashrrev_i32_e32 v5, 31, v4
	v_add3_u32 v18, v18, v19, 1
	v_lshlrev_b64 v[6:7], 2, v[4:5]
	v_ashrrev_i32_e32 v19, 31, v18
	v_lshl_add_u64 v[4:5], s[8:9], 0, v[6:7]
	v_lshl_add_u64 v[6:7], s[10:11], 0, v[6:7]
	v_lshlrev_b64 v[18:19], 9, v[18:19]
	v_lshl_add_u64 v[6:7], v[6:7], 0, v[176:177]
	v_lshl_add_u64 v[18:19], s[6:7], 0, v[18:19]
	v_lshl_add_u64 v[4:5], v[4:5], 0, v[176:177]
	v_lshl_add_u64 v[2:3], v[18:19], 0, v[2:3]
	global_load_dwordx4 v[18:21], v[6:7], off
	global_load_dwordx4 v[22:25], v[2:3], off
	global_load_dwordx4 v[26:29], v[4:5], off
	s_waitcnt vmcnt(0) lgkmcnt(0)
	v_mov_b32_e32 v31, v24
	v_mov_b32_e32 v24, v23
	v_mov_b32_e32 v30, v22
	v_pk_mul_f32 v[22:23], v[26:27], v[24:25]
	s_nop 0
	v_pk_fma_f32 v[22:23], v[18:19], v[30:31], v[22:23]
	v_pk_mul_f32 v[18:19], v[18:19], v[24:25]
	s_nop 0
	v_pk_fma_f32 v[18:19], v[30:31], v[26:27], v[18:19] neg_lo:[0,0,1] neg_hi:[0,0,1]
	s_nop 0
	v_cndmask_b32_e64 v30, v19, -v23, vcc
	v_cndmask_b32_e64 v31, v18, -v22, vcc
	global_load_dwordx4 v[22:25], v[2:3], off offset:16
	s_waitcnt vmcnt(0) lgkmcnt(0)
	v_mov_b32_e32 v19, v24
	v_mov_b32_e32 v24, v23
	v_mov_b32_e32 v18, v22
	v_pk_mul_f32 v[22:23], v[28:29], v[24:25]
	s_nop 0
	v_pk_fma_f32 v[22:23], v[20:21], v[18:19], v[22:23]
	v_pk_mul_f32 v[20:21], v[20:21], v[24:25]
	s_nop 0
	v_pk_fma_f32 v[18:19], v[18:19], v[28:29], v[20:21] neg_lo:[0,0,1] neg_hi:[0,0,1]
	s_nop 0
	v_cndmask_b32_e64 v28, v19, -v23, vcc
	v_cndmask_b32_e64 v29, v18, -v22, vcc
	global_load_dwordx4 v[18:21], v[6:7], off offset:16
	global_load_dwordx4 v[22:25], v[2:3], off offset:32
	s_waitcnt vmcnt(0) lgkmcnt(0)
	v_mov_b32_e32 v27, v24
	global_load_dwordx4 v[4:7], v[4:5], off offset:16
	v_mov_b32_e32 v24, v23
	v_mov_b32_e32 v26, v22
	s_waitcnt vmcnt(0) lgkmcnt(0)
	v_pk_mul_f32 v[22:23], v[4:5], v[24:25]
	s_nop 0
	v_pk_fma_f32 v[22:23], v[18:19], v[26:27], v[22:23]
	v_pk_mul_f32 v[18:19], v[18:19], v[24:25]
	s_nop 0
	v_pk_fma_f32 v[4:5], v[26:27], v[4:5], v[18:19] neg_lo:[0,0,1] neg_hi:[0,0,1]
	s_nop 0
	v_cndmask_b32_e64 v23, v5, -v23, vcc
	v_cndmask_b32_e64 v22, v4, -v22, vcc
	global_load_dwordx4 v[2:5], v[2:3], off offset:48
	s_waitcnt vmcnt(0) lgkmcnt(0)
	v_mov_b32_e32 v19, v4
	v_mov_b32_e32 v4, v3
	v_mov_b32_e32 v18, v2
	v_pk_mul_f32 v[2:3], v[6:7], v[4:5]
	v_pk_mul_f32 v[4:5], v[20:21], v[4:5]
	v_pk_fma_f32 v[2:3], v[20:21], v[18:19], v[2:3]
	v_pk_fma_f32 v[4:5], v[18:19], v[6:7], v[4:5] neg_lo:[0,0,1] neg_hi:[0,0,1]
	v_mad_i64_i32 v[6:7], s[0:1], v17, s52, v[0:1]
	v_cndmask_b32_e64 v5, v5, -v3, vcc
	v_cndmask_b32_e64 v18, v4, -v2, vcc
	v_cvt_pk_f16_f32 v2, v31, v30
	v_cvt_pk_f16_f32 v3, v29, v28
	v_cvt_pk_f16_f32 v4, v22, v23
	v_cvt_pk_f16_f32 v5, v18, v5
	global_store_dwordx4 v[6:7], v[2:5], off
	s_nop 1
	v_add_u32_e32 v4, s74, v16
	v_cmp_lt_i32_e64 s[0:1], s16, v4
	s_or_b64 s[12:13], s[0:1], s[12:13]
	s_andn2_b64 exec, exec, s[12:13]
	s_cbranch_execnz .LBB0_988
.LBB0_989:
	s_or_b64 exec, exec, s[2:3]
	v_lshlrev_b32_e32 v176, 4, v9
	v_lshl_add_u64 v[2:3], s[60:61], 0, v[176:177]
	s_mov_b64 s[8:9], 0x31000000
	v_lshl_add_u64 v[2:3], v[2:3], 0, s[8:9]
	v_mul_hi_u32 v1, v13, v203
	v_readlane_b32 s8, v255, 17
	v_add_u32_e32 v5, 1, v1
	s_add_u32 s0, s60, 0x3d23a200
	v_mul_lo_u32 v4, v1, s8
	v_sub_u32_e32 v4, v13, v4
	v_cmp_le_u32_e32 vcc, s8, v4
	s_addc_u32 s1, s61, 0
	s_add_u32 s2, s60, 0x3d2ba200
	v_cndmask_b32_e32 v1, v1, v5, vcc
	v_subrev_u32_e32 v5, s8, v4
	v_cndmask_b32_e32 v4, v4, v5, vcc
	v_add_u32_e32 v5, 1, v1
	v_cmp_le_u32_e32 vcc, s8, v4
	s_addc_u32 s3, s61, 0
	v_xor_b32_e32 v0, 63, v10
	v_cndmask_b32_e32 v1, v1, v5, vcc
	v_add_u32_e32 v4, v11, v1
	v_and_b32_e32 v4, 1, v4
	v_cmp_eq_u32_e32 vcc, 1, v4
	s_and_saveexec_b64 s[8:9], vcc
	s_cbranch_execz .LBB0_1023
	v_ashrrev_i32_e32 v5, 14, v12
	v_add_u32_e32 v5, s14, v5
	s_movk_i32 s10, 0x41
	v_mad_u64_u32 v[6:7], s[10:11], v5, s10, v[0:1]
	v_ashrrev_i32_e32 v4, 7, v12
	v_ashrrev_i32_e32 v7, 31, v6
	v_and_b32_e32 v9, 63, v4
	v_lshlrev_b64 v[6:7], 9, v[6:7]
	v_lshl_add_u64 v[6:7], s[6:7], 0, v[6:7]
	v_lshlrev_b32_e32 v176, 3, v9
	v_lshl_add_u64 v[6:7], v[6:7], 0, v[176:177]
	global_load_dwordx2 v[6:7], v[6:7], off
	v_and_b32_e32 v10, 0x2000, v12
	v_lshlrev_b32_e32 v9, 4, v9
	v_cmp_ne_u32_e32 vcc, 0, v10
	v_lshl_or_b32 v10, v5, 10, v9
	v_ashrrev_i32_e32 v11, 31, v10
	v_lshlrev_b64 v[10:11], 2, v[10:11]
	v_lshlrev_b32_e32 v5, 5, v8
	v_lshl_add_u64 v[16:17], s[0:1], 0, v[10:11]
	v_and_b32_e32 v176, 32, v5
	v_lshl_add_u64 v[10:11], s[2:3], 0, v[10:11]
	v_lshl_add_u64 v[8:9], v[16:17], 0, v[176:177]
	v_lshl_add_u64 v[10:11], v[10:11], 0, v[176:177]
	s_and_saveexec_b64 s[10:11], vcc
	s_xor_b64 s[10:11], exec, s[10:11]
	s_cbranch_execz .LBB0_992
	global_load_dword v16, v[10:11], off
	global_load_dword v17, v[8:9], off
	s_waitcnt vmcnt(0) lgkmcnt(0)
	v_pk_mul_f32 v[16:17], v[6:7], v[16:17]
	s_nop 0
	v_add_f32_e32 v13, v16, v17
	s_andn2_saveexec_b64 s[10:11], s[10:11]
	s_cbranch_execz .LBB0_994
	s_branch .LBB0_993

.LBB0_993:
	global_load_dword v16, v[8:9], off
	global_load_dword v17, v[10:11], off
	s_waitcnt vmcnt(0) lgkmcnt(0)
	v_pk_mul_f32 v[16:17], v[6:7], v[16:17]
	s_nop 0
	v_sub_f32_e32 v13, v16, v17
.LBB0_994:
	s_or_b64 exec, exec, s[10:11]
	s_and_saveexec_b64 s[10:11], vcc
	s_xor_b64 s[10:11], exec, s[10:11]
	s_cbranch_execz .LBB0_996
	global_load_dword v16, v[10:11], off offset:4
	global_load_dword v17, v[8:9], off offset:4
	s_waitcnt vmcnt(0) lgkmcnt(0)
	v_pk_mul_f32 v[16:17], v[6:7], v[16:17]
	s_nop 0
	v_add_f32_e32 v15, v16, v17
	s_andn2_saveexec_b64 s[10:11], s[10:11]
	s_cbranch_execz .LBB0_998
	s_branch .LBB0_997

.LBB0_997:
	global_load_dword v16, v[8:9], off offset:4
	global_load_dword v17, v[10:11], off offset:4
	s_waitcnt vmcnt(0) lgkmcnt(0)
	v_pk_mul_f32 v[16:17], v[6:7], v[16:17]
	s_nop 0
	v_sub_f32_e32 v15, v16, v17
.LBB0_998:
	s_or_b64 exec, exec, s[10:11]
	s_and_saveexec_b64 s[10:11], vcc
	s_xor_b64 s[10:11], exec, s[10:11]
	s_cbranch_execz .LBB0_1000
	global_load_dword v16, v[10:11], off offset:8
	global_load_dword v17, v[8:9], off offset:8
	s_waitcnt vmcnt(0) lgkmcnt(0)
	v_pk_mul_f32 v[16:17], v[6:7], v[16:17]
	s_nop 0
	v_add_f32_e32 v16, v16, v17
	s_andn2_saveexec_b64 s[10:11], s[10:11]
	s_cbranch_execz .LBB0_1002
	s_branch .LBB0_1001

.LBB0_1001:
	global_load_dword v16, v[8:9], off offset:8
	global_load_dword v17, v[10:11], off offset:8
	s_waitcnt vmcnt(0) lgkmcnt(0)
	v_pk_mul_f32 v[16:17], v[6:7], v[16:17]
	s_nop 0
	v_sub_f32_e32 v16, v16, v17
.LBB0_1002:
	s_or_b64 exec, exec, s[10:11]
	s_and_saveexec_b64 s[10:11], vcc
	s_xor_b64 s[10:11], exec, s[10:11]
	s_cbranch_execz .LBB0_1004
	global_load_dword v18, v[10:11], off offset:12
	global_load_dword v19, v[8:9], off offset:12
	s_waitcnt vmcnt(0) lgkmcnt(0)
	v_pk_mul_f32 v[18:19], v[6:7], v[18:19]
	s_nop 0
	v_add_f32_e32 v17, v18, v19
	s_andn2_saveexec_b64 s[10:11], s[10:11]
	s_cbranch_execz .LBB0_1006
	s_branch .LBB0_1005

.LBB0_1005:
	global_load_dword v18, v[8:9], off offset:12
	global_load_dword v19, v[10:11], off offset:12
	s_waitcnt vmcnt(0) lgkmcnt(0)
	v_pk_mul_f32 v[18:19], v[6:7], v[18:19]
	s_nop 0
	v_sub_f32_e32 v17, v18, v19
.LBB0_1006:
	s_or_b64 exec, exec, s[10:11]
	s_and_saveexec_b64 s[10:11], vcc
	s_xor_b64 s[10:11], exec, s[10:11]
	s_cbranch_execz .LBB0_1008
	global_load_dword v18, v[10:11], off offset:16
	global_load_dword v19, v[8:9], off offset:16
	s_waitcnt vmcnt(0) lgkmcnt(0)
	v_pk_mul_f32 v[18:19], v[6:7], v[18:19]
	s_nop 0
	v_add_f32_e32 v18, v18, v19
	s_andn2_saveexec_b64 s[10:11], s[10:11]
	s_cbranch_execz .LBB0_1010
	s_branch .LBB0_1009

.LBB0_1009:
	global_load_dword v18, v[8:9], off offset:16
	global_load_dword v19, v[10:11], off offset:16
	s_waitcnt vmcnt(0) lgkmcnt(0)
	v_pk_mul_f32 v[18:19], v[6:7], v[18:19]
	s_nop 0
	v_sub_f32_e32 v18, v18, v19
.LBB0_1010:
	s_or_b64 exec, exec, s[10:11]
	s_and_saveexec_b64 s[10:11], vcc
	s_xor_b64 s[10:11], exec, s[10:11]
	s_cbranch_execz .LBB0_1012
	global_load_dword v20, v[10:11], off offset:20
	global_load_dword v21, v[8:9], off offset:20
	s_waitcnt vmcnt(0) lgkmcnt(0)
	v_pk_mul_f32 v[20:21], v[6:7], v[20:21]
	s_nop 0
	v_add_f32_e32 v19, v20, v21
	s_andn2_saveexec_b64 s[10:11], s[10:11]
	s_cbranch_execz .LBB0_1014
	s_branch .LBB0_1013

.LBB0_1013:
	global_load_dword v20, v[8:9], off offset:20
	global_load_dword v21, v[10:11], off offset:20
	s_waitcnt vmcnt(0) lgkmcnt(0)
	v_pk_mul_f32 v[20:21], v[6:7], v[20:21]
	s_nop 0
	v_sub_f32_e32 v19, v20, v21
.LBB0_1014:
	s_or_b64 exec, exec, s[10:11]
	s_and_saveexec_b64 s[10:11], vcc
	s_xor_b64 s[10:11], exec, s[10:11]
	s_cbranch_execz .LBB0_1016
	global_load_dword v20, v[10:11], off offset:24
	global_load_dword v21, v[8:9], off offset:24
	s_waitcnt vmcnt(0) lgkmcnt(0)
	v_pk_mul_f32 v[20:21], v[6:7], v[20:21]
	s_nop 0
	v_add_f32_e32 v20, v20, v21
	s_andn2_saveexec_b64 s[10:11], s[10:11]
	s_cbranch_execz .LBB0_1018
	s_branch .LBB0_1017

.LBB0_1017:
	global_load_dword v20, v[8:9], off offset:24
	global_load_dword v21, v[10:11], off offset:24
	s_waitcnt vmcnt(0) lgkmcnt(0)
	v_pk_mul_f32 v[20:21], v[6:7], v[20:21]
	s_nop 0
	v_sub_f32_e32 v20, v20, v21
.LBB0_1018:
	s_or_b64 exec, exec, s[10:11]
	s_and_saveexec_b64 s[10:11], vcc
	s_xor_b64 s[10:11], exec, s[10:11]
	s_cbranch_execz .LBB0_1020
	global_load_dword v10, v[10:11], off offset:28
	s_nop 0
	global_load_dword v11, v[8:9], off offset:28
	s_waitcnt vmcnt(0) lgkmcnt(0)
	v_pk_mul_f32 v[6:7], v[6:7], v[10:11]
	s_nop 0
	v_add_f32_e32 v21, v6, v7
	s_andn2_saveexec_b64 s[10:11], s[10:11]
	s_cbranch_execnz .LBB0_1021
	s_branch .LBB0_1022

.LBB0_1021:
	global_load_dword v8, v[8:9], off offset:28
	s_nop 0
	global_load_dword v9, v[10:11], off offset:28
	s_waitcnt vmcnt(0) lgkmcnt(0)
	v_pk_mul_f32 v[6:7], v[6:7], v[8:9]
	s_nop 0
	v_sub_f32_e32 v21, v6, v7
.LBB0_1022:
	s_or_b64 exec, exec, s[10:11]
	v_ashrrev_i32_e32 v5, 31, v4
	v_lshlrev_b64 v[4:5], 11, v[4:5]
	v_lshl_add_u64 v[8:9], v[2:3], 0, v[4:5]
	v_cvt_pk_f16_f32 v4, v13, v15
	v_cvt_pk_f16_f32 v5, v16, v17
	s_waitcnt vmcnt(0) lgkmcnt(0)
	v_cvt_pk_f16_f32 v6, v18, v19
	v_cvt_pk_f16_f32 v7, v20, v21
	v_add_u32_e32 v12, s74, v12
	global_store_dwordx4 v[8:9], v[4:7], off

.LBB0_1025:
	s_or_b64 exec, exec, s[10:11]
	v_ashrrev_i32_e32 v5, 31, v4
	v_add_u32_e32 v12, s74, v12
	v_lshlrev_b64 v[4:5], 11, v[4:5]
	v_cmp_lt_i32_e32 vcc, s16, v12
	v_lshl_add_u64 v[8:9], v[2:3], 0, v[4:5]
	v_cvt_pk_f16_f32 v4, v13, v14
	v_cvt_pk_f16_f32 v5, v15, v16
	s_waitcnt vmcnt(0) lgkmcnt(0)
	v_cvt_pk_f16_f32 v6, v17, v18
	v_cvt_pk_f16_f32 v7, v19, v20
	s_or_b64 s[8:9], vcc, s[8:9]
	v_add_u32_e32 v1, s15, v1
	global_store_dwordx4 v[8:9], v[4:7], off
	s_andn2_b64 exec, exec, s[8:9]
	s_cbranch_execz .LBB0_1090
.LBB0_1026:
	v_ashrrev_i32_e32 v5, 14, v12
	v_add_u32_e32 v5, s14, v5
	s_movk_i32 s10, 0x41
	v_mad_u64_u32 v[6:7], s[10:11], v5, s10, v[0:1]
	v_ashrrev_i32_e32 v4, 7, v12
	v_ashrrev_i32_e32 v7, 31, v6
	v_and_b32_e32 v8, 63, v4
	v_lshlrev_b64 v[6:7], 9, v[6:7]
	v_lshl_add_u64 v[6:7], s[6:7], 0, v[6:7]
	v_lshlrev_b32_e32 v176, 3, v8
	v_lshl_add_u64 v[6:7], v[6:7], 0, v[176:177]
	global_load_dwordx2 v[6:7], v[6:7], off
	v_lshlrev_b32_e32 v8, 4, v8
	v_and_b32_e32 v9, 0x2000, v12
	v_lshl_or_b32 v8, v5, 10, v8
	v_cmp_ne_u32_e32 vcc, 0, v9
	v_ashrrev_i32_e32 v9, 31, v8
	v_and_b32_e32 v13, 8, v1
	v_lshlrev_b64 v[10:11], 2, v[8:9]
	v_lshl_add_u64 v[8:9], s[0:1], 0, v[10:11]
	v_lshlrev_b32_e32 v176, 2, v13
	v_lshl_add_u64 v[10:11], s[2:3], 0, v[10:11]
	v_lshl_add_u64 v[8:9], v[8:9], 0, v[176:177]
	v_lshl_add_u64 v[10:11], v[10:11], 0, v[176:177]
	s_and_saveexec_b64 s[10:11], vcc
	s_xor_b64 s[10:11], exec, s[10:11]
	s_cbranch_execz .LBB0_1028
	global_load_dword v14, v[10:11], off
	global_load_dword v15, v[8:9], off
	s_waitcnt vmcnt(0) lgkmcnt(0)
	v_pk_mul_f32 v[14:15], v[6:7], v[14:15]
	s_nop 0
	v_add_f32_e32 v13, v14, v15
	s_andn2_saveexec_b64 s[10:11], s[10:11]
	s_cbranch_execz .LBB0_1030
	s_branch .LBB0_1029

.LBB0_1029:
	global_load_dword v14, v[8:9], off
	global_load_dword v15, v[10:11], off
	s_waitcnt vmcnt(0) lgkmcnt(0)
	v_pk_mul_f32 v[14:15], v[6:7], v[14:15]
	s_nop 0
	v_sub_f32_e32 v13, v14, v15
.LBB0_1030:
	s_or_b64 exec, exec, s[10:11]
	s_and_saveexec_b64 s[10:11], vcc
	s_xor_b64 s[10:11], exec, s[10:11]
	s_cbranch_execz .LBB0_1032
	global_load_dword v14, v[10:11], off offset:4
	global_load_dword v15, v[8:9], off offset:4
	s_waitcnt vmcnt(0) lgkmcnt(0)
	v_pk_mul_f32 v[14:15], v[6:7], v[14:15]
	s_nop 0
	v_add_f32_e32 v14, v14, v15
	s_andn2_saveexec_b64 s[10:11], s[10:11]
	s_cbranch_execz .LBB0_1034
	s_branch .LBB0_1033

.LBB0_1033:
	global_load_dword v14, v[8:9], off offset:4
	global_load_dword v15, v[10:11], off offset:4
	s_waitcnt vmcnt(0) lgkmcnt(0)
	v_pk_mul_f32 v[14:15], v[6:7], v[14:15]
	s_nop 0
	v_sub_f32_e32 v14, v14, v15
.LBB0_1034:
	s_or_b64 exec, exec, s[10:11]
	s_and_saveexec_b64 s[10:11], vcc
	s_xor_b64 s[10:11], exec, s[10:11]
	s_cbranch_execz .LBB0_1036
	global_load_dword v16, v[10:11], off offset:8
	global_load_dword v17, v[8:9], off offset:8
	s_waitcnt vmcnt(0) lgkmcnt(0)
	v_pk_mul_f32 v[16:17], v[6:7], v[16:17]
	s_nop 0
	v_add_f32_e32 v15, v16, v17
	s_andn2_saveexec_b64 s[10:11], s[10:11]
	s_cbranch_execz .LBB0_1038
	s_branch .LBB0_1037

.LBB0_1037:
	global_load_dword v16, v[8:9], off offset:8
	global_load_dword v17, v[10:11], off offset:8
	s_waitcnt vmcnt(0) lgkmcnt(0)
	v_pk_mul_f32 v[16:17], v[6:7], v[16:17]
	s_nop 0
	v_sub_f32_e32 v15, v16, v17
.LBB0_1038:
	s_or_b64 exec, exec, s[10:11]
	s_and_saveexec_b64 s[10:11], vcc
	s_xor_b64 s[10:11], exec, s[10:11]
	s_cbranch_execz .LBB0_1040
	global_load_dword v16, v[10:11], off offset:12
	global_load_dword v17, v[8:9], off offset:12
	s_waitcnt vmcnt(0) lgkmcnt(0)
	v_pk_mul_f32 v[16:17], v[6:7], v[16:17]
	s_nop 0
	v_add_f32_e32 v16, v16, v17
	s_andn2_saveexec_b64 s[10:11], s[10:11]
	s_cbranch_execz .LBB0_1042
	s_branch .LBB0_1041

.LBB0_1041:
	global_load_dword v16, v[8:9], off offset:12
	global_load_dword v17, v[10:11], off offset:12
	s_waitcnt vmcnt(0) lgkmcnt(0)
	v_pk_mul_f32 v[16:17], v[6:7], v[16:17]
	s_nop 0
	v_sub_f32_e32 v16, v16, v17
.LBB0_1042:
	s_or_b64 exec, exec, s[10:11]
	s_and_saveexec_b64 s[10:11], vcc
	s_xor_b64 s[10:11], exec, s[10:11]
	s_cbranch_execz .LBB0_1044
	global_load_dword v18, v[10:11], off offset:16
	global_load_dword v19, v[8:9], off offset:16
	s_waitcnt vmcnt(0) lgkmcnt(0)
	v_pk_mul_f32 v[18:19], v[6:7], v[18:19]
	s_nop 0
	v_add_f32_e32 v17, v18, v19
	s_andn2_saveexec_b64 s[10:11], s[10:11]
	s_cbranch_execz .LBB0_1046
	s_branch .LBB0_1045

.LBB0_1045:
	global_load_dword v18, v[8:9], off offset:16
	global_load_dword v19, v[10:11], off offset:16
	s_waitcnt vmcnt(0) lgkmcnt(0)
	v_pk_mul_f32 v[18:19], v[6:7], v[18:19]
	s_nop 0
	v_sub_f32_e32 v17, v18, v19
.LBB0_1046:
	s_or_b64 exec, exec, s[10:11]
	s_and_saveexec_b64 s[10:11], vcc
	s_xor_b64 s[10:11], exec, s[10:11]
	s_cbranch_execz .LBB0_1048
	global_load_dword v18, v[10:11], off offset:20
	global_load_dword v19, v[8:9], off offset:20
	s_waitcnt vmcnt(0) lgkmcnt(0)
	v_pk_mul_f32 v[18:19], v[6:7], v[18:19]
	s_nop 0
	v_add_f32_e32 v18, v18, v19
	s_andn2_saveexec_b64 s[10:11], s[10:11]
	s_cbranch_execz .LBB0_1050
	s_branch .LBB0_1049

.LBB0_1049:
	global_load_dword v18, v[8:9], off offset:20
	global_load_dword v19, v[10:11], off offset:20
	s_waitcnt vmcnt(0) lgkmcnt(0)
	v_pk_mul_f32 v[18:19], v[6:7], v[18:19]
	s_nop 0
	v_sub_f32_e32 v18, v18, v19
.LBB0_1050:
	s_or_b64 exec, exec, s[10:11]
	s_and_saveexec_b64 s[10:11], vcc
	s_xor_b64 s[10:11], exec, s[10:11]
	s_cbranch_execz .LBB0_1052
	global_load_dword v20, v[10:11], off offset:24
	global_load_dword v21, v[8:9], off offset:24
	s_waitcnt vmcnt(0) lgkmcnt(0)
	v_pk_mul_f32 v[20:21], v[6:7], v[20:21]
	s_nop 0
	v_add_f32_e32 v19, v20, v21
	s_andn2_saveexec_b64 s[10:11], s[10:11]
	s_cbranch_execz .LBB0_1054
	s_branch .LBB0_1053

.LBB0_1053:
	global_load_dword v20, v[8:9], off offset:24
	global_load_dword v21, v[10:11], off offset:24
	s_waitcnt vmcnt(0) lgkmcnt(0)
	v_pk_mul_f32 v[20:21], v[6:7], v[20:21]
	s_nop 0
	v_sub_f32_e32 v19, v20, v21
.LBB0_1054:
	s_or_b64 exec, exec, s[10:11]
	s_and_saveexec_b64 s[10:11], vcc
	s_xor_b64 s[10:11], exec, s[10:11]
	s_cbranch_execz .LBB0_1056
	global_load_dword v10, v[10:11], off offset:28
	s_nop 0
	global_load_dword v11, v[8:9], off offset:28
	s_waitcnt vmcnt(0) lgkmcnt(0)
	v_pk_mul_f32 v[6:7], v[6:7], v[10:11]
	s_nop 0
	v_add_f32_e32 v20, v6, v7
	s_andn2_saveexec_b64 s[10:11], s[10:11]
	s_cbranch_execnz .LBB0_1057
	s_branch .LBB0_1058

.LBB0_1057:
	global_load_dword v8, v[8:9], off offset:28
	s_nop 0
	global_load_dword v9, v[10:11], off offset:28
	s_waitcnt vmcnt(0) lgkmcnt(0)
	v_pk_mul_f32 v[6:7], v[6:7], v[8:9]
	s_nop 0
	v_sub_f32_e32 v20, v6, v7
.LBB0_1058:
	s_or_b64 exec, exec, s[10:11]
	v_ashrrev_i32_e32 v5, 31, v4
	v_lshlrev_b64 v[4:5], 11, v[4:5]
	v_lshl_add_u64 v[8:9], v[2:3], 0, v[4:5]
	v_cvt_pk_f16_f32 v4, v13, v14
	v_cvt_pk_f16_f32 v5, v15, v16
	s_waitcnt vmcnt(0) lgkmcnt(0)
	v_cvt_pk_f16_f32 v6, v17, v18
	v_cvt_pk_f16_f32 v7, v19, v20
	v_add_u32_e32 v12, s74, v12
	global_store_dwordx4 v[8:9], v[4:7], off
	s_movk_i32 s10, 0x41
	v_mov_b32_e32 v9, v177
	v_ashrrev_i32_e32 v5, 14, v12
	v_add_u32_e32 v5, s14, v5
	v_mad_u64_u32 v[6:7], s[10:11], v5, s10, v[0:1]
	v_ashrrev_i32_e32 v4, 7, v12
	v_ashrrev_i32_e32 v7, 31, v6
	v_and_b32_e32 v10, 63, v4
	v_lshlrev_b64 v[6:7], 9, v[6:7]
	v_lshl_add_u64 v[6:7], s[6:7], 0, v[6:7]
	v_lshlrev_b32_e32 v8, 3, v10
	v_lshl_add_u64 v[6:7], v[6:7], 0, v[8:9]
	global_load_dwordx2 v[6:7], v[6:7], off
	v_and_b32_e32 v8, 0x2000, v12
	v_cmp_ne_u32_e32 vcc, 0, v8
	v_lshlrev_b32_e32 v8, 4, v10
	v_lshl_or_b32 v8, v5, 10, v8
	v_ashrrev_i32_e32 v9, 31, v8
	v_lshlrev_b64 v[10:11], 2, v[8:9]
	v_lshl_add_u64 v[8:9], s[0:1], 0, v[10:11]
	v_lshl_add_u64 v[10:11], s[2:3], 0, v[10:11]
	v_lshl_add_u64 v[8:9], v[8:9], 0, v[176:177]
	v_lshl_add_u64 v[10:11], v[10:11], 0, v[176:177]
	s_and_saveexec_b64 s[10:11], vcc
	s_xor_b64 s[10:11], exec, s[10:11]
	s_cbranch_execz .LBB0_1060
	global_load_dword v14, v[10:11], off
	global_load_dword v15, v[8:9], off
	s_waitcnt vmcnt(0) lgkmcnt(0)
	v_pk_mul_f32 v[14:15], v[6:7], v[14:15]
	s_nop 0
	v_add_f32_e32 v13, v14, v15
	s_andn2_saveexec_b64 s[10:11], s[10:11]
	s_cbranch_execz .LBB0_1062
	s_branch .LBB0_1061

.LBB0_1086:
	s_or_b64 exec, exec, s[10:11]
	s_and_saveexec_b64 s[10:11], vcc
	s_xor_b64 s[10:11], exec, s[10:11]
	s_cbranch_execz .LBB0_1088
	global_load_dword v10, v[10:11], off offset:28
	s_nop 0
	global_load_dword v11, v[8:9], off offset:28
	s_waitcnt vmcnt(0) lgkmcnt(0)
	v_pk_mul_f32 v[6:7], v[6:7], v[10:11]
	s_nop 0
	v_add_f32_e32 v20, v6, v7
	s_andn2_saveexec_b64 s[10:11], s[10:11]
	s_cbranch_execz .LBB0_1025
	s_branch .LBB0_1089

.LBB0_1089:
	global_load_dword v8, v[8:9], off offset:28
	s_nop 0
	global_load_dword v9, v[10:11], off offset:28
	s_waitcnt vmcnt(0) lgkmcnt(0)
	v_pk_mul_f32 v[6:7], v[6:7], v[8:9]
	s_nop 0
	v_sub_f32_e32 v20, v6, v7
	s_branch .LBB0_1025
